# scan inner loops fully unrolled (16 steps per chunk, no inner back-edge)
# baseline (speedup 1.0000x reference)
.LBB0_859:
	s_waitcnt lgkmcnt(0)
	v_mov_b32_e32 v95, v96
	v_add_u32_e32 v96, s7, v100
	ds_read_b128 v[70:73], v96 offset:1568
	ds_read_b128 v[66:69], v96 offset:1584
	ds_read_b128 v[50:53], v96 offset:1824
	ds_read_b128 v[46:49], v96 offset:1840
	ds_read_b128 v[54:57], v96 offset:2080
	ds_read_b128 v[42:45], v96 offset:2096
	ds_read_b128 v[78:81], v96 offset:2336
	ds_read_b128 v[74:77], v96 offset:2352
	ds_read_b128 v[62:65], v96 offset:2592
	ds_read_b128 v[58:61], v96 offset:2608
	v_pk_fma_f32 v[34:35], v[84:85], v[34:35], 0 op_sel_hi:[1,1,0]
	v_pk_fma_f32 v[22:23], v[84:85], v[22:23], 0 op_sel_hi:[1,1,0]
	v_pk_fma_f32 v[34:35], v[86:87], v[36:37], v[34:35]
	v_pk_fma_f32 v[22:23], v[86:87], v[24:25], v[22:23]
	v_add_u32_e32 v103, s7, v102
	v_mov_b32_e32 v98, s7
	v_pk_fma_f32 v[24:25], v[88:89], v[38:39], v[34:35]
	v_pk_fma_f32 v[18:19], v[88:89], v[18:19], v[22:23]
	ds_read_b32 v0, v103 offset:2848
	ds_read_b64 v[98:99], v98 offset:3104
	v_pk_fma_f32 v[22:23], v[90:91], v[40:41], v[24:25]
	v_pk_fma_f32 v[20:21], v[90:91], v[20:21], v[18:19]
	v_add_f32_e32 v18, v22, v23
	v_add_f32_e32 v19, v20, v21
	s_nop 0
	v_add_f32_dpp v18, v18, v18 quad_perm:[1,0,3,2] row_mask:0xf bank_mask:0xf bound_ctrl:1
	v_add_f32_dpp v19, v19, v19 quad_perm:[1,0,3,2] row_mask:0xf bank_mask:0xf bound_ctrl:1
	s_nop 0
	v_add_f32_dpp v18, v18, v18 quad_perm:[2,3,0,1] row_mask:0xf bank_mask:0xf bound_ctrl:1
	v_add_f32_dpp v19, v19, v19 quad_perm:[2,3,0,1] row_mask:0xf bank_mask:0xf bound_ctrl:1
	s_nop 0
	v_add_f32_dpp v18, v18, v18 row_half_mirror row_mask:0xf bank_mask:0xf bound_ctrl:1
	v_mov_b32_e32 v22, v97
	v_mov_b32_e32 v23, v18
	v_pk_mul_f32 v[22:23], v[22:23], v[94:95]
	v_add_f32_dpp v19, v19, v19 row_half_mirror row_mask:0xf bank_mask:0xf bound_ctrl:1
	v_add_f32_e32 v19, v23, v19
	v_add_f32_e32 v19, v22, v19
	s_ashr_i32 s47, s46, 31
	v_bfe_u32 v20, v19, 16, 1
	s_lshl_b64 s[20:21], s[46:47], 9
	v_add3_u32 v19, v19, v20, s28
	v_lshl_add_u64 v[20:21], v[92:93], 0, s[20:21]
	global_store_short_d16_hi v[20:21], v19, off
	v_pk_mul_f32 v[2:3], v[84:85], v[2:3]
	s_nop 0
	v_pk_fma_f32 v[2:3], v[18:19], v[26:27], v[2:3] op_sel_hi:[0,1,1]
	v_pk_fma_f32 v[84:85], v[94:95], v[10:11], v[2:3] op_sel_hi:[0,1,1]
	v_pk_mul_f32 v[2:3], v[86:87], v[4:5]
	s_waitcnt lgkmcnt(5)
	v_pk_fma_f32 v[78:79], v[84:85], v[78:79], 0 op_sel_hi:[1,1,0]
	v_pk_fma_f32 v[2:3], v[18:19], v[28:29], v[2:3] op_sel_hi:[0,1,1]
	v_pk_fma_f32 v[86:87], v[94:95], v[12:13], v[2:3] op_sel_hi:[0,1,1]
	v_pk_mul_f32 v[2:3], v[88:89], v[6:7]
	v_pk_fma_f32 v[70:71], v[84:85], v[70:71], 0 op_sel_hi:[1,1,0]
	v_pk_fma_f32 v[2:3], v[18:19], v[30:31], v[2:3] op_sel_hi:[0,1,1]
	v_pk_fma_f32 v[88:89], v[94:95], v[14:15], v[2:3] op_sel_hi:[0,1,1]
	v_pk_mul_f32 v[2:3], v[90:91], v[8:9]
	v_pk_fma_f32 v[78:79], v[86:87], v[80:81], v[78:79]
	v_pk_fma_f32 v[2:3], v[18:19], v[32:33], v[2:3] op_sel_hi:[0,1,1]
	v_pk_fma_f32 v[90:91], v[94:95], v[16:17], v[2:3] op_sel_hi:[0,1,1]
	ds_read_b128 v[22:25], v96 offset:3136
	ds_read_b128 v[18:21], v96 offset:3152
	ds_read_b128 v[2:5], v96 offset:3392
	ds_read_b128 v[6:9], v96 offset:3408
	ds_read_b128 v[10:13], v96 offset:3648
	ds_read_b128 v[14:17], v96 offset:3664
	ds_read_b128 v[34:37], v96 offset:3904
	ds_read_b128 v[38:41], v96 offset:3920
	ds_read_b128 v[26:29], v96 offset:4160
	ds_read_b128 v[30:33], v96 offset:4176
	v_pk_fma_f32 v[70:71], v[86:87], v[72:73], v[70:71]
	s_waitcnt lgkmcnt(14)
	v_pk_fma_f32 v[72:73], v[88:89], v[74:75], v[78:79]
	v_pk_fma_f32 v[66:67], v[88:89], v[66:67], v[70:71]
	v_mov_b32_e32 v95, s7
	ds_read_b32 v94, v103 offset:4416
	ds_read_b64 v[96:97], v95 offset:4672
	v_pk_fma_f32 v[70:71], v[90:91], v[76:77], v[72:73]
	v_pk_fma_f32 v[68:69], v[90:91], v[68:69], v[66:67]
	v_add_f32_e32 v66, v70, v71
	v_add_f32_e32 v67, v68, v69
	s_nop 0
	v_add_f32_dpp v66, v66, v66 quad_perm:[1,0,3,2] row_mask:0xf bank_mask:0xf bound_ctrl:1
	v_add_f32_dpp v67, v67, v67 quad_perm:[1,0,3,2] row_mask:0xf bank_mask:0xf bound_ctrl:1
	s_nop 0
	v_add_f32_dpp v66, v66, v66 quad_perm:[2,3,0,1] row_mask:0xf bank_mask:0xf bound_ctrl:1
	v_add_f32_dpp v68, v67, v67 quad_perm:[2,3,0,1] row_mask:0xf bank_mask:0xf bound_ctrl:1
	s_nop 0
	v_add_f32_dpp v66, v66, v66 row_half_mirror row_mask:0xf bank_mask:0xf bound_ctrl:1
	s_waitcnt lgkmcnt(13)
	v_mov_b32_e32 v67, v0
	s_waitcnt lgkmcnt(12)
	v_pk_mul_f32 v[70:71], v[98:99], v[66:67]
	v_add_f32_dpp v67, v68, v68 row_half_mirror row_mask:0xf bank_mask:0xf bound_ctrl:1
	v_add_f32_e32 v67, v70, v67
	s_add_i32 s20, s2, s46
	v_add_f32_e32 v67, v71, v67
	s_ashr_i32 s21, s20, 31
	v_bfe_u32 v68, v67, 16, 1
	s_lshl_b64 s[20:21], s[20:21], 9
	v_add3_u32 v67, v67, v68, s28
	v_lshl_add_u64 v[68:69], v[92:93], 0, s[20:21]
	global_store_short_d16_hi v[68:69], v67, off
	v_pk_mul_f32 v[50:51], v[50:51], v[84:85]
	v_pk_mul_f32 v[46:47], v[46:47], v[88:89]
	s_waitcnt lgkmcnt(14)
	v_pk_fma_f32 v[50:51], v[66:67], v[62:63], v[50:51] op_sel_hi:[0,1,1]
	v_pk_fma_f32 v[46:47], v[66:67], v[58:59], v[46:47] op_sel_hi:[0,1,1]
	s_waitcnt lgkmcnt(13)
	v_pk_fma_f32 v[84:85], v[0:1], v[54:55], v[50:51] op_sel_hi:[0,1,1]
	v_pk_mul_f32 v[50:51], v[52:53], v[86:87]
	v_pk_fma_f32 v[88:89], v[0:1], v[42:43], v[46:47] op_sel_hi:[0,1,1]
	v_pk_mul_f32 v[42:43], v[48:49], v[90:91]
	v_pk_fma_f32 v[50:51], v[66:67], v[64:65], v[50:51] op_sel_hi:[0,1,1]
	v_pk_fma_f32 v[42:43], v[66:67], v[60:61], v[42:43] op_sel_hi:[0,1,1]
	s_add_i32 s46, s46, s3
	s_add_i32 s10, s10, 2
	s_addk_i32 s7, 0xc40
	v_pk_fma_f32 v[86:87], v[0:1], v[56:57], v[50:51] op_sel_hi:[0,1,1]
	v_pk_fma_f32 v[90:91], v[0:1], v[44:45], v[42:43] op_sel_hi:[0,1,1]
	s_waitcnt lgkmcnt(0)
	v_mov_b32_e32 v95, v96
	v_add_u32_e32 v96, s7, v100
	ds_read_b128 v[70:73], v96 offset:1568
	ds_read_b128 v[66:69], v96 offset:1584
	ds_read_b128 v[50:53], v96 offset:1824
	ds_read_b128 v[46:49], v96 offset:1840
	ds_read_b128 v[54:57], v96 offset:2080
	ds_read_b128 v[42:45], v96 offset:2096
	ds_read_b128 v[78:81], v96 offset:2336
	ds_read_b128 v[74:77], v96 offset:2352
	ds_read_b128 v[62:65], v96 offset:2592
	ds_read_b128 v[58:61], v96 offset:2608
	v_pk_fma_f32 v[34:35], v[84:85], v[34:35], 0 op_sel_hi:[1,1,0]
	v_pk_fma_f32 v[22:23], v[84:85], v[22:23], 0 op_sel_hi:[1,1,0]
	v_pk_fma_f32 v[34:35], v[86:87], v[36:37], v[34:35]
	v_pk_fma_f32 v[22:23], v[86:87], v[24:25], v[22:23]
	v_add_u32_e32 v103, s7, v102
	v_mov_b32_e32 v98, s7
	v_pk_fma_f32 v[24:25], v[88:89], v[38:39], v[34:35]
	v_pk_fma_f32 v[18:19], v[88:89], v[18:19], v[22:23]
	ds_read_b32 v0, v103 offset:2848
	ds_read_b64 v[98:99], v98 offset:3104
	v_pk_fma_f32 v[22:23], v[90:91], v[40:41], v[24:25]
	v_pk_fma_f32 v[20:21], v[90:91], v[20:21], v[18:19]
	v_add_f32_e32 v18, v22, v23
	v_add_f32_e32 v19, v20, v21
	s_nop 0
	v_add_f32_dpp v18, v18, v18 quad_perm:[1,0,3,2] row_mask:0xf bank_mask:0xf bound_ctrl:1
	v_add_f32_dpp v19, v19, v19 quad_perm:[1,0,3,2] row_mask:0xf bank_mask:0xf bound_ctrl:1
	s_nop 0
	v_add_f32_dpp v18, v18, v18 quad_perm:[2,3,0,1] row_mask:0xf bank_mask:0xf bound_ctrl:1
	v_add_f32_dpp v19, v19, v19 quad_perm:[2,3,0,1] row_mask:0xf bank_mask:0xf bound_ctrl:1
	s_nop 0
	v_add_f32_dpp v18, v18, v18 row_half_mirror row_mask:0xf bank_mask:0xf bound_ctrl:1
	v_mov_b32_e32 v22, v97
	v_mov_b32_e32 v23, v18
	v_pk_mul_f32 v[22:23], v[22:23], v[94:95]
	v_add_f32_dpp v19, v19, v19 row_half_mirror row_mask:0xf bank_mask:0xf bound_ctrl:1
	v_add_f32_e32 v19, v23, v19
	v_add_f32_e32 v19, v22, v19
	s_ashr_i32 s47, s46, 31
	v_bfe_u32 v20, v19, 16, 1
	s_lshl_b64 s[20:21], s[46:47], 9
	v_add3_u32 v19, v19, v20, s28
	v_lshl_add_u64 v[20:21], v[92:93], 0, s[20:21]
	global_store_short_d16_hi v[20:21], v19, off
	v_pk_mul_f32 v[2:3], v[84:85], v[2:3]
	s_nop 0
	v_pk_fma_f32 v[2:3], v[18:19], v[26:27], v[2:3] op_sel_hi:[0,1,1]
	v_pk_fma_f32 v[84:85], v[94:95], v[10:11], v[2:3] op_sel_hi:[0,1,1]
	v_pk_mul_f32 v[2:3], v[86:87], v[4:5]
	s_waitcnt lgkmcnt(5)
	v_pk_fma_f32 v[78:79], v[84:85], v[78:79], 0 op_sel_hi:[1,1,0]
	v_pk_fma_f32 v[2:3], v[18:19], v[28:29], v[2:3] op_sel_hi:[0,1,1]
	v_pk_fma_f32 v[86:87], v[94:95], v[12:13], v[2:3] op_sel_hi:[0,1,1]
	v_pk_mul_f32 v[2:3], v[88:89], v[6:7]
	v_pk_fma_f32 v[70:71], v[84:85], v[70:71], 0 op_sel_hi:[1,1,0]
	v_pk_fma_f32 v[2:3], v[18:19], v[30:31], v[2:3] op_sel_hi:[0,1,1]
	v_pk_fma_f32 v[88:89], v[94:95], v[14:15], v[2:3] op_sel_hi:[0,1,1]
	v_pk_mul_f32 v[2:3], v[90:91], v[8:9]
	v_pk_fma_f32 v[78:79], v[86:87], v[80:81], v[78:79]
	v_pk_fma_f32 v[2:3], v[18:19], v[32:33], v[2:3] op_sel_hi:[0,1,1]
	v_pk_fma_f32 v[90:91], v[94:95], v[16:17], v[2:3] op_sel_hi:[0,1,1]
	ds_read_b128 v[22:25], v96 offset:3136
	ds_read_b128 v[18:21], v96 offset:3152
	ds_read_b128 v[2:5], v96 offset:3392
	ds_read_b128 v[6:9], v96 offset:3408
	ds_read_b128 v[10:13], v96 offset:3648
	ds_read_b128 v[14:17], v96 offset:3664
	ds_read_b128 v[34:37], v96 offset:3904
	ds_read_b128 v[38:41], v96 offset:3920
	ds_read_b128 v[26:29], v96 offset:4160
	ds_read_b128 v[30:33], v96 offset:4176
	v_pk_fma_f32 v[70:71], v[86:87], v[72:73], v[70:71]
	s_waitcnt lgkmcnt(14)
	v_pk_fma_f32 v[72:73], v[88:89], v[74:75], v[78:79]
	v_pk_fma_f32 v[66:67], v[88:89], v[66:67], v[70:71]
	v_mov_b32_e32 v95, s7
	ds_read_b32 v94, v103 offset:4416
	ds_read_b64 v[96:97], v95 offset:4672
	v_pk_fma_f32 v[70:71], v[90:91], v[76:77], v[72:73]
	v_pk_fma_f32 v[68:69], v[90:91], v[68:69], v[66:67]
	v_add_f32_e32 v66, v70, v71
	v_add_f32_e32 v67, v68, v69
	s_nop 0
	v_add_f32_dpp v66, v66, v66 quad_perm:[1,0,3,2] row_mask:0xf bank_mask:0xf bound_ctrl:1
	v_add_f32_dpp v67, v67, v67 quad_perm:[1,0,3,2] row_mask:0xf bank_mask:0xf bound_ctrl:1
	s_nop 0
	v_add_f32_dpp v66, v66, v66 quad_perm:[2,3,0,1] row_mask:0xf bank_mask:0xf bound_ctrl:1
	v_add_f32_dpp v68, v67, v67 quad_perm:[2,3,0,1] row_mask:0xf bank_mask:0xf bound_ctrl:1
	s_nop 0
	v_add_f32_dpp v66, v66, v66 row_half_mirror row_mask:0xf bank_mask:0xf bound_ctrl:1
	s_waitcnt lgkmcnt(13)
	v_mov_b32_e32 v67, v0
	s_waitcnt lgkmcnt(12)
	v_pk_mul_f32 v[70:71], v[98:99], v[66:67]
	v_add_f32_dpp v67, v68, v68 row_half_mirror row_mask:0xf bank_mask:0xf bound_ctrl:1
	v_add_f32_e32 v67, v70, v67
	s_add_i32 s20, s2, s46
	v_add_f32_e32 v67, v71, v67
	s_ashr_i32 s21, s20, 31
	v_bfe_u32 v68, v67, 16, 1
	s_lshl_b64 s[20:21], s[20:21], 9
	v_add3_u32 v67, v67, v68, s28
	v_lshl_add_u64 v[68:69], v[92:93], 0, s[20:21]
	global_store_short_d16_hi v[68:69], v67, off
	v_pk_mul_f32 v[50:51], v[50:51], v[84:85]
	v_pk_mul_f32 v[46:47], v[46:47], v[88:89]
	s_waitcnt lgkmcnt(14)
	v_pk_fma_f32 v[50:51], v[66:67], v[62:63], v[50:51] op_sel_hi:[0,1,1]
	v_pk_fma_f32 v[46:47], v[66:67], v[58:59], v[46:47] op_sel_hi:[0,1,1]
	s_waitcnt lgkmcnt(13)
	v_pk_fma_f32 v[84:85], v[0:1], v[54:55], v[50:51] op_sel_hi:[0,1,1]
	v_pk_mul_f32 v[50:51], v[52:53], v[86:87]
	v_pk_fma_f32 v[88:89], v[0:1], v[42:43], v[46:47] op_sel_hi:[0,1,1]
	v_pk_mul_f32 v[42:43], v[48:49], v[90:91]
	v_pk_fma_f32 v[50:51], v[66:67], v[64:65], v[50:51] op_sel_hi:[0,1,1]
	v_pk_fma_f32 v[42:43], v[66:67], v[60:61], v[42:43] op_sel_hi:[0,1,1]
	s_add_i32 s46, s46, s3
	s_add_i32 s10, s10, 2
	s_addk_i32 s7, 0xc40
	v_pk_fma_f32 v[86:87], v[0:1], v[56:57], v[50:51] op_sel_hi:[0,1,1]
	v_pk_fma_f32 v[90:91], v[0:1], v[44:45], v[42:43] op_sel_hi:[0,1,1]
	s_waitcnt lgkmcnt(0)
	v_mov_b32_e32 v95, v96
	v_add_u32_e32 v96, s7, v100
	ds_read_b128 v[70:73], v96 offset:1568
	ds_read_b128 v[66:69], v96 offset:1584
	ds_read_b128 v[50:53], v96 offset:1824
	ds_read_b128 v[46:49], v96 offset:1840
	ds_read_b128 v[54:57], v96 offset:2080
	ds_read_b128 v[42:45], v96 offset:2096
	ds_read_b128 v[78:81], v96 offset:2336
	ds_read_b128 v[74:77], v96 offset:2352
	ds_read_b128 v[62:65], v96 offset:2592
	ds_read_b128 v[58:61], v96 offset:2608
	v_pk_fma_f32 v[34:35], v[84:85], v[34:35], 0 op_sel_hi:[1,1,0]
	v_pk_fma_f32 v[22:23], v[84:85], v[22:23], 0 op_sel_hi:[1,1,0]
	v_pk_fma_f32 v[34:35], v[86:87], v[36:37], v[34:35]
	v_pk_fma_f32 v[22:23], v[86:87], v[24:25], v[22:23]
	v_add_u32_e32 v103, s7, v102
	v_mov_b32_e32 v98, s7
	v_pk_fma_f32 v[24:25], v[88:89], v[38:39], v[34:35]
	v_pk_fma_f32 v[18:19], v[88:89], v[18:19], v[22:23]
	ds_read_b32 v0, v103 offset:2848
	ds_read_b64 v[98:99], v98 offset:3104
	v_pk_fma_f32 v[22:23], v[90:91], v[40:41], v[24:25]
	v_pk_fma_f32 v[20:21], v[90:91], v[20:21], v[18:19]
	v_add_f32_e32 v18, v22, v23
	v_add_f32_e32 v19, v20, v21
	s_nop 0
	v_add_f32_dpp v18, v18, v18 quad_perm:[1,0,3,2] row_mask:0xf bank_mask:0xf bound_ctrl:1
	v_add_f32_dpp v19, v19, v19 quad_perm:[1,0,3,2] row_mask:0xf bank_mask:0xf bound_ctrl:1
	s_nop 0
	v_add_f32_dpp v18, v18, v18 quad_perm:[2,3,0,1] row_mask:0xf bank_mask:0xf bound_ctrl:1
	v_add_f32_dpp v19, v19, v19 quad_perm:[2,3,0,1] row_mask:0xf bank_mask:0xf bound_ctrl:1
	s_nop 0
	v_add_f32_dpp v18, v18, v18 row_half_mirror row_mask:0xf bank_mask:0xf bound_ctrl:1
	v_mov_b32_e32 v22, v97
	v_mov_b32_e32 v23, v18
	v_pk_mul_f32 v[22:23], v[22:23], v[94:95]
	v_add_f32_dpp v19, v19, v19 row_half_mirror row_mask:0xf bank_mask:0xf bound_ctrl:1
	v_add_f32_e32 v19, v23, v19
	v_add_f32_e32 v19, v22, v19
	s_ashr_i32 s47, s46, 31
	v_bfe_u32 v20, v19, 16, 1
	s_lshl_b64 s[20:21], s[46:47], 9
	v_add3_u32 v19, v19, v20, s28
	v_lshl_add_u64 v[20:21], v[92:93], 0, s[20:21]
	global_store_short_d16_hi v[20:21], v19, off
	v_pk_mul_f32 v[2:3], v[84:85], v[2:3]
	s_nop 0
	v_pk_fma_f32 v[2:3], v[18:19], v[26:27], v[2:3] op_sel_hi:[0,1,1]
	v_pk_fma_f32 v[84:85], v[94:95], v[10:11], v[2:3] op_sel_hi:[0,1,1]
	v_pk_mul_f32 v[2:3], v[86:87], v[4:5]
	s_waitcnt lgkmcnt(5)
	v_pk_fma_f32 v[78:79], v[84:85], v[78:79], 0 op_sel_hi:[1,1,0]
	v_pk_fma_f32 v[2:3], v[18:19], v[28:29], v[2:3] op_sel_hi:[0,1,1]
	v_pk_fma_f32 v[86:87], v[94:95], v[12:13], v[2:3] op_sel_hi:[0,1,1]
	v_pk_mul_f32 v[2:3], v[88:89], v[6:7]
	v_pk_fma_f32 v[70:71], v[84:85], v[70:71], 0 op_sel_hi:[1,1,0]
	v_pk_fma_f32 v[2:3], v[18:19], v[30:31], v[2:3] op_sel_hi:[0,1,1]
	v_pk_fma_f32 v[88:89], v[94:95], v[14:15], v[2:3] op_sel_hi:[0,1,1]
	v_pk_mul_f32 v[2:3], v[90:91], v[8:9]
	v_pk_fma_f32 v[78:79], v[86:87], v[80:81], v[78:79]
	v_pk_fma_f32 v[2:3], v[18:19], v[32:33], v[2:3] op_sel_hi:[0,1,1]
	v_pk_fma_f32 v[90:91], v[94:95], v[16:17], v[2:3] op_sel_hi:[0,1,1]
	ds_read_b128 v[22:25], v96 offset:3136
	ds_read_b128 v[18:21], v96 offset:3152
	ds_read_b128 v[2:5], v96 offset:3392
	ds_read_b128 v[6:9], v96 offset:3408
	ds_read_b128 v[10:13], v96 offset:3648
	ds_read_b128 v[14:17], v96 offset:3664
	ds_read_b128 v[34:37], v96 offset:3904
	ds_read_b128 v[38:41], v96 offset:3920
	ds_read_b128 v[26:29], v96 offset:4160
	ds_read_b128 v[30:33], v96 offset:4176
	v_pk_fma_f32 v[70:71], v[86:87], v[72:73], v[70:71]
	s_waitcnt lgkmcnt(14)
	v_pk_fma_f32 v[72:73], v[88:89], v[74:75], v[78:79]
	v_pk_fma_f32 v[66:67], v[88:89], v[66:67], v[70:71]
	v_mov_b32_e32 v95, s7
	ds_read_b32 v94, v103 offset:4416
	ds_read_b64 v[96:97], v95 offset:4672
	v_pk_fma_f32 v[70:71], v[90:91], v[76:77], v[72:73]
	v_pk_fma_f32 v[68:69], v[90:91], v[68:69], v[66:67]
	v_add_f32_e32 v66, v70, v71
	v_add_f32_e32 v67, v68, v69
	s_nop 0
	v_add_f32_dpp v66, v66, v66 quad_perm:[1,0,3,2] row_mask:0xf bank_mask:0xf bound_ctrl:1
	v_add_f32_dpp v67, v67, v67 quad_perm:[1,0,3,2] row_mask:0xf bank_mask:0xf bound_ctrl:1
	s_nop 0
	v_add_f32_dpp v66, v66, v66 quad_perm:[2,3,0,1] row_mask:0xf bank_mask:0xf bound_ctrl:1
	v_add_f32_dpp v68, v67, v67 quad_perm:[2,3,0,1] row_mask:0xf bank_mask:0xf bound_ctrl:1
	s_nop 0
	v_add_f32_dpp v66, v66, v66 row_half_mirror row_mask:0xf bank_mask:0xf bound_ctrl:1
	s_waitcnt lgkmcnt(13)
	v_mov_b32_e32 v67, v0
	s_waitcnt lgkmcnt(12)
	v_pk_mul_f32 v[70:71], v[98:99], v[66:67]
	v_add_f32_dpp v67, v68, v68 row_half_mirror row_mask:0xf bank_mask:0xf bound_ctrl:1
	v_add_f32_e32 v67, v70, v67
	s_add_i32 s20, s2, s46
	v_add_f32_e32 v67, v71, v67
	s_ashr_i32 s21, s20, 31
	v_bfe_u32 v68, v67, 16, 1
	s_lshl_b64 s[20:21], s[20:21], 9
	v_add3_u32 v67, v67, v68, s28
	v_lshl_add_u64 v[68:69], v[92:93], 0, s[20:21]
	global_store_short_d16_hi v[68:69], v67, off
	v_pk_mul_f32 v[50:51], v[50:51], v[84:85]
	v_pk_mul_f32 v[46:47], v[46:47], v[88:89]
	s_waitcnt lgkmcnt(14)
	v_pk_fma_f32 v[50:51], v[66:67], v[62:63], v[50:51] op_sel_hi:[0,1,1]
	v_pk_fma_f32 v[46:47], v[66:67], v[58:59], v[46:47] op_sel_hi:[0,1,1]
	s_waitcnt lgkmcnt(13)
	v_pk_fma_f32 v[84:85], v[0:1], v[54:55], v[50:51] op_sel_hi:[0,1,1]
	v_pk_mul_f32 v[50:51], v[52:53], v[86:87]
	v_pk_fma_f32 v[88:89], v[0:1], v[42:43], v[46:47] op_sel_hi:[0,1,1]
	v_pk_mul_f32 v[42:43], v[48:49], v[90:91]
	v_pk_fma_f32 v[50:51], v[66:67], v[64:65], v[50:51] op_sel_hi:[0,1,1]
	v_pk_fma_f32 v[42:43], v[66:67], v[60:61], v[42:43] op_sel_hi:[0,1,1]
	s_add_i32 s46, s46, s3
	s_add_i32 s10, s10, 2
	s_addk_i32 s7, 0xc40
	v_pk_fma_f32 v[86:87], v[0:1], v[56:57], v[50:51] op_sel_hi:[0,1,1]
	v_pk_fma_f32 v[90:91], v[0:1], v[44:45], v[42:43] op_sel_hi:[0,1,1]
	s_waitcnt lgkmcnt(0)
	v_mov_b32_e32 v95, v96
	v_add_u32_e32 v96, s7, v100
	ds_read_b128 v[70:73], v96 offset:1568
	ds_read_b128 v[66:69], v96 offset:1584
	ds_read_b128 v[50:53], v96 offset:1824
	ds_read_b128 v[46:49], v96 offset:1840
	ds_read_b128 v[54:57], v96 offset:2080
	ds_read_b128 v[42:45], v96 offset:2096
	ds_read_b128 v[78:81], v96 offset:2336
	ds_read_b128 v[74:77], v96 offset:2352
	ds_read_b128 v[62:65], v96 offset:2592
	ds_read_b128 v[58:61], v96 offset:2608
	v_pk_fma_f32 v[34:35], v[84:85], v[34:35], 0 op_sel_hi:[1,1,0]
	v_pk_fma_f32 v[22:23], v[84:85], v[22:23], 0 op_sel_hi:[1,1,0]
	v_pk_fma_f32 v[34:35], v[86:87], v[36:37], v[34:35]
	v_pk_fma_f32 v[22:23], v[86:87], v[24:25], v[22:23]
	v_add_u32_e32 v103, s7, v102
	v_mov_b32_e32 v98, s7
	v_pk_fma_f32 v[24:25], v[88:89], v[38:39], v[34:35]
	v_pk_fma_f32 v[18:19], v[88:89], v[18:19], v[22:23]
	ds_read_b32 v0, v103 offset:2848
	ds_read_b64 v[98:99], v98 offset:3104
	v_pk_fma_f32 v[22:23], v[90:91], v[40:41], v[24:25]
	v_pk_fma_f32 v[20:21], v[90:91], v[20:21], v[18:19]
	v_add_f32_e32 v18, v22, v23
	v_add_f32_e32 v19, v20, v21
	s_nop 0
	v_add_f32_dpp v18, v18, v18 quad_perm:[1,0,3,2] row_mask:0xf bank_mask:0xf bound_ctrl:1
	v_add_f32_dpp v19, v19, v19 quad_perm:[1,0,3,2] row_mask:0xf bank_mask:0xf bound_ctrl:1
	s_nop 0
	v_add_f32_dpp v18, v18, v18 quad_perm:[2,3,0,1] row_mask:0xf bank_mask:0xf bound_ctrl:1
	v_add_f32_dpp v19, v19, v19 quad_perm:[2,3,0,1] row_mask:0xf bank_mask:0xf bound_ctrl:1
	s_nop 0
	v_add_f32_dpp v18, v18, v18 row_half_mirror row_mask:0xf bank_mask:0xf bound_ctrl:1
	v_mov_b32_e32 v22, v97
	v_mov_b32_e32 v23, v18
	v_pk_mul_f32 v[22:23], v[22:23], v[94:95]
	v_add_f32_dpp v19, v19, v19 row_half_mirror row_mask:0xf bank_mask:0xf bound_ctrl:1
	v_add_f32_e32 v19, v23, v19
	v_add_f32_e32 v19, v22, v19
	s_ashr_i32 s47, s46, 31
	v_bfe_u32 v20, v19, 16, 1
	s_lshl_b64 s[20:21], s[46:47], 9
	v_add3_u32 v19, v19, v20, s28
	v_lshl_add_u64 v[20:21], v[92:93], 0, s[20:21]
	global_store_short_d16_hi v[20:21], v19, off
	v_pk_mul_f32 v[2:3], v[84:85], v[2:3]
	s_nop 0
	v_pk_fma_f32 v[2:3], v[18:19], v[26:27], v[2:3] op_sel_hi:[0,1,1]
	v_pk_fma_f32 v[84:85], v[94:95], v[10:11], v[2:3] op_sel_hi:[0,1,1]
	v_pk_mul_f32 v[2:3], v[86:87], v[4:5]
	s_waitcnt lgkmcnt(5)
	v_pk_fma_f32 v[78:79], v[84:85], v[78:79], 0 op_sel_hi:[1,1,0]
	v_pk_fma_f32 v[2:3], v[18:19], v[28:29], v[2:3] op_sel_hi:[0,1,1]
	v_pk_fma_f32 v[86:87], v[94:95], v[12:13], v[2:3] op_sel_hi:[0,1,1]
	v_pk_mul_f32 v[2:3], v[88:89], v[6:7]
	v_pk_fma_f32 v[70:71], v[84:85], v[70:71], 0 op_sel_hi:[1,1,0]
	v_pk_fma_f32 v[2:3], v[18:19], v[30:31], v[2:3] op_sel_hi:[0,1,1]
	v_pk_fma_f32 v[88:89], v[94:95], v[14:15], v[2:3] op_sel_hi:[0,1,1]
	v_pk_mul_f32 v[2:3], v[90:91], v[8:9]
	v_pk_fma_f32 v[78:79], v[86:87], v[80:81], v[78:79]
	v_pk_fma_f32 v[2:3], v[18:19], v[32:33], v[2:3] op_sel_hi:[0,1,1]
	v_pk_fma_f32 v[90:91], v[94:95], v[16:17], v[2:3] op_sel_hi:[0,1,1]
	ds_read_b128 v[22:25], v96 offset:3136
	ds_read_b128 v[18:21], v96 offset:3152
	ds_read_b128 v[2:5], v96 offset:3392
	ds_read_b128 v[6:9], v96 offset:3408
	ds_read_b128 v[10:13], v96 offset:3648
	ds_read_b128 v[14:17], v96 offset:3664
	ds_read_b128 v[34:37], v96 offset:3904
	ds_read_b128 v[38:41], v96 offset:3920
	ds_read_b128 v[26:29], v96 offset:4160
	ds_read_b128 v[30:33], v96 offset:4176
	v_pk_fma_f32 v[70:71], v[86:87], v[72:73], v[70:71]
	s_waitcnt lgkmcnt(14)
	v_pk_fma_f32 v[72:73], v[88:89], v[74:75], v[78:79]
	v_pk_fma_f32 v[66:67], v[88:89], v[66:67], v[70:71]
	v_mov_b32_e32 v95, s7
	ds_read_b32 v94, v103 offset:4416
	ds_read_b64 v[96:97], v95 offset:4672
	v_pk_fma_f32 v[70:71], v[90:91], v[76:77], v[72:73]
	v_pk_fma_f32 v[68:69], v[90:91], v[68:69], v[66:67]
	v_add_f32_e32 v66, v70, v71
	v_add_f32_e32 v67, v68, v69
	s_nop 0
	v_add_f32_dpp v66, v66, v66 quad_perm:[1,0,3,2] row_mask:0xf bank_mask:0xf bound_ctrl:1
	v_add_f32_dpp v67, v67, v67 quad_perm:[1,0,3,2] row_mask:0xf bank_mask:0xf bound_ctrl:1
	s_nop 0
	v_add_f32_dpp v66, v66, v66 quad_perm:[2,3,0,1] row_mask:0xf bank_mask:0xf bound_ctrl:1
	v_add_f32_dpp v68, v67, v67 quad_perm:[2,3,0,1] row_mask:0xf bank_mask:0xf bound_ctrl:1
	s_nop 0
	v_add_f32_dpp v66, v66, v66 row_half_mirror row_mask:0xf bank_mask:0xf bound_ctrl:1
	s_waitcnt lgkmcnt(13)
	v_mov_b32_e32 v67, v0
	s_waitcnt lgkmcnt(12)
	v_pk_mul_f32 v[70:71], v[98:99], v[66:67]
	v_add_f32_dpp v67, v68, v68 row_half_mirror row_mask:0xf bank_mask:0xf bound_ctrl:1
	v_add_f32_e32 v67, v70, v67
	s_add_i32 s20, s2, s46
	v_add_f32_e32 v67, v71, v67
	s_ashr_i32 s21, s20, 31
	v_bfe_u32 v68, v67, 16, 1
	s_lshl_b64 s[20:21], s[20:21], 9
	v_add3_u32 v67, v67, v68, s28
	v_lshl_add_u64 v[68:69], v[92:93], 0, s[20:21]
	global_store_short_d16_hi v[68:69], v67, off
	v_pk_mul_f32 v[50:51], v[50:51], v[84:85]
	v_pk_mul_f32 v[46:47], v[46:47], v[88:89]
	s_waitcnt lgkmcnt(14)
	v_pk_fma_f32 v[50:51], v[66:67], v[62:63], v[50:51] op_sel_hi:[0,1,1]
	v_pk_fma_f32 v[46:47], v[66:67], v[58:59], v[46:47] op_sel_hi:[0,1,1]
	s_waitcnt lgkmcnt(13)
	v_pk_fma_f32 v[84:85], v[0:1], v[54:55], v[50:51] op_sel_hi:[0,1,1]
	v_pk_mul_f32 v[50:51], v[52:53], v[86:87]
	v_pk_fma_f32 v[88:89], v[0:1], v[42:43], v[46:47] op_sel_hi:[0,1,1]
	v_pk_mul_f32 v[42:43], v[48:49], v[90:91]
	v_pk_fma_f32 v[50:51], v[66:67], v[64:65], v[50:51] op_sel_hi:[0,1,1]
	v_pk_fma_f32 v[42:43], v[66:67], v[60:61], v[42:43] op_sel_hi:[0,1,1]
	s_add_i32 s46, s46, s3
	s_add_i32 s10, s10, 2
	s_addk_i32 s7, 0xc40
	v_pk_fma_f32 v[86:87], v[0:1], v[56:57], v[50:51] op_sel_hi:[0,1,1]
	v_pk_fma_f32 v[90:91], v[0:1], v[44:45], v[42:43] op_sel_hi:[0,1,1]
	s_waitcnt lgkmcnt(0)
	v_mov_b32_e32 v95, v96
	v_add_u32_e32 v96, s7, v100
	ds_read_b128 v[70:73], v96 offset:1568
	ds_read_b128 v[66:69], v96 offset:1584
	ds_read_b128 v[50:53], v96 offset:1824
	ds_read_b128 v[46:49], v96 offset:1840
	ds_read_b128 v[54:57], v96 offset:2080
	ds_read_b128 v[42:45], v96 offset:2096
	ds_read_b128 v[78:81], v96 offset:2336
	ds_read_b128 v[74:77], v96 offset:2352
	ds_read_b128 v[62:65], v96 offset:2592
	ds_read_b128 v[58:61], v96 offset:2608
	v_pk_fma_f32 v[34:35], v[84:85], v[34:35], 0 op_sel_hi:[1,1,0]
	v_pk_fma_f32 v[22:23], v[84:85], v[22:23], 0 op_sel_hi:[1,1,0]
	v_pk_fma_f32 v[34:35], v[86:87], v[36:37], v[34:35]
	v_pk_fma_f32 v[22:23], v[86:87], v[24:25], v[22:23]
	v_add_u32_e32 v103, s7, v102
	v_mov_b32_e32 v98, s7
	v_pk_fma_f32 v[24:25], v[88:89], v[38:39], v[34:35]
	v_pk_fma_f32 v[18:19], v[88:89], v[18:19], v[22:23]
	ds_read_b32 v0, v103 offset:2848
	ds_read_b64 v[98:99], v98 offset:3104
	v_pk_fma_f32 v[22:23], v[90:91], v[40:41], v[24:25]
	v_pk_fma_f32 v[20:21], v[90:91], v[20:21], v[18:19]
	v_add_f32_e32 v18, v22, v23
	v_add_f32_e32 v19, v20, v21
	s_nop 0
	v_add_f32_dpp v18, v18, v18 quad_perm:[1,0,3,2] row_mask:0xf bank_mask:0xf bound_ctrl:1
	v_add_f32_dpp v19, v19, v19 quad_perm:[1,0,3,2] row_mask:0xf bank_mask:0xf bound_ctrl:1
	s_nop 0
	v_add_f32_dpp v18, v18, v18 quad_perm:[2,3,0,1] row_mask:0xf bank_mask:0xf bound_ctrl:1
	v_add_f32_dpp v19, v19, v19 quad_perm:[2,3,0,1] row_mask:0xf bank_mask:0xf bound_ctrl:1
	s_nop 0
	v_add_f32_dpp v18, v18, v18 row_half_mirror row_mask:0xf bank_mask:0xf bound_ctrl:1
	v_mov_b32_e32 v22, v97
	v_mov_b32_e32 v23, v18
	v_pk_mul_f32 v[22:23], v[22:23], v[94:95]
	v_add_f32_dpp v19, v19, v19 row_half_mirror row_mask:0xf bank_mask:0xf bound_ctrl:1
	v_add_f32_e32 v19, v23, v19
	v_add_f32_e32 v19, v22, v19
	s_ashr_i32 s47, s46, 31
	v_bfe_u32 v20, v19, 16, 1
	s_lshl_b64 s[20:21], s[46:47], 9
	v_add3_u32 v19, v19, v20, s28
	v_lshl_add_u64 v[20:21], v[92:93], 0, s[20:21]
	global_store_short_d16_hi v[20:21], v19, off
	v_pk_mul_f32 v[2:3], v[84:85], v[2:3]
	s_nop 0
	v_pk_fma_f32 v[2:3], v[18:19], v[26:27], v[2:3] op_sel_hi:[0,1,1]
	v_pk_fma_f32 v[84:85], v[94:95], v[10:11], v[2:3] op_sel_hi:[0,1,1]
	v_pk_mul_f32 v[2:3], v[86:87], v[4:5]
	s_waitcnt lgkmcnt(5)
	v_pk_fma_f32 v[78:79], v[84:85], v[78:79], 0 op_sel_hi:[1,1,0]
	v_pk_fma_f32 v[2:3], v[18:19], v[28:29], v[2:3] op_sel_hi:[0,1,1]
	v_pk_fma_f32 v[86:87], v[94:95], v[12:13], v[2:3] op_sel_hi:[0,1,1]
	v_pk_mul_f32 v[2:3], v[88:89], v[6:7]
	v_pk_fma_f32 v[70:71], v[84:85], v[70:71], 0 op_sel_hi:[1,1,0]
	v_pk_fma_f32 v[2:3], v[18:19], v[30:31], v[2:3] op_sel_hi:[0,1,1]
	v_pk_fma_f32 v[88:89], v[94:95], v[14:15], v[2:3] op_sel_hi:[0,1,1]
	v_pk_mul_f32 v[2:3], v[90:91], v[8:9]
	v_pk_fma_f32 v[78:79], v[86:87], v[80:81], v[78:79]
	v_pk_fma_f32 v[2:3], v[18:19], v[32:33], v[2:3] op_sel_hi:[0,1,1]
	v_pk_fma_f32 v[90:91], v[94:95], v[16:17], v[2:3] op_sel_hi:[0,1,1]
	ds_read_b128 v[22:25], v96 offset:3136
	ds_read_b128 v[18:21], v96 offset:3152
	ds_read_b128 v[2:5], v96 offset:3392
	ds_read_b128 v[6:9], v96 offset:3408
	ds_read_b128 v[10:13], v96 offset:3648
	ds_read_b128 v[14:17], v96 offset:3664
	ds_read_b128 v[34:37], v96 offset:3904
	ds_read_b128 v[38:41], v96 offset:3920
	ds_read_b128 v[26:29], v96 offset:4160
	ds_read_b128 v[30:33], v96 offset:4176
	v_pk_fma_f32 v[70:71], v[86:87], v[72:73], v[70:71]
	s_waitcnt lgkmcnt(14)
	v_pk_fma_f32 v[72:73], v[88:89], v[74:75], v[78:79]
	v_pk_fma_f32 v[66:67], v[88:89], v[66:67], v[70:71]
	v_mov_b32_e32 v95, s7
	ds_read_b32 v94, v103 offset:4416
	ds_read_b64 v[96:97], v95 offset:4672
	v_pk_fma_f32 v[70:71], v[90:91], v[76:77], v[72:73]
	v_pk_fma_f32 v[68:69], v[90:91], v[68:69], v[66:67]
	v_add_f32_e32 v66, v70, v71
	v_add_f32_e32 v67, v68, v69
	s_nop 0
	v_add_f32_dpp v66, v66, v66 quad_perm:[1,0,3,2] row_mask:0xf bank_mask:0xf bound_ctrl:1
	v_add_f32_dpp v67, v67, v67 quad_perm:[1,0,3,2] row_mask:0xf bank_mask:0xf bound_ctrl:1
	s_nop 0
	v_add_f32_dpp v66, v66, v66 quad_perm:[2,3,0,1] row_mask:0xf bank_mask:0xf bound_ctrl:1
	v_add_f32_dpp v68, v67, v67 quad_perm:[2,3,0,1] row_mask:0xf bank_mask:0xf bound_ctrl:1
	s_nop 0
	v_add_f32_dpp v66, v66, v66 row_half_mirror row_mask:0xf bank_mask:0xf bound_ctrl:1
	s_waitcnt lgkmcnt(13)
	v_mov_b32_e32 v67, v0
	s_waitcnt lgkmcnt(12)
	v_pk_mul_f32 v[70:71], v[98:99], v[66:67]
	v_add_f32_dpp v67, v68, v68 row_half_mirror row_mask:0xf bank_mask:0xf bound_ctrl:1
	v_add_f32_e32 v67, v70, v67
	s_add_i32 s20, s2, s46
	v_add_f32_e32 v67, v71, v67
	s_ashr_i32 s21, s20, 31
	v_bfe_u32 v68, v67, 16, 1
	s_lshl_b64 s[20:21], s[20:21], 9
	v_add3_u32 v67, v67, v68, s28
	v_lshl_add_u64 v[68:69], v[92:93], 0, s[20:21]
	global_store_short_d16_hi v[68:69], v67, off
	v_pk_mul_f32 v[50:51], v[50:51], v[84:85]
	v_pk_mul_f32 v[46:47], v[46:47], v[88:89]
	s_waitcnt lgkmcnt(14)
	v_pk_fma_f32 v[50:51], v[66:67], v[62:63], v[50:51] op_sel_hi:[0,1,1]
	v_pk_fma_f32 v[46:47], v[66:67], v[58:59], v[46:47] op_sel_hi:[0,1,1]
	s_waitcnt lgkmcnt(13)
	v_pk_fma_f32 v[84:85], v[0:1], v[54:55], v[50:51] op_sel_hi:[0,1,1]
	v_pk_mul_f32 v[50:51], v[52:53], v[86:87]
	v_pk_fma_f32 v[88:89], v[0:1], v[42:43], v[46:47] op_sel_hi:[0,1,1]
	v_pk_mul_f32 v[42:43], v[48:49], v[90:91]
	v_pk_fma_f32 v[50:51], v[66:67], v[64:65], v[50:51] op_sel_hi:[0,1,1]
	v_pk_fma_f32 v[42:43], v[66:67], v[60:61], v[42:43] op_sel_hi:[0,1,1]
	s_add_i32 s46, s46, s3
	s_add_i32 s10, s10, 2
	s_addk_i32 s7, 0xc40
	v_pk_fma_f32 v[86:87], v[0:1], v[56:57], v[50:51] op_sel_hi:[0,1,1]
	v_pk_fma_f32 v[90:91], v[0:1], v[44:45], v[42:43] op_sel_hi:[0,1,1]
	s_waitcnt lgkmcnt(0)
	v_mov_b32_e32 v95, v96
	v_add_u32_e32 v96, s7, v100
	ds_read_b128 v[70:73], v96 offset:1568
	ds_read_b128 v[66:69], v96 offset:1584
	ds_read_b128 v[50:53], v96 offset:1824
	ds_read_b128 v[46:49], v96 offset:1840
	ds_read_b128 v[54:57], v96 offset:2080
	ds_read_b128 v[42:45], v96 offset:2096
	ds_read_b128 v[78:81], v96 offset:2336
	ds_read_b128 v[74:77], v96 offset:2352
	ds_read_b128 v[62:65], v96 offset:2592
	ds_read_b128 v[58:61], v96 offset:2608
	v_pk_fma_f32 v[34:35], v[84:85], v[34:35], 0 op_sel_hi:[1,1,0]
	v_pk_fma_f32 v[22:23], v[84:85], v[22:23], 0 op_sel_hi:[1,1,0]
	v_pk_fma_f32 v[34:35], v[86:87], v[36:37], v[34:35]
	v_pk_fma_f32 v[22:23], v[86:87], v[24:25], v[22:23]
	v_add_u32_e32 v103, s7, v102
	v_mov_b32_e32 v98, s7
	v_pk_fma_f32 v[24:25], v[88:89], v[38:39], v[34:35]
	v_pk_fma_f32 v[18:19], v[88:89], v[18:19], v[22:23]
	ds_read_b32 v0, v103 offset:2848
	ds_read_b64 v[98:99], v98 offset:3104
	v_pk_fma_f32 v[22:23], v[90:91], v[40:41], v[24:25]
	v_pk_fma_f32 v[20:21], v[90:91], v[20:21], v[18:19]
	v_add_f32_e32 v18, v22, v23
	v_add_f32_e32 v19, v20, v21
	s_nop 0
	v_add_f32_dpp v18, v18, v18 quad_perm:[1,0,3,2] row_mask:0xf bank_mask:0xf bound_ctrl:1
	v_add_f32_dpp v19, v19, v19 quad_perm:[1,0,3,2] row_mask:0xf bank_mask:0xf bound_ctrl:1
	s_nop 0
	v_add_f32_dpp v18, v18, v18 quad_perm:[2,3,0,1] row_mask:0xf bank_mask:0xf bound_ctrl:1
	v_add_f32_dpp v19, v19, v19 quad_perm:[2,3,0,1] row_mask:0xf bank_mask:0xf bound_ctrl:1
	s_nop 0
	v_add_f32_dpp v18, v18, v18 row_half_mirror row_mask:0xf bank_mask:0xf bound_ctrl:1
	v_mov_b32_e32 v22, v97
	v_mov_b32_e32 v23, v18
	v_pk_mul_f32 v[22:23], v[22:23], v[94:95]
	v_add_f32_dpp v19, v19, v19 row_half_mirror row_mask:0xf bank_mask:0xf bound_ctrl:1
	v_add_f32_e32 v19, v23, v19
	v_add_f32_e32 v19, v22, v19
	s_ashr_i32 s47, s46, 31
	v_bfe_u32 v20, v19, 16, 1
	s_lshl_b64 s[20:21], s[46:47], 9
	v_add3_u32 v19, v19, v20, s28
	v_lshl_add_u64 v[20:21], v[92:93], 0, s[20:21]
	global_store_short_d16_hi v[20:21], v19, off
	v_pk_mul_f32 v[2:3], v[84:85], v[2:3]
	s_nop 0
	v_pk_fma_f32 v[2:3], v[18:19], v[26:27], v[2:3] op_sel_hi:[0,1,1]
	v_pk_fma_f32 v[84:85], v[94:95], v[10:11], v[2:3] op_sel_hi:[0,1,1]
	v_pk_mul_f32 v[2:3], v[86:87], v[4:5]
	s_waitcnt lgkmcnt(5)
	v_pk_fma_f32 v[78:79], v[84:85], v[78:79], 0 op_sel_hi:[1,1,0]
	v_pk_fma_f32 v[2:3], v[18:19], v[28:29], v[2:3] op_sel_hi:[0,1,1]
	v_pk_fma_f32 v[86:87], v[94:95], v[12:13], v[2:3] op_sel_hi:[0,1,1]
	v_pk_mul_f32 v[2:3], v[88:89], v[6:7]
	v_pk_fma_f32 v[70:71], v[84:85], v[70:71], 0 op_sel_hi:[1,1,0]
	v_pk_fma_f32 v[2:3], v[18:19], v[30:31], v[2:3] op_sel_hi:[0,1,1]
	v_pk_fma_f32 v[88:89], v[94:95], v[14:15], v[2:3] op_sel_hi:[0,1,1]
	v_pk_mul_f32 v[2:3], v[90:91], v[8:9]
	v_pk_fma_f32 v[78:79], v[86:87], v[80:81], v[78:79]
	v_pk_fma_f32 v[2:3], v[18:19], v[32:33], v[2:3] op_sel_hi:[0,1,1]
	v_pk_fma_f32 v[90:91], v[94:95], v[16:17], v[2:3] op_sel_hi:[0,1,1]
	ds_read_b128 v[22:25], v96 offset:3136
	ds_read_b128 v[18:21], v96 offset:3152
	ds_read_b128 v[2:5], v96 offset:3392
	ds_read_b128 v[6:9], v96 offset:3408
	ds_read_b128 v[10:13], v96 offset:3648
	ds_read_b128 v[14:17], v96 offset:3664
	ds_read_b128 v[34:37], v96 offset:3904
	ds_read_b128 v[38:41], v96 offset:3920
	ds_read_b128 v[26:29], v96 offset:4160
	ds_read_b128 v[30:33], v96 offset:4176
	v_pk_fma_f32 v[70:71], v[86:87], v[72:73], v[70:71]
	s_waitcnt lgkmcnt(14)
	v_pk_fma_f32 v[72:73], v[88:89], v[74:75], v[78:79]
	v_pk_fma_f32 v[66:67], v[88:89], v[66:67], v[70:71]
	v_mov_b32_e32 v95, s7
	ds_read_b32 v94, v103 offset:4416
	ds_read_b64 v[96:97], v95 offset:4672
	v_pk_fma_f32 v[70:71], v[90:91], v[76:77], v[72:73]
	v_pk_fma_f32 v[68:69], v[90:91], v[68:69], v[66:67]
	v_add_f32_e32 v66, v70, v71
	v_add_f32_e32 v67, v68, v69
	s_nop 0
	v_add_f32_dpp v66, v66, v66 quad_perm:[1,0,3,2] row_mask:0xf bank_mask:0xf bound_ctrl:1
	v_add_f32_dpp v67, v67, v67 quad_perm:[1,0,3,2] row_mask:0xf bank_mask:0xf bound_ctrl:1
	s_nop 0
	v_add_f32_dpp v66, v66, v66 quad_perm:[2,3,0,1] row_mask:0xf bank_mask:0xf bound_ctrl:1
	v_add_f32_dpp v68, v67, v67 quad_perm:[2,3,0,1] row_mask:0xf bank_mask:0xf bound_ctrl:1
	s_nop 0
	v_add_f32_dpp v66, v66, v66 row_half_mirror row_mask:0xf bank_mask:0xf bound_ctrl:1
	s_waitcnt lgkmcnt(13)
	v_mov_b32_e32 v67, v0
	s_waitcnt lgkmcnt(12)
	v_pk_mul_f32 v[70:71], v[98:99], v[66:67]
	v_add_f32_dpp v67, v68, v68 row_half_mirror row_mask:0xf bank_mask:0xf bound_ctrl:1
	v_add_f32_e32 v67, v70, v67
	s_add_i32 s20, s2, s46
	v_add_f32_e32 v67, v71, v67
	s_ashr_i32 s21, s20, 31
	v_bfe_u32 v68, v67, 16, 1
	s_lshl_b64 s[20:21], s[20:21], 9
	v_add3_u32 v67, v67, v68, s28
	v_lshl_add_u64 v[68:69], v[92:93], 0, s[20:21]
	global_store_short_d16_hi v[68:69], v67, off
	v_pk_mul_f32 v[50:51], v[50:51], v[84:85]
	v_pk_mul_f32 v[46:47], v[46:47], v[88:89]
	s_waitcnt lgkmcnt(14)
	v_pk_fma_f32 v[50:51], v[66:67], v[62:63], v[50:51] op_sel_hi:[0,1,1]
	v_pk_fma_f32 v[46:47], v[66:67], v[58:59], v[46:47] op_sel_hi:[0,1,1]
	s_waitcnt lgkmcnt(13)
	v_pk_fma_f32 v[84:85], v[0:1], v[54:55], v[50:51] op_sel_hi:[0,1,1]
	v_pk_mul_f32 v[50:51], v[52:53], v[86:87]
	v_pk_fma_f32 v[88:89], v[0:1], v[42:43], v[46:47] op_sel_hi:[0,1,1]
	v_pk_mul_f32 v[42:43], v[48:49], v[90:91]
	v_pk_fma_f32 v[50:51], v[66:67], v[64:65], v[50:51] op_sel_hi:[0,1,1]
	v_pk_fma_f32 v[42:43], v[66:67], v[60:61], v[42:43] op_sel_hi:[0,1,1]
	s_add_i32 s46, s46, s3
	s_add_i32 s10, s10, 2
	s_addk_i32 s7, 0xc40
	v_pk_fma_f32 v[86:87], v[0:1], v[56:57], v[50:51] op_sel_hi:[0,1,1]
	v_pk_fma_f32 v[90:91], v[0:1], v[44:45], v[42:43] op_sel_hi:[0,1,1]
	s_waitcnt lgkmcnt(0)
	v_mov_b32_e32 v95, v96
	v_add_u32_e32 v96, s7, v100
	ds_read_b128 v[70:73], v96 offset:1568
	ds_read_b128 v[66:69], v96 offset:1584
	ds_read_b128 v[50:53], v96 offset:1824
	ds_read_b128 v[46:49], v96 offset:1840
	ds_read_b128 v[54:57], v96 offset:2080
	ds_read_b128 v[42:45], v96 offset:2096
	ds_read_b128 v[78:81], v96 offset:2336
	ds_read_b128 v[74:77], v96 offset:2352
	ds_read_b128 v[62:65], v96 offset:2592
	ds_read_b128 v[58:61], v96 offset:2608
	v_pk_fma_f32 v[34:35], v[84:85], v[34:35], 0 op_sel_hi:[1,1,0]
	v_pk_fma_f32 v[22:23], v[84:85], v[22:23], 0 op_sel_hi:[1,1,0]
	v_pk_fma_f32 v[34:35], v[86:87], v[36:37], v[34:35]
	v_pk_fma_f32 v[22:23], v[86:87], v[24:25], v[22:23]
	v_add_u32_e32 v103, s7, v102
	v_mov_b32_e32 v98, s7
	v_pk_fma_f32 v[24:25], v[88:89], v[38:39], v[34:35]
	v_pk_fma_f32 v[18:19], v[88:89], v[18:19], v[22:23]
	ds_read_b32 v0, v103 offset:2848
	ds_read_b64 v[98:99], v98 offset:3104
	v_pk_fma_f32 v[22:23], v[90:91], v[40:41], v[24:25]
	v_pk_fma_f32 v[20:21], v[90:91], v[20:21], v[18:19]
	v_add_f32_e32 v18, v22, v23
	v_add_f32_e32 v19, v20, v21
	s_nop 0
	v_add_f32_dpp v18, v18, v18 quad_perm:[1,0,3,2] row_mask:0xf bank_mask:0xf bound_ctrl:1
	v_add_f32_dpp v19, v19, v19 quad_perm:[1,0,3,2] row_mask:0xf bank_mask:0xf bound_ctrl:1
	s_nop 0
	v_add_f32_dpp v18, v18, v18 quad_perm:[2,3,0,1] row_mask:0xf bank_mask:0xf bound_ctrl:1
	v_add_f32_dpp v19, v19, v19 quad_perm:[2,3,0,1] row_mask:0xf bank_mask:0xf bound_ctrl:1
	s_nop 0
	v_add_f32_dpp v18, v18, v18 row_half_mirror row_mask:0xf bank_mask:0xf bound_ctrl:1
	v_mov_b32_e32 v22, v97
	v_mov_b32_e32 v23, v18
	v_pk_mul_f32 v[22:23], v[22:23], v[94:95]
	v_add_f32_dpp v19, v19, v19 row_half_mirror row_mask:0xf bank_mask:0xf bound_ctrl:1
	v_add_f32_e32 v19, v23, v19
	v_add_f32_e32 v19, v22, v19
	s_ashr_i32 s47, s46, 31
	v_bfe_u32 v20, v19, 16, 1
	s_lshl_b64 s[20:21], s[46:47], 9
	v_add3_u32 v19, v19, v20, s28
	v_lshl_add_u64 v[20:21], v[92:93], 0, s[20:21]
	global_store_short_d16_hi v[20:21], v19, off
	v_pk_mul_f32 v[2:3], v[84:85], v[2:3]
	s_nop 0
	v_pk_fma_f32 v[2:3], v[18:19], v[26:27], v[2:3] op_sel_hi:[0,1,1]
	v_pk_fma_f32 v[84:85], v[94:95], v[10:11], v[2:3] op_sel_hi:[0,1,1]
	v_pk_mul_f32 v[2:3], v[86:87], v[4:5]
	s_waitcnt lgkmcnt(5)
	v_pk_fma_f32 v[78:79], v[84:85], v[78:79], 0 op_sel_hi:[1,1,0]
	v_pk_fma_f32 v[2:3], v[18:19], v[28:29], v[2:3] op_sel_hi:[0,1,1]
	v_pk_fma_f32 v[86:87], v[94:95], v[12:13], v[2:3] op_sel_hi:[0,1,1]
	v_pk_mul_f32 v[2:3], v[88:89], v[6:7]
	v_pk_fma_f32 v[70:71], v[84:85], v[70:71], 0 op_sel_hi:[1,1,0]
	v_pk_fma_f32 v[2:3], v[18:19], v[30:31], v[2:3] op_sel_hi:[0,1,1]
	v_pk_fma_f32 v[88:89], v[94:95], v[14:15], v[2:3] op_sel_hi:[0,1,1]
	v_pk_mul_f32 v[2:3], v[90:91], v[8:9]
	v_pk_fma_f32 v[78:79], v[86:87], v[80:81], v[78:79]
	v_pk_fma_f32 v[2:3], v[18:19], v[32:33], v[2:3] op_sel_hi:[0,1,1]
	v_pk_fma_f32 v[90:91], v[94:95], v[16:17], v[2:3] op_sel_hi:[0,1,1]
	ds_read_b128 v[22:25], v96 offset:3136
	ds_read_b128 v[18:21], v96 offset:3152
	ds_read_b128 v[2:5], v96 offset:3392
	ds_read_b128 v[6:9], v96 offset:3408
	ds_read_b128 v[10:13], v96 offset:3648
	ds_read_b128 v[14:17], v96 offset:3664
	ds_read_b128 v[34:37], v96 offset:3904
	ds_read_b128 v[38:41], v96 offset:3920
	ds_read_b128 v[26:29], v96 offset:4160
	ds_read_b128 v[30:33], v96 offset:4176
	v_pk_fma_f32 v[70:71], v[86:87], v[72:73], v[70:71]
	s_waitcnt lgkmcnt(14)
	v_pk_fma_f32 v[72:73], v[88:89], v[74:75], v[78:79]
	v_pk_fma_f32 v[66:67], v[88:89], v[66:67], v[70:71]
	v_mov_b32_e32 v95, s7
	ds_read_b32 v94, v103 offset:4416
	ds_read_b64 v[96:97], v95 offset:4672
	v_pk_fma_f32 v[70:71], v[90:91], v[76:77], v[72:73]
	v_pk_fma_f32 v[68:69], v[90:91], v[68:69], v[66:67]
	v_add_f32_e32 v66, v70, v71
	v_add_f32_e32 v67, v68, v69
	s_nop 0
	v_add_f32_dpp v66, v66, v66 quad_perm:[1,0,3,2] row_mask:0xf bank_mask:0xf bound_ctrl:1
	v_add_f32_dpp v67, v67, v67 quad_perm:[1,0,3,2] row_mask:0xf bank_mask:0xf bound_ctrl:1
	s_nop 0
	v_add_f32_dpp v66, v66, v66 quad_perm:[2,3,0,1] row_mask:0xf bank_mask:0xf bound_ctrl:1
	v_add_f32_dpp v68, v67, v67 quad_perm:[2,3,0,1] row_mask:0xf bank_mask:0xf bound_ctrl:1
	s_nop 0
	v_add_f32_dpp v66, v66, v66 row_half_mirror row_mask:0xf bank_mask:0xf bound_ctrl:1
	s_waitcnt lgkmcnt(13)
	v_mov_b32_e32 v67, v0
	s_waitcnt lgkmcnt(12)
	v_pk_mul_f32 v[70:71], v[98:99], v[66:67]
	v_add_f32_dpp v67, v68, v68 row_half_mirror row_mask:0xf bank_mask:0xf bound_ctrl:1
	v_add_f32_e32 v67, v70, v67
	s_add_i32 s20, s2, s46
	v_add_f32_e32 v67, v71, v67
	s_ashr_i32 s21, s20, 31
	v_bfe_u32 v68, v67, 16, 1
	s_lshl_b64 s[20:21], s[20:21], 9
	v_add3_u32 v67, v67, v68, s28
	v_lshl_add_u64 v[68:69], v[92:93], 0, s[20:21]
	global_store_short_d16_hi v[68:69], v67, off
	v_pk_mul_f32 v[50:51], v[50:51], v[84:85]
	v_pk_mul_f32 v[46:47], v[46:47], v[88:89]
	s_waitcnt lgkmcnt(14)
	v_pk_fma_f32 v[50:51], v[66:67], v[62:63], v[50:51] op_sel_hi:[0,1,1]
	v_pk_fma_f32 v[46:47], v[66:67], v[58:59], v[46:47] op_sel_hi:[0,1,1]
	s_waitcnt lgkmcnt(13)
	v_pk_fma_f32 v[84:85], v[0:1], v[54:55], v[50:51] op_sel_hi:[0,1,1]
	v_pk_mul_f32 v[50:51], v[52:53], v[86:87]
	v_pk_fma_f32 v[88:89], v[0:1], v[42:43], v[46:47] op_sel_hi:[0,1,1]
	v_pk_mul_f32 v[42:43], v[48:49], v[90:91]
	v_pk_fma_f32 v[50:51], v[66:67], v[64:65], v[50:51] op_sel_hi:[0,1,1]
	v_pk_fma_f32 v[42:43], v[66:67], v[60:61], v[42:43] op_sel_hi:[0,1,1]
	s_add_i32 s46, s46, s3
	s_add_i32 s10, s10, 2
	s_addk_i32 s7, 0xc40
	v_pk_fma_f32 v[86:87], v[0:1], v[56:57], v[50:51] op_sel_hi:[0,1,1]
	v_pk_fma_f32 v[90:91], v[0:1], v[44:45], v[42:43] op_sel_hi:[0,1,1]
	s_waitcnt lgkmcnt(0)
	v_mov_b32_e32 v95, v96
	v_add_u32_e32 v96, s7, v100
	ds_read_b128 v[70:73], v96 offset:1568
	ds_read_b128 v[66:69], v96 offset:1584
	ds_read_b128 v[50:53], v96 offset:1824
	ds_read_b128 v[46:49], v96 offset:1840
	ds_read_b128 v[54:57], v96 offset:2080
	ds_read_b128 v[42:45], v96 offset:2096
	ds_read_b128 v[78:81], v96 offset:2336
	ds_read_b128 v[74:77], v96 offset:2352
	ds_read_b128 v[62:65], v96 offset:2592
	ds_read_b128 v[58:61], v96 offset:2608
	v_pk_fma_f32 v[34:35], v[84:85], v[34:35], 0 op_sel_hi:[1,1,0]
	v_pk_fma_f32 v[22:23], v[84:85], v[22:23], 0 op_sel_hi:[1,1,0]
	v_pk_fma_f32 v[34:35], v[86:87], v[36:37], v[34:35]
	v_pk_fma_f32 v[22:23], v[86:87], v[24:25], v[22:23]
	v_add_u32_e32 v103, s7, v102
	v_mov_b32_e32 v98, s7
	v_pk_fma_f32 v[24:25], v[88:89], v[38:39], v[34:35]
	v_pk_fma_f32 v[18:19], v[88:89], v[18:19], v[22:23]
	ds_read_b32 v0, v103 offset:2848
	ds_read_b64 v[98:99], v98 offset:3104
	v_pk_fma_f32 v[22:23], v[90:91], v[40:41], v[24:25]
	v_pk_fma_f32 v[20:21], v[90:91], v[20:21], v[18:19]
	v_add_f32_e32 v18, v22, v23
	v_add_f32_e32 v19, v20, v21
	s_nop 0
	v_add_f32_dpp v18, v18, v18 quad_perm:[1,0,3,2] row_mask:0xf bank_mask:0xf bound_ctrl:1
	v_add_f32_dpp v19, v19, v19 quad_perm:[1,0,3,2] row_mask:0xf bank_mask:0xf bound_ctrl:1
	s_nop 0
	v_add_f32_dpp v18, v18, v18 quad_perm:[2,3,0,1] row_mask:0xf bank_mask:0xf bound_ctrl:1
	v_add_f32_dpp v19, v19, v19 quad_perm:[2,3,0,1] row_mask:0xf bank_mask:0xf bound_ctrl:1
	s_nop 0
	v_add_f32_dpp v18, v18, v18 row_half_mirror row_mask:0xf bank_mask:0xf bound_ctrl:1
	v_mov_b32_e32 v22, v97
	v_mov_b32_e32 v23, v18
	v_pk_mul_f32 v[22:23], v[22:23], v[94:95]
	v_add_f32_dpp v19, v19, v19 row_half_mirror row_mask:0xf bank_mask:0xf bound_ctrl:1
	v_add_f32_e32 v19, v23, v19
	v_add_f32_e32 v19, v22, v19
	s_ashr_i32 s47, s46, 31
	v_bfe_u32 v20, v19, 16, 1
	s_lshl_b64 s[20:21], s[46:47], 9
	v_add3_u32 v19, v19, v20, s28
	v_lshl_add_u64 v[20:21], v[92:93], 0, s[20:21]
	global_store_short_d16_hi v[20:21], v19, off
	v_pk_mul_f32 v[2:3], v[84:85], v[2:3]
	s_nop 0
	v_pk_fma_f32 v[2:3], v[18:19], v[26:27], v[2:3] op_sel_hi:[0,1,1]
	v_pk_fma_f32 v[84:85], v[94:95], v[10:11], v[2:3] op_sel_hi:[0,1,1]
	v_pk_mul_f32 v[2:3], v[86:87], v[4:5]
	s_waitcnt lgkmcnt(5)
	v_pk_fma_f32 v[78:79], v[84:85], v[78:79], 0 op_sel_hi:[1,1,0]
	v_pk_fma_f32 v[2:3], v[18:19], v[28:29], v[2:3] op_sel_hi:[0,1,1]
	v_pk_fma_f32 v[86:87], v[94:95], v[12:13], v[2:3] op_sel_hi:[0,1,1]
	v_pk_mul_f32 v[2:3], v[88:89], v[6:7]
	v_pk_fma_f32 v[70:71], v[84:85], v[70:71], 0 op_sel_hi:[1,1,0]
	v_pk_fma_f32 v[2:3], v[18:19], v[30:31], v[2:3] op_sel_hi:[0,1,1]
	v_pk_fma_f32 v[88:89], v[94:95], v[14:15], v[2:3] op_sel_hi:[0,1,1]
	v_pk_mul_f32 v[2:3], v[90:91], v[8:9]
	v_pk_fma_f32 v[78:79], v[86:87], v[80:81], v[78:79]
	v_pk_fma_f32 v[2:3], v[18:19], v[32:33], v[2:3] op_sel_hi:[0,1,1]
	v_pk_fma_f32 v[90:91], v[94:95], v[16:17], v[2:3] op_sel_hi:[0,1,1]
	ds_read_b128 v[22:25], v96 offset:3136
	ds_read_b128 v[18:21], v96 offset:3152
	ds_read_b128 v[2:5], v96 offset:3392
	ds_read_b128 v[6:9], v96 offset:3408
	ds_read_b128 v[10:13], v96 offset:3648
	ds_read_b128 v[14:17], v96 offset:3664
	ds_read_b128 v[34:37], v96 offset:3904
	ds_read_b128 v[38:41], v96 offset:3920
	ds_read_b128 v[26:29], v96 offset:4160
	ds_read_b128 v[30:33], v96 offset:4176
	v_pk_fma_f32 v[70:71], v[86:87], v[72:73], v[70:71]
	s_waitcnt lgkmcnt(14)
	v_pk_fma_f32 v[72:73], v[88:89], v[74:75], v[78:79]
	v_pk_fma_f32 v[66:67], v[88:89], v[66:67], v[70:71]
	v_mov_b32_e32 v95, s7
	ds_read_b32 v94, v103 offset:4416
	ds_read_b64 v[96:97], v95 offset:4672
	v_pk_fma_f32 v[70:71], v[90:91], v[76:77], v[72:73]
	v_pk_fma_f32 v[68:69], v[90:91], v[68:69], v[66:67]
	v_add_f32_e32 v66, v70, v71
	v_add_f32_e32 v67, v68, v69
	s_nop 0
	v_add_f32_dpp v66, v66, v66 quad_perm:[1,0,3,2] row_mask:0xf bank_mask:0xf bound_ctrl:1
	v_add_f32_dpp v67, v67, v67 quad_perm:[1,0,3,2] row_mask:0xf bank_mask:0xf bound_ctrl:1
	s_nop 0
	v_add_f32_dpp v66, v66, v66 quad_perm:[2,3,0,1] row_mask:0xf bank_mask:0xf bound_ctrl:1
	v_add_f32_dpp v68, v67, v67 quad_perm:[2,3,0,1] row_mask:0xf bank_mask:0xf bound_ctrl:1
	s_nop 0
	v_add_f32_dpp v66, v66, v66 row_half_mirror row_mask:0xf bank_mask:0xf bound_ctrl:1
	s_waitcnt lgkmcnt(13)
	v_mov_b32_e32 v67, v0
	s_waitcnt lgkmcnt(12)
	v_pk_mul_f32 v[70:71], v[98:99], v[66:67]
	v_add_f32_dpp v67, v68, v68 row_half_mirror row_mask:0xf bank_mask:0xf bound_ctrl:1
	v_add_f32_e32 v67, v70, v67
	s_add_i32 s20, s2, s46
	v_add_f32_e32 v67, v71, v67
	s_ashr_i32 s21, s20, 31
	v_bfe_u32 v68, v67, 16, 1
	s_lshl_b64 s[20:21], s[20:21], 9
	v_add3_u32 v67, v67, v68, s28
	v_lshl_add_u64 v[68:69], v[92:93], 0, s[20:21]
	global_store_short_d16_hi v[68:69], v67, off
	v_pk_mul_f32 v[50:51], v[50:51], v[84:85]
	v_pk_mul_f32 v[46:47], v[46:47], v[88:89]
	s_waitcnt lgkmcnt(14)
	v_pk_fma_f32 v[50:51], v[66:67], v[62:63], v[50:51] op_sel_hi:[0,1,1]
	v_pk_fma_f32 v[46:47], v[66:67], v[58:59], v[46:47] op_sel_hi:[0,1,1]
	s_waitcnt lgkmcnt(13)
	v_pk_fma_f32 v[84:85], v[0:1], v[54:55], v[50:51] op_sel_hi:[0,1,1]
	v_pk_mul_f32 v[50:51], v[52:53], v[86:87]
	v_pk_fma_f32 v[88:89], v[0:1], v[42:43], v[46:47] op_sel_hi:[0,1,1]
	v_pk_mul_f32 v[42:43], v[48:49], v[90:91]
	v_pk_fma_f32 v[50:51], v[66:67], v[64:65], v[50:51] op_sel_hi:[0,1,1]
	v_pk_fma_f32 v[42:43], v[66:67], v[60:61], v[42:43] op_sel_hi:[0,1,1]
	s_add_i32 s46, s46, s3
	s_add_i32 s10, s10, 2
	s_addk_i32 s7, 0xc40
	v_pk_fma_f32 v[86:87], v[0:1], v[56:57], v[50:51] op_sel_hi:[0,1,1]
	s_cmp_gt_u32 s10, 13
	v_pk_fma_f32 v[90:91], v[0:1], v[44:45], v[42:43] op_sel_hi:[0,1,1]
	s_cbranch_scc0 .LBB0_859

.LBB0_869:
	s_waitcnt lgkmcnt(0)
	v_mov_b32_e32 v95, v96
	v_add_u32_e32 v96, s6, v100
	ds_read_b128 v[70:73], v96 offset:26656
	ds_read_b128 v[66:69], v96 offset:26672
	ds_read_b128 v[50:53], v96 offset:26912
	ds_read_b128 v[46:49], v96 offset:26928
	ds_read_b128 v[54:57], v96 offset:27168
	ds_read_b128 v[42:45], v96 offset:27184
	ds_read_b128 v[78:81], v96 offset:27424
	ds_read_b128 v[74:77], v96 offset:27440
	ds_read_b128 v[62:65], v96 offset:27680
	ds_read_b128 v[58:61], v96 offset:27696
	v_pk_fma_f32 v[34:35], v[84:85], v[34:35], 0 op_sel_hi:[1,1,0]
	v_pk_fma_f32 v[22:23], v[84:85], v[22:23], 0 op_sel_hi:[1,1,0]
	v_pk_fma_f32 v[34:35], v[86:87], v[36:37], v[34:35]
	v_pk_fma_f32 v[22:23], v[86:87], v[24:25], v[22:23]
	v_add_u32_e32 v103, s6, v102
	v_mov_b32_e32 v98, s6
	v_pk_fma_f32 v[24:25], v[88:89], v[38:39], v[34:35]
	v_pk_fma_f32 v[18:19], v[88:89], v[18:19], v[22:23]
	ds_read_b32 v0, v103 offset:27936
	ds_read_b64 v[98:99], v98 offset:28192
	v_pk_fma_f32 v[22:23], v[90:91], v[40:41], v[24:25]
	v_pk_fma_f32 v[20:21], v[90:91], v[20:21], v[18:19]
	v_add_f32_e32 v18, v22, v23
	v_add_f32_e32 v19, v20, v21
	s_nop 0
	v_add_f32_dpp v18, v18, v18 quad_perm:[1,0,3,2] row_mask:0xf bank_mask:0xf bound_ctrl:1
	v_add_f32_dpp v19, v19, v19 quad_perm:[1,0,3,2] row_mask:0xf bank_mask:0xf bound_ctrl:1
	s_nop 0
	v_add_f32_dpp v18, v18, v18 quad_perm:[2,3,0,1] row_mask:0xf bank_mask:0xf bound_ctrl:1
	v_add_f32_dpp v19, v19, v19 quad_perm:[2,3,0,1] row_mask:0xf bank_mask:0xf bound_ctrl:1
	s_nop 0
	v_add_f32_dpp v18, v18, v18 row_half_mirror row_mask:0xf bank_mask:0xf bound_ctrl:1
	v_mov_b32_e32 v22, v97
	v_mov_b32_e32 v23, v18
	v_pk_mul_f32 v[22:23], v[22:23], v[94:95]
	v_add_f32_dpp v19, v19, v19 row_half_mirror row_mask:0xf bank_mask:0xf bound_ctrl:1
	v_add_f32_e32 v19, v23, v19
	v_add_f32_e32 v19, v22, v19
	s_ashr_i32 s19, s18, 31
	v_bfe_u32 v20, v19, 16, 1
	s_lshl_b64 s[10:11], s[18:19], 9
	v_add3_u32 v19, v19, v20, s28
	v_lshl_add_u64 v[20:21], v[92:93], 0, s[10:11]
	global_store_short_d16_hi v[20:21], v19, off
	v_pk_mul_f32 v[2:3], v[84:85], v[2:3]
	s_nop 0
	v_pk_fma_f32 v[2:3], v[18:19], v[26:27], v[2:3] op_sel_hi:[0,1,1]
	v_pk_fma_f32 v[84:85], v[94:95], v[10:11], v[2:3] op_sel_hi:[0,1,1]
	v_pk_mul_f32 v[2:3], v[86:87], v[4:5]
	s_waitcnt lgkmcnt(5)
	v_pk_fma_f32 v[78:79], v[84:85], v[78:79], 0 op_sel_hi:[1,1,0]
	v_pk_fma_f32 v[2:3], v[18:19], v[28:29], v[2:3] op_sel_hi:[0,1,1]
	v_pk_fma_f32 v[86:87], v[94:95], v[12:13], v[2:3] op_sel_hi:[0,1,1]
	v_pk_mul_f32 v[2:3], v[88:89], v[6:7]
	v_pk_fma_f32 v[70:71], v[84:85], v[70:71], 0 op_sel_hi:[1,1,0]
	v_pk_fma_f32 v[2:3], v[18:19], v[30:31], v[2:3] op_sel_hi:[0,1,1]
	v_pk_fma_f32 v[88:89], v[94:95], v[14:15], v[2:3] op_sel_hi:[0,1,1]
	v_pk_mul_f32 v[2:3], v[90:91], v[8:9]
	v_pk_fma_f32 v[78:79], v[86:87], v[80:81], v[78:79]
	v_pk_fma_f32 v[2:3], v[18:19], v[32:33], v[2:3] op_sel_hi:[0,1,1]
	v_pk_fma_f32 v[90:91], v[94:95], v[16:17], v[2:3] op_sel_hi:[0,1,1]
	ds_read_b128 v[22:25], v96 offset:28224
	ds_read_b128 v[18:21], v96 offset:28240
	ds_read_b128 v[2:5], v96 offset:28480
	ds_read_b128 v[6:9], v96 offset:28496
	ds_read_b128 v[10:13], v96 offset:28736
	ds_read_b128 v[14:17], v96 offset:28752
	ds_read_b128 v[34:37], v96 offset:28992
	ds_read_b128 v[38:41], v96 offset:29008
	ds_read_b128 v[26:29], v96 offset:29248
	ds_read_b128 v[30:33], v96 offset:29264
	v_pk_fma_f32 v[70:71], v[86:87], v[72:73], v[70:71]
	s_waitcnt lgkmcnt(14)
	v_pk_fma_f32 v[72:73], v[88:89], v[74:75], v[78:79]
	v_pk_fma_f32 v[66:67], v[88:89], v[66:67], v[70:71]
	v_mov_b32_e32 v95, s6
	ds_read_b32 v94, v103 offset:29504
	ds_read_b64 v[96:97], v95 offset:29760
	v_pk_fma_f32 v[70:71], v[90:91], v[76:77], v[72:73]
	v_pk_fma_f32 v[68:69], v[90:91], v[68:69], v[66:67]
	v_add_f32_e32 v66, v70, v71
	v_add_f32_e32 v67, v68, v69
	s_nop 0
	v_add_f32_dpp v66, v66, v66 quad_perm:[1,0,3,2] row_mask:0xf bank_mask:0xf bound_ctrl:1
	v_add_f32_dpp v67, v67, v67 quad_perm:[1,0,3,2] row_mask:0xf bank_mask:0xf bound_ctrl:1
	s_nop 0
	v_add_f32_dpp v66, v66, v66 quad_perm:[2,3,0,1] row_mask:0xf bank_mask:0xf bound_ctrl:1
	v_add_f32_dpp v68, v67, v67 quad_perm:[2,3,0,1] row_mask:0xf bank_mask:0xf bound_ctrl:1
	s_nop 0
	v_add_f32_dpp v66, v66, v66 row_half_mirror row_mask:0xf bank_mask:0xf bound_ctrl:1
	s_waitcnt lgkmcnt(13)
	v_mov_b32_e32 v67, v0
	s_waitcnt lgkmcnt(12)
	v_pk_mul_f32 v[70:71], v[98:99], v[66:67]
	v_add_f32_dpp v67, v68, v68 row_half_mirror row_mask:0xf bank_mask:0xf bound_ctrl:1
	v_add_f32_e32 v67, v70, v67
	s_add_i32 s10, s2, s18
	v_add_f32_e32 v67, v71, v67
	s_ashr_i32 s11, s10, 31
	v_bfe_u32 v68, v67, 16, 1
	s_lshl_b64 s[10:11], s[10:11], 9
	v_add3_u32 v67, v67, v68, s28
	v_lshl_add_u64 v[68:69], v[92:93], 0, s[10:11]
	global_store_short_d16_hi v[68:69], v67, off
	v_pk_mul_f32 v[50:51], v[50:51], v[84:85]
	v_pk_mul_f32 v[46:47], v[46:47], v[88:89]
	s_waitcnt lgkmcnt(14)
	v_pk_fma_f32 v[50:51], v[66:67], v[62:63], v[50:51] op_sel_hi:[0,1,1]
	v_pk_fma_f32 v[46:47], v[66:67], v[58:59], v[46:47] op_sel_hi:[0,1,1]
	s_waitcnt lgkmcnt(13)
	v_pk_fma_f32 v[84:85], v[0:1], v[54:55], v[50:51] op_sel_hi:[0,1,1]
	v_pk_mul_f32 v[50:51], v[52:53], v[86:87]
	v_pk_fma_f32 v[88:89], v[0:1], v[42:43], v[46:47] op_sel_hi:[0,1,1]
	v_pk_mul_f32 v[42:43], v[48:49], v[90:91]
	v_pk_fma_f32 v[50:51], v[66:67], v[64:65], v[50:51] op_sel_hi:[0,1,1]
	v_pk_fma_f32 v[42:43], v[66:67], v[60:61], v[42:43] op_sel_hi:[0,1,1]
	s_add_i32 s18, s18, s3
	s_add_i32 s7, s7, 2
	s_addk_i32 s6, 0xc40
	v_pk_fma_f32 v[86:87], v[0:1], v[56:57], v[50:51] op_sel_hi:[0,1,1]
	v_pk_fma_f32 v[90:91], v[0:1], v[44:45], v[42:43] op_sel_hi:[0,1,1]
	s_waitcnt lgkmcnt(0)
	v_mov_b32_e32 v95, v96
	v_add_u32_e32 v96, s6, v100
	ds_read_b128 v[70:73], v96 offset:26656
	ds_read_b128 v[66:69], v96 offset:26672
	ds_read_b128 v[50:53], v96 offset:26912
	ds_read_b128 v[46:49], v96 offset:26928
	ds_read_b128 v[54:57], v96 offset:27168
	ds_read_b128 v[42:45], v96 offset:27184
	ds_read_b128 v[78:81], v96 offset:27424
	ds_read_b128 v[74:77], v96 offset:27440
	ds_read_b128 v[62:65], v96 offset:27680
	ds_read_b128 v[58:61], v96 offset:27696
	v_pk_fma_f32 v[34:35], v[84:85], v[34:35], 0 op_sel_hi:[1,1,0]
	v_pk_fma_f32 v[22:23], v[84:85], v[22:23], 0 op_sel_hi:[1,1,0]
	v_pk_fma_f32 v[34:35], v[86:87], v[36:37], v[34:35]
	v_pk_fma_f32 v[22:23], v[86:87], v[24:25], v[22:23]
	v_add_u32_e32 v103, s6, v102
	v_mov_b32_e32 v98, s6
	v_pk_fma_f32 v[24:25], v[88:89], v[38:39], v[34:35]
	v_pk_fma_f32 v[18:19], v[88:89], v[18:19], v[22:23]
	ds_read_b32 v0, v103 offset:27936
	ds_read_b64 v[98:99], v98 offset:28192
	v_pk_fma_f32 v[22:23], v[90:91], v[40:41], v[24:25]
	v_pk_fma_f32 v[20:21], v[90:91], v[20:21], v[18:19]
	v_add_f32_e32 v18, v22, v23
	v_add_f32_e32 v19, v20, v21
	s_nop 0
	v_add_f32_dpp v18, v18, v18 quad_perm:[1,0,3,2] row_mask:0xf bank_mask:0xf bound_ctrl:1
	v_add_f32_dpp v19, v19, v19 quad_perm:[1,0,3,2] row_mask:0xf bank_mask:0xf bound_ctrl:1
	s_nop 0
	v_add_f32_dpp v18, v18, v18 quad_perm:[2,3,0,1] row_mask:0xf bank_mask:0xf bound_ctrl:1
	v_add_f32_dpp v19, v19, v19 quad_perm:[2,3,0,1] row_mask:0xf bank_mask:0xf bound_ctrl:1
	s_nop 0
	v_add_f32_dpp v18, v18, v18 row_half_mirror row_mask:0xf bank_mask:0xf bound_ctrl:1
	v_mov_b32_e32 v22, v97
	v_mov_b32_e32 v23, v18
	v_pk_mul_f32 v[22:23], v[22:23], v[94:95]
	v_add_f32_dpp v19, v19, v19 row_half_mirror row_mask:0xf bank_mask:0xf bound_ctrl:1
	v_add_f32_e32 v19, v23, v19
	v_add_f32_e32 v19, v22, v19
	s_ashr_i32 s19, s18, 31
	v_bfe_u32 v20, v19, 16, 1
	s_lshl_b64 s[10:11], s[18:19], 9
	v_add3_u32 v19, v19, v20, s28
	v_lshl_add_u64 v[20:21], v[92:93], 0, s[10:11]
	global_store_short_d16_hi v[20:21], v19, off
	v_pk_mul_f32 v[2:3], v[84:85], v[2:3]
	s_nop 0
	v_pk_fma_f32 v[2:3], v[18:19], v[26:27], v[2:3] op_sel_hi:[0,1,1]
	v_pk_fma_f32 v[84:85], v[94:95], v[10:11], v[2:3] op_sel_hi:[0,1,1]
	v_pk_mul_f32 v[2:3], v[86:87], v[4:5]
	s_waitcnt lgkmcnt(5)
	v_pk_fma_f32 v[78:79], v[84:85], v[78:79], 0 op_sel_hi:[1,1,0]
	v_pk_fma_f32 v[2:3], v[18:19], v[28:29], v[2:3] op_sel_hi:[0,1,1]
	v_pk_fma_f32 v[86:87], v[94:95], v[12:13], v[2:3] op_sel_hi:[0,1,1]
	v_pk_mul_f32 v[2:3], v[88:89], v[6:7]
	v_pk_fma_f32 v[70:71], v[84:85], v[70:71], 0 op_sel_hi:[1,1,0]
	v_pk_fma_f32 v[2:3], v[18:19], v[30:31], v[2:3] op_sel_hi:[0,1,1]
	v_pk_fma_f32 v[88:89], v[94:95], v[14:15], v[2:3] op_sel_hi:[0,1,1]
	v_pk_mul_f32 v[2:3], v[90:91], v[8:9]
	v_pk_fma_f32 v[78:79], v[86:87], v[80:81], v[78:79]
	v_pk_fma_f32 v[2:3], v[18:19], v[32:33], v[2:3] op_sel_hi:[0,1,1]
	v_pk_fma_f32 v[90:91], v[94:95], v[16:17], v[2:3] op_sel_hi:[0,1,1]
	ds_read_b128 v[22:25], v96 offset:28224
	ds_read_b128 v[18:21], v96 offset:28240
	ds_read_b128 v[2:5], v96 offset:28480
	ds_read_b128 v[6:9], v96 offset:28496
	ds_read_b128 v[10:13], v96 offset:28736
	ds_read_b128 v[14:17], v96 offset:28752
	ds_read_b128 v[34:37], v96 offset:28992
	ds_read_b128 v[38:41], v96 offset:29008
	ds_read_b128 v[26:29], v96 offset:29248
	ds_read_b128 v[30:33], v96 offset:29264
	v_pk_fma_f32 v[70:71], v[86:87], v[72:73], v[70:71]
	s_waitcnt lgkmcnt(14)
	v_pk_fma_f32 v[72:73], v[88:89], v[74:75], v[78:79]
	v_pk_fma_f32 v[66:67], v[88:89], v[66:67], v[70:71]
	v_mov_b32_e32 v95, s6
	ds_read_b32 v94, v103 offset:29504
	ds_read_b64 v[96:97], v95 offset:29760
	v_pk_fma_f32 v[70:71], v[90:91], v[76:77], v[72:73]
	v_pk_fma_f32 v[68:69], v[90:91], v[68:69], v[66:67]
	v_add_f32_e32 v66, v70, v71
	v_add_f32_e32 v67, v68, v69
	s_nop 0
	v_add_f32_dpp v66, v66, v66 quad_perm:[1,0,3,2] row_mask:0xf bank_mask:0xf bound_ctrl:1
	v_add_f32_dpp v67, v67, v67 quad_perm:[1,0,3,2] row_mask:0xf bank_mask:0xf bound_ctrl:1
	s_nop 0
	v_add_f32_dpp v66, v66, v66 quad_perm:[2,3,0,1] row_mask:0xf bank_mask:0xf bound_ctrl:1
	v_add_f32_dpp v68, v67, v67 quad_perm:[2,3,0,1] row_mask:0xf bank_mask:0xf bound_ctrl:1
	s_nop 0
	v_add_f32_dpp v66, v66, v66 row_half_mirror row_mask:0xf bank_mask:0xf bound_ctrl:1
	s_waitcnt lgkmcnt(13)
	v_mov_b32_e32 v67, v0
	s_waitcnt lgkmcnt(12)
	v_pk_mul_f32 v[70:71], v[98:99], v[66:67]
	v_add_f32_dpp v67, v68, v68 row_half_mirror row_mask:0xf bank_mask:0xf bound_ctrl:1
	v_add_f32_e32 v67, v70, v67
	s_add_i32 s10, s2, s18
	v_add_f32_e32 v67, v71, v67
	s_ashr_i32 s11, s10, 31
	v_bfe_u32 v68, v67, 16, 1
	s_lshl_b64 s[10:11], s[10:11], 9
	v_add3_u32 v67, v67, v68, s28
	v_lshl_add_u64 v[68:69], v[92:93], 0, s[10:11]
	global_store_short_d16_hi v[68:69], v67, off
	v_pk_mul_f32 v[50:51], v[50:51], v[84:85]
	v_pk_mul_f32 v[46:47], v[46:47], v[88:89]
	s_waitcnt lgkmcnt(14)
	v_pk_fma_f32 v[50:51], v[66:67], v[62:63], v[50:51] op_sel_hi:[0,1,1]
	v_pk_fma_f32 v[46:47], v[66:67], v[58:59], v[46:47] op_sel_hi:[0,1,1]
	s_waitcnt lgkmcnt(13)
	v_pk_fma_f32 v[84:85], v[0:1], v[54:55], v[50:51] op_sel_hi:[0,1,1]
	v_pk_mul_f32 v[50:51], v[52:53], v[86:87]
	v_pk_fma_f32 v[88:89], v[0:1], v[42:43], v[46:47] op_sel_hi:[0,1,1]
	v_pk_mul_f32 v[42:43], v[48:49], v[90:91]
	v_pk_fma_f32 v[50:51], v[66:67], v[64:65], v[50:51] op_sel_hi:[0,1,1]
	v_pk_fma_f32 v[42:43], v[66:67], v[60:61], v[42:43] op_sel_hi:[0,1,1]
	s_add_i32 s18, s18, s3
	s_add_i32 s7, s7, 2
	s_addk_i32 s6, 0xc40
	v_pk_fma_f32 v[86:87], v[0:1], v[56:57], v[50:51] op_sel_hi:[0,1,1]
	v_pk_fma_f32 v[90:91], v[0:1], v[44:45], v[42:43] op_sel_hi:[0,1,1]
	s_waitcnt lgkmcnt(0)
	v_mov_b32_e32 v95, v96
	v_add_u32_e32 v96, s6, v100
	ds_read_b128 v[70:73], v96 offset:26656
	ds_read_b128 v[66:69], v96 offset:26672
	ds_read_b128 v[50:53], v96 offset:26912
	ds_read_b128 v[46:49], v96 offset:26928
	ds_read_b128 v[54:57], v96 offset:27168
	ds_read_b128 v[42:45], v96 offset:27184
	ds_read_b128 v[78:81], v96 offset:27424
	ds_read_b128 v[74:77], v96 offset:27440
	ds_read_b128 v[62:65], v96 offset:27680
	ds_read_b128 v[58:61], v96 offset:27696
	v_pk_fma_f32 v[34:35], v[84:85], v[34:35], 0 op_sel_hi:[1,1,0]
	v_pk_fma_f32 v[22:23], v[84:85], v[22:23], 0 op_sel_hi:[1,1,0]
	v_pk_fma_f32 v[34:35], v[86:87], v[36:37], v[34:35]
	v_pk_fma_f32 v[22:23], v[86:87], v[24:25], v[22:23]
	v_add_u32_e32 v103, s6, v102
	v_mov_b32_e32 v98, s6
	v_pk_fma_f32 v[24:25], v[88:89], v[38:39], v[34:35]
	v_pk_fma_f32 v[18:19], v[88:89], v[18:19], v[22:23]
	ds_read_b32 v0, v103 offset:27936
	ds_read_b64 v[98:99], v98 offset:28192
	v_pk_fma_f32 v[22:23], v[90:91], v[40:41], v[24:25]
	v_pk_fma_f32 v[20:21], v[90:91], v[20:21], v[18:19]
	v_add_f32_e32 v18, v22, v23
	v_add_f32_e32 v19, v20, v21
	s_nop 0
	v_add_f32_dpp v18, v18, v18 quad_perm:[1,0,3,2] row_mask:0xf bank_mask:0xf bound_ctrl:1
	v_add_f32_dpp v19, v19, v19 quad_perm:[1,0,3,2] row_mask:0xf bank_mask:0xf bound_ctrl:1
	s_nop 0
	v_add_f32_dpp v18, v18, v18 quad_perm:[2,3,0,1] row_mask:0xf bank_mask:0xf bound_ctrl:1
	v_add_f32_dpp v19, v19, v19 quad_perm:[2,3,0,1] row_mask:0xf bank_mask:0xf bound_ctrl:1
	s_nop 0
	v_add_f32_dpp v18, v18, v18 row_half_mirror row_mask:0xf bank_mask:0xf bound_ctrl:1
	v_mov_b32_e32 v22, v97
	v_mov_b32_e32 v23, v18
	v_pk_mul_f32 v[22:23], v[22:23], v[94:95]
	v_add_f32_dpp v19, v19, v19 row_half_mirror row_mask:0xf bank_mask:0xf bound_ctrl:1
	v_add_f32_e32 v19, v23, v19
	v_add_f32_e32 v19, v22, v19
	s_ashr_i32 s19, s18, 31
	v_bfe_u32 v20, v19, 16, 1
	s_lshl_b64 s[10:11], s[18:19], 9
	v_add3_u32 v19, v19, v20, s28
	v_lshl_add_u64 v[20:21], v[92:93], 0, s[10:11]
	global_store_short_d16_hi v[20:21], v19, off
	v_pk_mul_f32 v[2:3], v[84:85], v[2:3]
	s_nop 0
	v_pk_fma_f32 v[2:3], v[18:19], v[26:27], v[2:3] op_sel_hi:[0,1,1]
	v_pk_fma_f32 v[84:85], v[94:95], v[10:11], v[2:3] op_sel_hi:[0,1,1]
	v_pk_mul_f32 v[2:3], v[86:87], v[4:5]
	s_waitcnt lgkmcnt(5)
	v_pk_fma_f32 v[78:79], v[84:85], v[78:79], 0 op_sel_hi:[1,1,0]
	v_pk_fma_f32 v[2:3], v[18:19], v[28:29], v[2:3] op_sel_hi:[0,1,1]
	v_pk_fma_f32 v[86:87], v[94:95], v[12:13], v[2:3] op_sel_hi:[0,1,1]
	v_pk_mul_f32 v[2:3], v[88:89], v[6:7]
	v_pk_fma_f32 v[70:71], v[84:85], v[70:71], 0 op_sel_hi:[1,1,0]
	v_pk_fma_f32 v[2:3], v[18:19], v[30:31], v[2:3] op_sel_hi:[0,1,1]
	v_pk_fma_f32 v[88:89], v[94:95], v[14:15], v[2:3] op_sel_hi:[0,1,1]
	v_pk_mul_f32 v[2:3], v[90:91], v[8:9]
	v_pk_fma_f32 v[78:79], v[86:87], v[80:81], v[78:79]
	v_pk_fma_f32 v[2:3], v[18:19], v[32:33], v[2:3] op_sel_hi:[0,1,1]
	v_pk_fma_f32 v[90:91], v[94:95], v[16:17], v[2:3] op_sel_hi:[0,1,1]
	ds_read_b128 v[22:25], v96 offset:28224
	ds_read_b128 v[18:21], v96 offset:28240
	ds_read_b128 v[2:5], v96 offset:28480
	ds_read_b128 v[6:9], v96 offset:28496
	ds_read_b128 v[10:13], v96 offset:28736
	ds_read_b128 v[14:17], v96 offset:28752
	ds_read_b128 v[34:37], v96 offset:28992
	ds_read_b128 v[38:41], v96 offset:29008
	ds_read_b128 v[26:29], v96 offset:29248
	ds_read_b128 v[30:33], v96 offset:29264
	v_pk_fma_f32 v[70:71], v[86:87], v[72:73], v[70:71]
	s_waitcnt lgkmcnt(14)
	v_pk_fma_f32 v[72:73], v[88:89], v[74:75], v[78:79]
	v_pk_fma_f32 v[66:67], v[88:89], v[66:67], v[70:71]
	v_mov_b32_e32 v95, s6
	ds_read_b32 v94, v103 offset:29504
	ds_read_b64 v[96:97], v95 offset:29760
	v_pk_fma_f32 v[70:71], v[90:91], v[76:77], v[72:73]
	v_pk_fma_f32 v[68:69], v[90:91], v[68:69], v[66:67]
	v_add_f32_e32 v66, v70, v71
	v_add_f32_e32 v67, v68, v69
	s_nop 0
	v_add_f32_dpp v66, v66, v66 quad_perm:[1,0,3,2] row_mask:0xf bank_mask:0xf bound_ctrl:1
	v_add_f32_dpp v67, v67, v67 quad_perm:[1,0,3,2] row_mask:0xf bank_mask:0xf bound_ctrl:1
	s_nop 0
	v_add_f32_dpp v66, v66, v66 quad_perm:[2,3,0,1] row_mask:0xf bank_mask:0xf bound_ctrl:1
	v_add_f32_dpp v68, v67, v67 quad_perm:[2,3,0,1] row_mask:0xf bank_mask:0xf bound_ctrl:1
	s_nop 0
	v_add_f32_dpp v66, v66, v66 row_half_mirror row_mask:0xf bank_mask:0xf bound_ctrl:1
	s_waitcnt lgkmcnt(13)
	v_mov_b32_e32 v67, v0
	s_waitcnt lgkmcnt(12)
	v_pk_mul_f32 v[70:71], v[98:99], v[66:67]
	v_add_f32_dpp v67, v68, v68 row_half_mirror row_mask:0xf bank_mask:0xf bound_ctrl:1
	v_add_f32_e32 v67, v70, v67
	s_add_i32 s10, s2, s18
	v_add_f32_e32 v67, v71, v67
	s_ashr_i32 s11, s10, 31
	v_bfe_u32 v68, v67, 16, 1
	s_lshl_b64 s[10:11], s[10:11], 9
	v_add3_u32 v67, v67, v68, s28
	v_lshl_add_u64 v[68:69], v[92:93], 0, s[10:11]
	global_store_short_d16_hi v[68:69], v67, off
	v_pk_mul_f32 v[50:51], v[50:51], v[84:85]
	v_pk_mul_f32 v[46:47], v[46:47], v[88:89]
	s_waitcnt lgkmcnt(14)
	v_pk_fma_f32 v[50:51], v[66:67], v[62:63], v[50:51] op_sel_hi:[0,1,1]
	v_pk_fma_f32 v[46:47], v[66:67], v[58:59], v[46:47] op_sel_hi:[0,1,1]
	s_waitcnt lgkmcnt(13)
	v_pk_fma_f32 v[84:85], v[0:1], v[54:55], v[50:51] op_sel_hi:[0,1,1]
	v_pk_mul_f32 v[50:51], v[52:53], v[86:87]
	v_pk_fma_f32 v[88:89], v[0:1], v[42:43], v[46:47] op_sel_hi:[0,1,1]
	v_pk_mul_f32 v[42:43], v[48:49], v[90:91]
	v_pk_fma_f32 v[50:51], v[66:67], v[64:65], v[50:51] op_sel_hi:[0,1,1]
	v_pk_fma_f32 v[42:43], v[66:67], v[60:61], v[42:43] op_sel_hi:[0,1,1]
	s_add_i32 s18, s18, s3
	s_add_i32 s7, s7, 2
	s_addk_i32 s6, 0xc40
	v_pk_fma_f32 v[86:87], v[0:1], v[56:57], v[50:51] op_sel_hi:[0,1,1]
	v_pk_fma_f32 v[90:91], v[0:1], v[44:45], v[42:43] op_sel_hi:[0,1,1]
	s_waitcnt lgkmcnt(0)
	v_mov_b32_e32 v95, v96
	v_add_u32_e32 v96, s6, v100
	ds_read_b128 v[70:73], v96 offset:26656
	ds_read_b128 v[66:69], v96 offset:26672
	ds_read_b128 v[50:53], v96 offset:26912
	ds_read_b128 v[46:49], v96 offset:26928
	ds_read_b128 v[54:57], v96 offset:27168
	ds_read_b128 v[42:45], v96 offset:27184
	ds_read_b128 v[78:81], v96 offset:27424
	ds_read_b128 v[74:77], v96 offset:27440
	ds_read_b128 v[62:65], v96 offset:27680
	ds_read_b128 v[58:61], v96 offset:27696
	v_pk_fma_f32 v[34:35], v[84:85], v[34:35], 0 op_sel_hi:[1,1,0]
	v_pk_fma_f32 v[22:23], v[84:85], v[22:23], 0 op_sel_hi:[1,1,0]
	v_pk_fma_f32 v[34:35], v[86:87], v[36:37], v[34:35]
	v_pk_fma_f32 v[22:23], v[86:87], v[24:25], v[22:23]
	v_add_u32_e32 v103, s6, v102
	v_mov_b32_e32 v98, s6
	v_pk_fma_f32 v[24:25], v[88:89], v[38:39], v[34:35]
	v_pk_fma_f32 v[18:19], v[88:89], v[18:19], v[22:23]
	ds_read_b32 v0, v103 offset:27936
	ds_read_b64 v[98:99], v98 offset:28192
	v_pk_fma_f32 v[22:23], v[90:91], v[40:41], v[24:25]
	v_pk_fma_f32 v[20:21], v[90:91], v[20:21], v[18:19]
	v_add_f32_e32 v18, v22, v23
	v_add_f32_e32 v19, v20, v21
	s_nop 0
	v_add_f32_dpp v18, v18, v18 quad_perm:[1,0,3,2] row_mask:0xf bank_mask:0xf bound_ctrl:1
	v_add_f32_dpp v19, v19, v19 quad_perm:[1,0,3,2] row_mask:0xf bank_mask:0xf bound_ctrl:1
	s_nop 0
	v_add_f32_dpp v18, v18, v18 quad_perm:[2,3,0,1] row_mask:0xf bank_mask:0xf bound_ctrl:1
	v_add_f32_dpp v19, v19, v19 quad_perm:[2,3,0,1] row_mask:0xf bank_mask:0xf bound_ctrl:1
	s_nop 0
	v_add_f32_dpp v18, v18, v18 row_half_mirror row_mask:0xf bank_mask:0xf bound_ctrl:1
	v_mov_b32_e32 v22, v97
	v_mov_b32_e32 v23, v18
	v_pk_mul_f32 v[22:23], v[22:23], v[94:95]
	v_add_f32_dpp v19, v19, v19 row_half_mirror row_mask:0xf bank_mask:0xf bound_ctrl:1
	v_add_f32_e32 v19, v23, v19
	v_add_f32_e32 v19, v22, v19
	s_ashr_i32 s19, s18, 31
	v_bfe_u32 v20, v19, 16, 1
	s_lshl_b64 s[10:11], s[18:19], 9
	v_add3_u32 v19, v19, v20, s28
	v_lshl_add_u64 v[20:21], v[92:93], 0, s[10:11]
	global_store_short_d16_hi v[20:21], v19, off
	v_pk_mul_f32 v[2:3], v[84:85], v[2:3]
	s_nop 0
	v_pk_fma_f32 v[2:3], v[18:19], v[26:27], v[2:3] op_sel_hi:[0,1,1]
	v_pk_fma_f32 v[84:85], v[94:95], v[10:11], v[2:3] op_sel_hi:[0,1,1]
	v_pk_mul_f32 v[2:3], v[86:87], v[4:5]
	s_waitcnt lgkmcnt(5)
	v_pk_fma_f32 v[78:79], v[84:85], v[78:79], 0 op_sel_hi:[1,1,0]
	v_pk_fma_f32 v[2:3], v[18:19], v[28:29], v[2:3] op_sel_hi:[0,1,1]
	v_pk_fma_f32 v[86:87], v[94:95], v[12:13], v[2:3] op_sel_hi:[0,1,1]
	v_pk_mul_f32 v[2:3], v[88:89], v[6:7]
	v_pk_fma_f32 v[70:71], v[84:85], v[70:71], 0 op_sel_hi:[1,1,0]
	v_pk_fma_f32 v[2:3], v[18:19], v[30:31], v[2:3] op_sel_hi:[0,1,1]
	v_pk_fma_f32 v[88:89], v[94:95], v[14:15], v[2:3] op_sel_hi:[0,1,1]
	v_pk_mul_f32 v[2:3], v[90:91], v[8:9]
	v_pk_fma_f32 v[78:79], v[86:87], v[80:81], v[78:79]
	v_pk_fma_f32 v[2:3], v[18:19], v[32:33], v[2:3] op_sel_hi:[0,1,1]
	v_pk_fma_f32 v[90:91], v[94:95], v[16:17], v[2:3] op_sel_hi:[0,1,1]
	ds_read_b128 v[22:25], v96 offset:28224
	ds_read_b128 v[18:21], v96 offset:28240
	ds_read_b128 v[2:5], v96 offset:28480
	ds_read_b128 v[6:9], v96 offset:28496
	ds_read_b128 v[10:13], v96 offset:28736
	ds_read_b128 v[14:17], v96 offset:28752
	ds_read_b128 v[34:37], v96 offset:28992
	ds_read_b128 v[38:41], v96 offset:29008
	ds_read_b128 v[26:29], v96 offset:29248
	ds_read_b128 v[30:33], v96 offset:29264
	v_pk_fma_f32 v[70:71], v[86:87], v[72:73], v[70:71]
	s_waitcnt lgkmcnt(14)
	v_pk_fma_f32 v[72:73], v[88:89], v[74:75], v[78:79]
	v_pk_fma_f32 v[66:67], v[88:89], v[66:67], v[70:71]
	v_mov_b32_e32 v95, s6
	ds_read_b32 v94, v103 offset:29504
	ds_read_b64 v[96:97], v95 offset:29760
	v_pk_fma_f32 v[70:71], v[90:91], v[76:77], v[72:73]
	v_pk_fma_f32 v[68:69], v[90:91], v[68:69], v[66:67]
	v_add_f32_e32 v66, v70, v71
	v_add_f32_e32 v67, v68, v69
	s_nop 0
	v_add_f32_dpp v66, v66, v66 quad_perm:[1,0,3,2] row_mask:0xf bank_mask:0xf bound_ctrl:1
	v_add_f32_dpp v67, v67, v67 quad_perm:[1,0,3,2] row_mask:0xf bank_mask:0xf bound_ctrl:1
	s_nop 0
	v_add_f32_dpp v66, v66, v66 quad_perm:[2,3,0,1] row_mask:0xf bank_mask:0xf bound_ctrl:1
	v_add_f32_dpp v68, v67, v67 quad_perm:[2,3,0,1] row_mask:0xf bank_mask:0xf bound_ctrl:1
	s_nop 0
	v_add_f32_dpp v66, v66, v66 row_half_mirror row_mask:0xf bank_mask:0xf bound_ctrl:1
	s_waitcnt lgkmcnt(13)
	v_mov_b32_e32 v67, v0
	s_waitcnt lgkmcnt(12)
	v_pk_mul_f32 v[70:71], v[98:99], v[66:67]
	v_add_f32_dpp v67, v68, v68 row_half_mirror row_mask:0xf bank_mask:0xf bound_ctrl:1
	v_add_f32_e32 v67, v70, v67
	s_add_i32 s10, s2, s18
	v_add_f32_e32 v67, v71, v67
	s_ashr_i32 s11, s10, 31
	v_bfe_u32 v68, v67, 16, 1
	s_lshl_b64 s[10:11], s[10:11], 9
	v_add3_u32 v67, v67, v68, s28
	v_lshl_add_u64 v[68:69], v[92:93], 0, s[10:11]
	global_store_short_d16_hi v[68:69], v67, off
	v_pk_mul_f32 v[50:51], v[50:51], v[84:85]
	v_pk_mul_f32 v[46:47], v[46:47], v[88:89]
	s_waitcnt lgkmcnt(14)
	v_pk_fma_f32 v[50:51], v[66:67], v[62:63], v[50:51] op_sel_hi:[0,1,1]
	v_pk_fma_f32 v[46:47], v[66:67], v[58:59], v[46:47] op_sel_hi:[0,1,1]
	s_waitcnt lgkmcnt(13)
	v_pk_fma_f32 v[84:85], v[0:1], v[54:55], v[50:51] op_sel_hi:[0,1,1]
	v_pk_mul_f32 v[50:51], v[52:53], v[86:87]
	v_pk_fma_f32 v[88:89], v[0:1], v[42:43], v[46:47] op_sel_hi:[0,1,1]
	v_pk_mul_f32 v[42:43], v[48:49], v[90:91]
	v_pk_fma_f32 v[50:51], v[66:67], v[64:65], v[50:51] op_sel_hi:[0,1,1]
	v_pk_fma_f32 v[42:43], v[66:67], v[60:61], v[42:43] op_sel_hi:[0,1,1]
	s_add_i32 s18, s18, s3
	s_add_i32 s7, s7, 2
	s_addk_i32 s6, 0xc40
	v_pk_fma_f32 v[86:87], v[0:1], v[56:57], v[50:51] op_sel_hi:[0,1,1]
	v_pk_fma_f32 v[90:91], v[0:1], v[44:45], v[42:43] op_sel_hi:[0,1,1]
	s_waitcnt lgkmcnt(0)
	v_mov_b32_e32 v95, v96
	v_add_u32_e32 v96, s6, v100
	ds_read_b128 v[70:73], v96 offset:26656
	ds_read_b128 v[66:69], v96 offset:26672
	ds_read_b128 v[50:53], v96 offset:26912
	ds_read_b128 v[46:49], v96 offset:26928
	ds_read_b128 v[54:57], v96 offset:27168
	ds_read_b128 v[42:45], v96 offset:27184
	ds_read_b128 v[78:81], v96 offset:27424
	ds_read_b128 v[74:77], v96 offset:27440
	ds_read_b128 v[62:65], v96 offset:27680
	ds_read_b128 v[58:61], v96 offset:27696
	v_pk_fma_f32 v[34:35], v[84:85], v[34:35], 0 op_sel_hi:[1,1,0]
	v_pk_fma_f32 v[22:23], v[84:85], v[22:23], 0 op_sel_hi:[1,1,0]
	v_pk_fma_f32 v[34:35], v[86:87], v[36:37], v[34:35]
	v_pk_fma_f32 v[22:23], v[86:87], v[24:25], v[22:23]
	v_add_u32_e32 v103, s6, v102
	v_mov_b32_e32 v98, s6
	v_pk_fma_f32 v[24:25], v[88:89], v[38:39], v[34:35]
	v_pk_fma_f32 v[18:19], v[88:89], v[18:19], v[22:23]
	ds_read_b32 v0, v103 offset:27936
	ds_read_b64 v[98:99], v98 offset:28192
	v_pk_fma_f32 v[22:23], v[90:91], v[40:41], v[24:25]
	v_pk_fma_f32 v[20:21], v[90:91], v[20:21], v[18:19]
	v_add_f32_e32 v18, v22, v23
	v_add_f32_e32 v19, v20, v21
	s_nop 0
	v_add_f32_dpp v18, v18, v18 quad_perm:[1,0,3,2] row_mask:0xf bank_mask:0xf bound_ctrl:1
	v_add_f32_dpp v19, v19, v19 quad_perm:[1,0,3,2] row_mask:0xf bank_mask:0xf bound_ctrl:1
	s_nop 0
	v_add_f32_dpp v18, v18, v18 quad_perm:[2,3,0,1] row_mask:0xf bank_mask:0xf bound_ctrl:1
	v_add_f32_dpp v19, v19, v19 quad_perm:[2,3,0,1] row_mask:0xf bank_mask:0xf bound_ctrl:1
	s_nop 0
	v_add_f32_dpp v18, v18, v18 row_half_mirror row_mask:0xf bank_mask:0xf bound_ctrl:1
	v_mov_b32_e32 v22, v97
	v_mov_b32_e32 v23, v18
	v_pk_mul_f32 v[22:23], v[22:23], v[94:95]
	v_add_f32_dpp v19, v19, v19 row_half_mirror row_mask:0xf bank_mask:0xf bound_ctrl:1
	v_add_f32_e32 v19, v23, v19
	v_add_f32_e32 v19, v22, v19
	s_ashr_i32 s19, s18, 31
	v_bfe_u32 v20, v19, 16, 1
	s_lshl_b64 s[10:11], s[18:19], 9
	v_add3_u32 v19, v19, v20, s28
	v_lshl_add_u64 v[20:21], v[92:93], 0, s[10:11]
	global_store_short_d16_hi v[20:21], v19, off
	v_pk_mul_f32 v[2:3], v[84:85], v[2:3]
	s_nop 0
	v_pk_fma_f32 v[2:3], v[18:19], v[26:27], v[2:3] op_sel_hi:[0,1,1]
	v_pk_fma_f32 v[84:85], v[94:95], v[10:11], v[2:3] op_sel_hi:[0,1,1]
	v_pk_mul_f32 v[2:3], v[86:87], v[4:5]
	s_waitcnt lgkmcnt(5)
	v_pk_fma_f32 v[78:79], v[84:85], v[78:79], 0 op_sel_hi:[1,1,0]
	v_pk_fma_f32 v[2:3], v[18:19], v[28:29], v[2:3] op_sel_hi:[0,1,1]
	v_pk_fma_f32 v[86:87], v[94:95], v[12:13], v[2:3] op_sel_hi:[0,1,1]
	v_pk_mul_f32 v[2:3], v[88:89], v[6:7]
	v_pk_fma_f32 v[70:71], v[84:85], v[70:71], 0 op_sel_hi:[1,1,0]
	v_pk_fma_f32 v[2:3], v[18:19], v[30:31], v[2:3] op_sel_hi:[0,1,1]
	v_pk_fma_f32 v[88:89], v[94:95], v[14:15], v[2:3] op_sel_hi:[0,1,1]
	v_pk_mul_f32 v[2:3], v[90:91], v[8:9]
	v_pk_fma_f32 v[78:79], v[86:87], v[80:81], v[78:79]
	v_pk_fma_f32 v[2:3], v[18:19], v[32:33], v[2:3] op_sel_hi:[0,1,1]
	v_pk_fma_f32 v[90:91], v[94:95], v[16:17], v[2:3] op_sel_hi:[0,1,1]
	ds_read_b128 v[22:25], v96 offset:28224
	ds_read_b128 v[18:21], v96 offset:28240
	ds_read_b128 v[2:5], v96 offset:28480
	ds_read_b128 v[6:9], v96 offset:28496
	ds_read_b128 v[10:13], v96 offset:28736
	ds_read_b128 v[14:17], v96 offset:28752
	ds_read_b128 v[34:37], v96 offset:28992
	ds_read_b128 v[38:41], v96 offset:29008
	ds_read_b128 v[26:29], v96 offset:29248
	ds_read_b128 v[30:33], v96 offset:29264
	v_pk_fma_f32 v[70:71], v[86:87], v[72:73], v[70:71]
	s_waitcnt lgkmcnt(14)
	v_pk_fma_f32 v[72:73], v[88:89], v[74:75], v[78:79]
	v_pk_fma_f32 v[66:67], v[88:89], v[66:67], v[70:71]
	v_mov_b32_e32 v95, s6
	ds_read_b32 v94, v103 offset:29504
	ds_read_b64 v[96:97], v95 offset:29760
	v_pk_fma_f32 v[70:71], v[90:91], v[76:77], v[72:73]
	v_pk_fma_f32 v[68:69], v[90:91], v[68:69], v[66:67]
	v_add_f32_e32 v66, v70, v71
	v_add_f32_e32 v67, v68, v69
	s_nop 0
	v_add_f32_dpp v66, v66, v66 quad_perm:[1,0,3,2] row_mask:0xf bank_mask:0xf bound_ctrl:1
	v_add_f32_dpp v67, v67, v67 quad_perm:[1,0,3,2] row_mask:0xf bank_mask:0xf bound_ctrl:1
	s_nop 0
	v_add_f32_dpp v66, v66, v66 quad_perm:[2,3,0,1] row_mask:0xf bank_mask:0xf bound_ctrl:1
	v_add_f32_dpp v68, v67, v67 quad_perm:[2,3,0,1] row_mask:0xf bank_mask:0xf bound_ctrl:1
	s_nop 0
	v_add_f32_dpp v66, v66, v66 row_half_mirror row_mask:0xf bank_mask:0xf bound_ctrl:1
	s_waitcnt lgkmcnt(13)
	v_mov_b32_e32 v67, v0
	s_waitcnt lgkmcnt(12)
	v_pk_mul_f32 v[70:71], v[98:99], v[66:67]
	v_add_f32_dpp v67, v68, v68 row_half_mirror row_mask:0xf bank_mask:0xf bound_ctrl:1
	v_add_f32_e32 v67, v70, v67
	s_add_i32 s10, s2, s18
	v_add_f32_e32 v67, v71, v67
	s_ashr_i32 s11, s10, 31
	v_bfe_u32 v68, v67, 16, 1
	s_lshl_b64 s[10:11], s[10:11], 9
	v_add3_u32 v67, v67, v68, s28
	v_lshl_add_u64 v[68:69], v[92:93], 0, s[10:11]
	global_store_short_d16_hi v[68:69], v67, off
	v_pk_mul_f32 v[50:51], v[50:51], v[84:85]
	v_pk_mul_f32 v[46:47], v[46:47], v[88:89]
	s_waitcnt lgkmcnt(14)
	v_pk_fma_f32 v[50:51], v[66:67], v[62:63], v[50:51] op_sel_hi:[0,1,1]
	v_pk_fma_f32 v[46:47], v[66:67], v[58:59], v[46:47] op_sel_hi:[0,1,1]
	s_waitcnt lgkmcnt(13)
	v_pk_fma_f32 v[84:85], v[0:1], v[54:55], v[50:51] op_sel_hi:[0,1,1]
	v_pk_mul_f32 v[50:51], v[52:53], v[86:87]
	v_pk_fma_f32 v[88:89], v[0:1], v[42:43], v[46:47] op_sel_hi:[0,1,1]
	v_pk_mul_f32 v[42:43], v[48:49], v[90:91]
	v_pk_fma_f32 v[50:51], v[66:67], v[64:65], v[50:51] op_sel_hi:[0,1,1]
	v_pk_fma_f32 v[42:43], v[66:67], v[60:61], v[42:43] op_sel_hi:[0,1,1]
	s_add_i32 s18, s18, s3
	s_add_i32 s7, s7, 2
	s_addk_i32 s6, 0xc40
	v_pk_fma_f32 v[86:87], v[0:1], v[56:57], v[50:51] op_sel_hi:[0,1,1]
	v_pk_fma_f32 v[90:91], v[0:1], v[44:45], v[42:43] op_sel_hi:[0,1,1]
	s_waitcnt lgkmcnt(0)
	v_mov_b32_e32 v95, v96
	v_add_u32_e32 v96, s6, v100
	ds_read_b128 v[70:73], v96 offset:26656
	ds_read_b128 v[66:69], v96 offset:26672
	ds_read_b128 v[50:53], v96 offset:26912
	ds_read_b128 v[46:49], v96 offset:26928
	ds_read_b128 v[54:57], v96 offset:27168
	ds_read_b128 v[42:45], v96 offset:27184
	ds_read_b128 v[78:81], v96 offset:27424
	ds_read_b128 v[74:77], v96 offset:27440
	ds_read_b128 v[62:65], v96 offset:27680
	ds_read_b128 v[58:61], v96 offset:27696
	v_pk_fma_f32 v[34:35], v[84:85], v[34:35], 0 op_sel_hi:[1,1,0]
	v_pk_fma_f32 v[22:23], v[84:85], v[22:23], 0 op_sel_hi:[1,1,0]
	v_pk_fma_f32 v[34:35], v[86:87], v[36:37], v[34:35]
	v_pk_fma_f32 v[22:23], v[86:87], v[24:25], v[22:23]
	v_add_u32_e32 v103, s6, v102
	v_mov_b32_e32 v98, s6
	v_pk_fma_f32 v[24:25], v[88:89], v[38:39], v[34:35]
	v_pk_fma_f32 v[18:19], v[88:89], v[18:19], v[22:23]
	ds_read_b32 v0, v103 offset:27936
	ds_read_b64 v[98:99], v98 offset:28192
	v_pk_fma_f32 v[22:23], v[90:91], v[40:41], v[24:25]
	v_pk_fma_f32 v[20:21], v[90:91], v[20:21], v[18:19]
	v_add_f32_e32 v18, v22, v23
	v_add_f32_e32 v19, v20, v21
	s_nop 0
	v_add_f32_dpp v18, v18, v18 quad_perm:[1,0,3,2] row_mask:0xf bank_mask:0xf bound_ctrl:1
	v_add_f32_dpp v19, v19, v19 quad_perm:[1,0,3,2] row_mask:0xf bank_mask:0xf bound_ctrl:1
	s_nop 0
	v_add_f32_dpp v18, v18, v18 quad_perm:[2,3,0,1] row_mask:0xf bank_mask:0xf bound_ctrl:1
	v_add_f32_dpp v19, v19, v19 quad_perm:[2,3,0,1] row_mask:0xf bank_mask:0xf bound_ctrl:1
	s_nop 0
	v_add_f32_dpp v18, v18, v18 row_half_mirror row_mask:0xf bank_mask:0xf bound_ctrl:1
	v_mov_b32_e32 v22, v97
	v_mov_b32_e32 v23, v18
	v_pk_mul_f32 v[22:23], v[22:23], v[94:95]
	v_add_f32_dpp v19, v19, v19 row_half_mirror row_mask:0xf bank_mask:0xf bound_ctrl:1
	v_add_f32_e32 v19, v23, v19
	v_add_f32_e32 v19, v22, v19
	s_ashr_i32 s19, s18, 31
	v_bfe_u32 v20, v19, 16, 1
	s_lshl_b64 s[10:11], s[18:19], 9
	v_add3_u32 v19, v19, v20, s28
	v_lshl_add_u64 v[20:21], v[92:93], 0, s[10:11]
	global_store_short_d16_hi v[20:21], v19, off
	v_pk_mul_f32 v[2:3], v[84:85], v[2:3]
	s_nop 0
	v_pk_fma_f32 v[2:3], v[18:19], v[26:27], v[2:3] op_sel_hi:[0,1,1]
	v_pk_fma_f32 v[84:85], v[94:95], v[10:11], v[2:3] op_sel_hi:[0,1,1]
	v_pk_mul_f32 v[2:3], v[86:87], v[4:5]
	s_waitcnt lgkmcnt(5)
	v_pk_fma_f32 v[78:79], v[84:85], v[78:79], 0 op_sel_hi:[1,1,0]
	v_pk_fma_f32 v[2:3], v[18:19], v[28:29], v[2:3] op_sel_hi:[0,1,1]
	v_pk_fma_f32 v[86:87], v[94:95], v[12:13], v[2:3] op_sel_hi:[0,1,1]
	v_pk_mul_f32 v[2:3], v[88:89], v[6:7]
	v_pk_fma_f32 v[70:71], v[84:85], v[70:71], 0 op_sel_hi:[1,1,0]
	v_pk_fma_f32 v[2:3], v[18:19], v[30:31], v[2:3] op_sel_hi:[0,1,1]
	v_pk_fma_f32 v[88:89], v[94:95], v[14:15], v[2:3] op_sel_hi:[0,1,1]
	v_pk_mul_f32 v[2:3], v[90:91], v[8:9]
	v_pk_fma_f32 v[78:79], v[86:87], v[80:81], v[78:79]
	v_pk_fma_f32 v[2:3], v[18:19], v[32:33], v[2:3] op_sel_hi:[0,1,1]
	v_pk_fma_f32 v[90:91], v[94:95], v[16:17], v[2:3] op_sel_hi:[0,1,1]
	ds_read_b128 v[22:25], v96 offset:28224
	ds_read_b128 v[18:21], v96 offset:28240
	ds_read_b128 v[2:5], v96 offset:28480
	ds_read_b128 v[6:9], v96 offset:28496
	ds_read_b128 v[10:13], v96 offset:28736
	ds_read_b128 v[14:17], v96 offset:28752
	ds_read_b128 v[34:37], v96 offset:28992
	ds_read_b128 v[38:41], v96 offset:29008
	ds_read_b128 v[26:29], v96 offset:29248
	ds_read_b128 v[30:33], v96 offset:29264
	v_pk_fma_f32 v[70:71], v[86:87], v[72:73], v[70:71]
	s_waitcnt lgkmcnt(14)
	v_pk_fma_f32 v[72:73], v[88:89], v[74:75], v[78:79]
	v_pk_fma_f32 v[66:67], v[88:89], v[66:67], v[70:71]
	v_mov_b32_e32 v95, s6
	ds_read_b32 v94, v103 offset:29504
	ds_read_b64 v[96:97], v95 offset:29760
	v_pk_fma_f32 v[70:71], v[90:91], v[76:77], v[72:73]
	v_pk_fma_f32 v[68:69], v[90:91], v[68:69], v[66:67]
	v_add_f32_e32 v66, v70, v71
	v_add_f32_e32 v67, v68, v69
	s_nop 0
	v_add_f32_dpp v66, v66, v66 quad_perm:[1,0,3,2] row_mask:0xf bank_mask:0xf bound_ctrl:1
	v_add_f32_dpp v67, v67, v67 quad_perm:[1,0,3,2] row_mask:0xf bank_mask:0xf bound_ctrl:1
	s_nop 0
	v_add_f32_dpp v66, v66, v66 quad_perm:[2,3,0,1] row_mask:0xf bank_mask:0xf bound_ctrl:1
	v_add_f32_dpp v68, v67, v67 quad_perm:[2,3,0,1] row_mask:0xf bank_mask:0xf bound_ctrl:1
	s_nop 0
	v_add_f32_dpp v66, v66, v66 row_half_mirror row_mask:0xf bank_mask:0xf bound_ctrl:1
	s_waitcnt lgkmcnt(13)
	v_mov_b32_e32 v67, v0
	s_waitcnt lgkmcnt(12)
	v_pk_mul_f32 v[70:71], v[98:99], v[66:67]
	v_add_f32_dpp v67, v68, v68 row_half_mirror row_mask:0xf bank_mask:0xf bound_ctrl:1
	v_add_f32_e32 v67, v70, v67
	s_add_i32 s10, s2, s18
	v_add_f32_e32 v67, v71, v67
	s_ashr_i32 s11, s10, 31
	v_bfe_u32 v68, v67, 16, 1
	s_lshl_b64 s[10:11], s[10:11], 9
	v_add3_u32 v67, v67, v68, s28
	v_lshl_add_u64 v[68:69], v[92:93], 0, s[10:11]
	global_store_short_d16_hi v[68:69], v67, off
	v_pk_mul_f32 v[50:51], v[50:51], v[84:85]
	v_pk_mul_f32 v[46:47], v[46:47], v[88:89]
	s_waitcnt lgkmcnt(14)
	v_pk_fma_f32 v[50:51], v[66:67], v[62:63], v[50:51] op_sel_hi:[0,1,1]
	v_pk_fma_f32 v[46:47], v[66:67], v[58:59], v[46:47] op_sel_hi:[0,1,1]
	s_waitcnt lgkmcnt(13)
	v_pk_fma_f32 v[84:85], v[0:1], v[54:55], v[50:51] op_sel_hi:[0,1,1]
	v_pk_mul_f32 v[50:51], v[52:53], v[86:87]
	v_pk_fma_f32 v[88:89], v[0:1], v[42:43], v[46:47] op_sel_hi:[0,1,1]
	v_pk_mul_f32 v[42:43], v[48:49], v[90:91]
	v_pk_fma_f32 v[50:51], v[66:67], v[64:65], v[50:51] op_sel_hi:[0,1,1]
	v_pk_fma_f32 v[42:43], v[66:67], v[60:61], v[42:43] op_sel_hi:[0,1,1]
	s_add_i32 s18, s18, s3
	s_add_i32 s7, s7, 2
	s_addk_i32 s6, 0xc40
	v_pk_fma_f32 v[86:87], v[0:1], v[56:57], v[50:51] op_sel_hi:[0,1,1]
	v_pk_fma_f32 v[90:91], v[0:1], v[44:45], v[42:43] op_sel_hi:[0,1,1]
	s_waitcnt lgkmcnt(0)
	v_mov_b32_e32 v95, v96
	v_add_u32_e32 v96, s6, v100
	ds_read_b128 v[70:73], v96 offset:26656
	ds_read_b128 v[66:69], v96 offset:26672
	ds_read_b128 v[50:53], v96 offset:26912
	ds_read_b128 v[46:49], v96 offset:26928
	ds_read_b128 v[54:57], v96 offset:27168
	ds_read_b128 v[42:45], v96 offset:27184
	ds_read_b128 v[78:81], v96 offset:27424
	ds_read_b128 v[74:77], v96 offset:27440
	ds_read_b128 v[62:65], v96 offset:27680
	ds_read_b128 v[58:61], v96 offset:27696
	v_pk_fma_f32 v[34:35], v[84:85], v[34:35], 0 op_sel_hi:[1,1,0]
	v_pk_fma_f32 v[22:23], v[84:85], v[22:23], 0 op_sel_hi:[1,1,0]
	v_pk_fma_f32 v[34:35], v[86:87], v[36:37], v[34:35]
	v_pk_fma_f32 v[22:23], v[86:87], v[24:25], v[22:23]
	v_add_u32_e32 v103, s6, v102
	v_mov_b32_e32 v98, s6
	v_pk_fma_f32 v[24:25], v[88:89], v[38:39], v[34:35]
	v_pk_fma_f32 v[18:19], v[88:89], v[18:19], v[22:23]
	ds_read_b32 v0, v103 offset:27936
	ds_read_b64 v[98:99], v98 offset:28192
	v_pk_fma_f32 v[22:23], v[90:91], v[40:41], v[24:25]
	v_pk_fma_f32 v[20:21], v[90:91], v[20:21], v[18:19]
	v_add_f32_e32 v18, v22, v23
	v_add_f32_e32 v19, v20, v21
	s_nop 0
	v_add_f32_dpp v18, v18, v18 quad_perm:[1,0,3,2] row_mask:0xf bank_mask:0xf bound_ctrl:1
	v_add_f32_dpp v19, v19, v19 quad_perm:[1,0,3,2] row_mask:0xf bank_mask:0xf bound_ctrl:1
	s_nop 0
	v_add_f32_dpp v18, v18, v18 quad_perm:[2,3,0,1] row_mask:0xf bank_mask:0xf bound_ctrl:1
	v_add_f32_dpp v19, v19, v19 quad_perm:[2,3,0,1] row_mask:0xf bank_mask:0xf bound_ctrl:1
	s_nop 0
	v_add_f32_dpp v18, v18, v18 row_half_mirror row_mask:0xf bank_mask:0xf bound_ctrl:1
	v_mov_b32_e32 v22, v97
	v_mov_b32_e32 v23, v18
	v_pk_mul_f32 v[22:23], v[22:23], v[94:95]
	v_add_f32_dpp v19, v19, v19 row_half_mirror row_mask:0xf bank_mask:0xf bound_ctrl:1
	v_add_f32_e32 v19, v23, v19
	v_add_f32_e32 v19, v22, v19
	s_ashr_i32 s19, s18, 31
	v_bfe_u32 v20, v19, 16, 1
	s_lshl_b64 s[10:11], s[18:19], 9
	v_add3_u32 v19, v19, v20, s28
	v_lshl_add_u64 v[20:21], v[92:93], 0, s[10:11]
	global_store_short_d16_hi v[20:21], v19, off
	v_pk_mul_f32 v[2:3], v[84:85], v[2:3]
	s_nop 0
	v_pk_fma_f32 v[2:3], v[18:19], v[26:27], v[2:3] op_sel_hi:[0,1,1]
	v_pk_fma_f32 v[84:85], v[94:95], v[10:11], v[2:3] op_sel_hi:[0,1,1]
	v_pk_mul_f32 v[2:3], v[86:87], v[4:5]
	s_waitcnt lgkmcnt(5)
	v_pk_fma_f32 v[78:79], v[84:85], v[78:79], 0 op_sel_hi:[1,1,0]
	v_pk_fma_f32 v[2:3], v[18:19], v[28:29], v[2:3] op_sel_hi:[0,1,1]
	v_pk_fma_f32 v[86:87], v[94:95], v[12:13], v[2:3] op_sel_hi:[0,1,1]
	v_pk_mul_f32 v[2:3], v[88:89], v[6:7]
	v_pk_fma_f32 v[70:71], v[84:85], v[70:71], 0 op_sel_hi:[1,1,0]
	v_pk_fma_f32 v[2:3], v[18:19], v[30:31], v[2:3] op_sel_hi:[0,1,1]
	v_pk_fma_f32 v[88:89], v[94:95], v[14:15], v[2:3] op_sel_hi:[0,1,1]
	v_pk_mul_f32 v[2:3], v[90:91], v[8:9]
	v_pk_fma_f32 v[78:79], v[86:87], v[80:81], v[78:79]
	v_pk_fma_f32 v[2:3], v[18:19], v[32:33], v[2:3] op_sel_hi:[0,1,1]
	v_pk_fma_f32 v[90:91], v[94:95], v[16:17], v[2:3] op_sel_hi:[0,1,1]
	ds_read_b128 v[22:25], v96 offset:28224
	ds_read_b128 v[18:21], v96 offset:28240
	ds_read_b128 v[2:5], v96 offset:28480
	ds_read_b128 v[6:9], v96 offset:28496
	ds_read_b128 v[10:13], v96 offset:28736
	ds_read_b128 v[14:17], v96 offset:28752
	ds_read_b128 v[34:37], v96 offset:28992
	ds_read_b128 v[38:41], v96 offset:29008
	ds_read_b128 v[26:29], v96 offset:29248
	ds_read_b128 v[30:33], v96 offset:29264
	v_pk_fma_f32 v[70:71], v[86:87], v[72:73], v[70:71]
	s_waitcnt lgkmcnt(14)
	v_pk_fma_f32 v[72:73], v[88:89], v[74:75], v[78:79]
	v_pk_fma_f32 v[66:67], v[88:89], v[66:67], v[70:71]
	v_mov_b32_e32 v95, s6
	ds_read_b32 v94, v103 offset:29504
	ds_read_b64 v[96:97], v95 offset:29760
	v_pk_fma_f32 v[70:71], v[90:91], v[76:77], v[72:73]
	v_pk_fma_f32 v[68:69], v[90:91], v[68:69], v[66:67]
	v_add_f32_e32 v66, v70, v71
	v_add_f32_e32 v67, v68, v69
	s_nop 0
	v_add_f32_dpp v66, v66, v66 quad_perm:[1,0,3,2] row_mask:0xf bank_mask:0xf bound_ctrl:1
	v_add_f32_dpp v67, v67, v67 quad_perm:[1,0,3,2] row_mask:0xf bank_mask:0xf bound_ctrl:1
	s_nop 0
	v_add_f32_dpp v66, v66, v66 quad_perm:[2,3,0,1] row_mask:0xf bank_mask:0xf bound_ctrl:1
	v_add_f32_dpp v68, v67, v67 quad_perm:[2,3,0,1] row_mask:0xf bank_mask:0xf bound_ctrl:1
	s_nop 0
	v_add_f32_dpp v66, v66, v66 row_half_mirror row_mask:0xf bank_mask:0xf bound_ctrl:1
	s_waitcnt lgkmcnt(13)
	v_mov_b32_e32 v67, v0
	s_waitcnt lgkmcnt(12)
	v_pk_mul_f32 v[70:71], v[98:99], v[66:67]
	v_add_f32_dpp v67, v68, v68 row_half_mirror row_mask:0xf bank_mask:0xf bound_ctrl:1
	v_add_f32_e32 v67, v70, v67
	s_add_i32 s10, s2, s18
	v_add_f32_e32 v67, v71, v67
	s_ashr_i32 s11, s10, 31
	v_bfe_u32 v68, v67, 16, 1
	s_lshl_b64 s[10:11], s[10:11], 9
	v_add3_u32 v67, v67, v68, s28
	v_lshl_add_u64 v[68:69], v[92:93], 0, s[10:11]
	global_store_short_d16_hi v[68:69], v67, off
	v_pk_mul_f32 v[50:51], v[50:51], v[84:85]
	v_pk_mul_f32 v[46:47], v[46:47], v[88:89]
	s_waitcnt lgkmcnt(14)
	v_pk_fma_f32 v[50:51], v[66:67], v[62:63], v[50:51] op_sel_hi:[0,1,1]
	v_pk_fma_f32 v[46:47], v[66:67], v[58:59], v[46:47] op_sel_hi:[0,1,1]
	s_waitcnt lgkmcnt(13)
	v_pk_fma_f32 v[84:85], v[0:1], v[54:55], v[50:51] op_sel_hi:[0,1,1]
	v_pk_mul_f32 v[50:51], v[52:53], v[86:87]
	v_pk_fma_f32 v[88:89], v[0:1], v[42:43], v[46:47] op_sel_hi:[0,1,1]
	v_pk_mul_f32 v[42:43], v[48:49], v[90:91]
	v_pk_fma_f32 v[50:51], v[66:67], v[64:65], v[50:51] op_sel_hi:[0,1,1]
	v_pk_fma_f32 v[42:43], v[66:67], v[60:61], v[42:43] op_sel_hi:[0,1,1]
	s_add_i32 s18, s18, s3
	s_add_i32 s7, s7, 2
	s_addk_i32 s6, 0xc40
	v_pk_fma_f32 v[86:87], v[0:1], v[56:57], v[50:51] op_sel_hi:[0,1,1]
	v_pk_fma_f32 v[90:91], v[0:1], v[44:45], v[42:43] op_sel_hi:[0,1,1]
	s_waitcnt lgkmcnt(0)
	v_mov_b32_e32 v95, v96
	v_add_u32_e32 v96, s6, v100
	ds_read_b128 v[70:73], v96 offset:26656
	ds_read_b128 v[66:69], v96 offset:26672
	ds_read_b128 v[50:53], v96 offset:26912
	ds_read_b128 v[46:49], v96 offset:26928
	ds_read_b128 v[54:57], v96 offset:27168
	ds_read_b128 v[42:45], v96 offset:27184
	ds_read_b128 v[78:81], v96 offset:27424
	ds_read_b128 v[74:77], v96 offset:27440
	ds_read_b128 v[62:65], v96 offset:27680
	ds_read_b128 v[58:61], v96 offset:27696
	v_pk_fma_f32 v[34:35], v[84:85], v[34:35], 0 op_sel_hi:[1,1,0]
	v_pk_fma_f32 v[22:23], v[84:85], v[22:23], 0 op_sel_hi:[1,1,0]
	v_pk_fma_f32 v[34:35], v[86:87], v[36:37], v[34:35]
	v_pk_fma_f32 v[22:23], v[86:87], v[24:25], v[22:23]
	v_add_u32_e32 v103, s6, v102
	v_mov_b32_e32 v98, s6
	v_pk_fma_f32 v[24:25], v[88:89], v[38:39], v[34:35]
	v_pk_fma_f32 v[18:19], v[88:89], v[18:19], v[22:23]
	ds_read_b32 v0, v103 offset:27936
	ds_read_b64 v[98:99], v98 offset:28192
	v_pk_fma_f32 v[22:23], v[90:91], v[40:41], v[24:25]
	v_pk_fma_f32 v[20:21], v[90:91], v[20:21], v[18:19]
	v_add_f32_e32 v18, v22, v23
	v_add_f32_e32 v19, v20, v21
	s_nop 0
	v_add_f32_dpp v18, v18, v18 quad_perm:[1,0,3,2] row_mask:0xf bank_mask:0xf bound_ctrl:1
	v_add_f32_dpp v19, v19, v19 quad_perm:[1,0,3,2] row_mask:0xf bank_mask:0xf bound_ctrl:1
	s_nop 0
	v_add_f32_dpp v18, v18, v18 quad_perm:[2,3,0,1] row_mask:0xf bank_mask:0xf bound_ctrl:1
	v_add_f32_dpp v19, v19, v19 quad_perm:[2,3,0,1] row_mask:0xf bank_mask:0xf bound_ctrl:1
	s_nop 0
	v_add_f32_dpp v18, v18, v18 row_half_mirror row_mask:0xf bank_mask:0xf bound_ctrl:1
	v_mov_b32_e32 v22, v97
	v_mov_b32_e32 v23, v18
	v_pk_mul_f32 v[22:23], v[22:23], v[94:95]
	v_add_f32_dpp v19, v19, v19 row_half_mirror row_mask:0xf bank_mask:0xf bound_ctrl:1
	v_add_f32_e32 v19, v23, v19
	v_add_f32_e32 v19, v22, v19
	s_ashr_i32 s19, s18, 31
	v_bfe_u32 v20, v19, 16, 1
	s_lshl_b64 s[10:11], s[18:19], 9
	v_add3_u32 v19, v19, v20, s28
	v_lshl_add_u64 v[20:21], v[92:93], 0, s[10:11]
	global_store_short_d16_hi v[20:21], v19, off
	v_pk_mul_f32 v[2:3], v[84:85], v[2:3]
	s_nop 0
	v_pk_fma_f32 v[2:3], v[18:19], v[26:27], v[2:3] op_sel_hi:[0,1,1]
	v_pk_fma_f32 v[84:85], v[94:95], v[10:11], v[2:3] op_sel_hi:[0,1,1]
	v_pk_mul_f32 v[2:3], v[86:87], v[4:5]
	s_waitcnt lgkmcnt(5)
	v_pk_fma_f32 v[78:79], v[84:85], v[78:79], 0 op_sel_hi:[1,1,0]
	v_pk_fma_f32 v[2:3], v[18:19], v[28:29], v[2:3] op_sel_hi:[0,1,1]
	v_pk_fma_f32 v[86:87], v[94:95], v[12:13], v[2:3] op_sel_hi:[0,1,1]
	v_pk_mul_f32 v[2:3], v[88:89], v[6:7]
	v_pk_fma_f32 v[70:71], v[84:85], v[70:71], 0 op_sel_hi:[1,1,0]
	v_pk_fma_f32 v[2:3], v[18:19], v[30:31], v[2:3] op_sel_hi:[0,1,1]
	v_pk_fma_f32 v[88:89], v[94:95], v[14:15], v[2:3] op_sel_hi:[0,1,1]
	v_pk_mul_f32 v[2:3], v[90:91], v[8:9]
	v_pk_fma_f32 v[78:79], v[86:87], v[80:81], v[78:79]
	v_pk_fma_f32 v[2:3], v[18:19], v[32:33], v[2:3] op_sel_hi:[0,1,1]
	v_pk_fma_f32 v[90:91], v[94:95], v[16:17], v[2:3] op_sel_hi:[0,1,1]
	ds_read_b128 v[22:25], v96 offset:28224
	ds_read_b128 v[18:21], v96 offset:28240
	ds_read_b128 v[2:5], v96 offset:28480
	ds_read_b128 v[6:9], v96 offset:28496
	ds_read_b128 v[10:13], v96 offset:28736
	ds_read_b128 v[14:17], v96 offset:28752
	ds_read_b128 v[34:37], v96 offset:28992
	ds_read_b128 v[38:41], v96 offset:29008
	ds_read_b128 v[26:29], v96 offset:29248
	ds_read_b128 v[30:33], v96 offset:29264
	v_pk_fma_f32 v[70:71], v[86:87], v[72:73], v[70:71]
	s_waitcnt lgkmcnt(14)
	v_pk_fma_f32 v[72:73], v[88:89], v[74:75], v[78:79]
	v_pk_fma_f32 v[66:67], v[88:89], v[66:67], v[70:71]
	v_mov_b32_e32 v95, s6
	ds_read_b32 v94, v103 offset:29504
	ds_read_b64 v[96:97], v95 offset:29760
	v_pk_fma_f32 v[70:71], v[90:91], v[76:77], v[72:73]
	v_pk_fma_f32 v[68:69], v[90:91], v[68:69], v[66:67]
	v_add_f32_e32 v66, v70, v71
	v_add_f32_e32 v67, v68, v69
	s_nop 0
	v_add_f32_dpp v66, v66, v66 quad_perm:[1,0,3,2] row_mask:0xf bank_mask:0xf bound_ctrl:1
	v_add_f32_dpp v67, v67, v67 quad_perm:[1,0,3,2] row_mask:0xf bank_mask:0xf bound_ctrl:1
	s_nop 0
	v_add_f32_dpp v66, v66, v66 quad_perm:[2,3,0,1] row_mask:0xf bank_mask:0xf bound_ctrl:1
	v_add_f32_dpp v68, v67, v67 quad_perm:[2,3,0,1] row_mask:0xf bank_mask:0xf bound_ctrl:1
	s_nop 0
	v_add_f32_dpp v66, v66, v66 row_half_mirror row_mask:0xf bank_mask:0xf bound_ctrl:1
	s_waitcnt lgkmcnt(13)
	v_mov_b32_e32 v67, v0
	s_waitcnt lgkmcnt(12)
	v_pk_mul_f32 v[70:71], v[98:99], v[66:67]
	v_add_f32_dpp v67, v68, v68 row_half_mirror row_mask:0xf bank_mask:0xf bound_ctrl:1
	v_add_f32_e32 v67, v70, v67
	s_add_i32 s10, s2, s18
	v_add_f32_e32 v67, v71, v67
	s_ashr_i32 s11, s10, 31
	v_bfe_u32 v68, v67, 16, 1
	s_lshl_b64 s[10:11], s[10:11], 9
	v_add3_u32 v67, v67, v68, s28
	v_lshl_add_u64 v[68:69], v[92:93], 0, s[10:11]
	global_store_short_d16_hi v[68:69], v67, off
	v_pk_mul_f32 v[50:51], v[50:51], v[84:85]
	v_pk_mul_f32 v[46:47], v[46:47], v[88:89]
	s_waitcnt lgkmcnt(14)
	v_pk_fma_f32 v[50:51], v[66:67], v[62:63], v[50:51] op_sel_hi:[0,1,1]
	v_pk_fma_f32 v[46:47], v[66:67], v[58:59], v[46:47] op_sel_hi:[0,1,1]
	s_waitcnt lgkmcnt(13)
	v_pk_fma_f32 v[84:85], v[0:1], v[54:55], v[50:51] op_sel_hi:[0,1,1]
	v_pk_mul_f32 v[50:51], v[52:53], v[86:87]
	v_pk_fma_f32 v[88:89], v[0:1], v[42:43], v[46:47] op_sel_hi:[0,1,1]
	v_pk_mul_f32 v[42:43], v[48:49], v[90:91]
	v_pk_fma_f32 v[50:51], v[66:67], v[64:65], v[50:51] op_sel_hi:[0,1,1]
	v_pk_fma_f32 v[42:43], v[66:67], v[60:61], v[42:43] op_sel_hi:[0,1,1]
	s_add_i32 s18, s18, s3
	s_add_i32 s7, s7, 2
	s_addk_i32 s6, 0xc40
	v_pk_fma_f32 v[86:87], v[0:1], v[56:57], v[50:51] op_sel_hi:[0,1,1]
	s_cmp_gt_u32 s7, 13
	v_pk_fma_f32 v[90:91], v[0:1], v[44:45], v[42:43] op_sel_hi:[0,1,1]
	s_cbranch_scc0 .LBB0_869
	s_branch .LBB0_852

.LBB0_906:
	s_waitcnt lgkmcnt(5)
	v_pk_fma_f32 v[100:101], v[74:75], v[2:3], 0 op_sel_hi:[1,1,0]
	s_waitcnt lgkmcnt(0)
	v_mov_b32_e32 v37, v34
	v_add_u32_e32 v34, s7, v94
	v_pk_fma_f32 v[30:31], v[74:75], v[30:31], 0 op_sel_hi:[1,1,0]
	v_pk_fma_f32 v[100:101], v[78:79], v[4:5], v[100:101]
	ds_read_b128 v[66:69], v34 offset:800
	ds_read_b128 v[62:65], v34 offset:816
	ds_read_b128 v[58:61], v34 offset:832
	ds_read_b128 v[54:57], v34 offset:848
	ds_read_b128 v[50:53], v34 offset:1056
	ds_read_b128 v[46:49], v34 offset:1072
	ds_read_b128 v[42:45], v34 offset:1088
	ds_read_b128 v[38:41], v34 offset:1104
	v_pk_fma_f32 v[30:31], v[78:79], v[32:33], v[30:31]
	v_pk_fma_f32 v[32:33], v[80:81], v[6:7], v[100:101]
	v_pk_fma_f32 v[26:27], v[80:81], v[26:27], v[30:31]
	v_pk_fma_f32 v[30:31], v[82:83], v[8:9], v[32:33]
	v_pk_fma_f32 v[26:27], v[82:83], v[28:29], v[26:27]
	s_waitcnt lgkmcnt(9)
	v_pk_fma_f32 v[28:29], v[84:85], v[14:15], v[30:31]
	v_pk_fma_f32 v[22:23], v[84:85], v[22:23], v[26:27]
	v_pk_fma_f32 v[26:27], v[86:87], v[16:17], v[28:29]
	v_pk_fma_f32 v[22:23], v[86:87], v[24:25], v[22:23]
	s_waitcnt lgkmcnt(8)
	v_pk_fma_f32 v[24:25], v[88:89], v[10:11], v[26:27]
	v_add_u32_e32 v98, s7, v97
	v_mov_b32_e32 v70, s7
	v_pk_fma_f32 v[18:19], v[88:89], v[18:19], v[22:23]
	v_pk_fma_f32 v[22:23], v[90:91], v[12:13], v[24:25]
	ds_read_b32 v0, v98
	ds_read_b96 v[70:72], v70 offset:1568
	v_pk_fma_f32 v[18:19], v[90:91], v[20:21], v[18:19]
	v_add_f32_e32 v20, v22, v23
	v_add_f32_e32 v18, v18, v19
	s_nop 0
	v_add_f32_dpp v20, v20, v20 quad_perm:[1,0,3,2] row_mask:0xf bank_mask:0xf bound_ctrl:1
	v_add_f32_dpp v19, v18, v18 quad_perm:[1,0,3,2] row_mask:0xf bank_mask:0xf bound_ctrl:1
	s_nop 0
	v_add_f32_dpp v20, v20, v20 quad_perm:[2,3,0,1] row_mask:0xf bank_mask:0xf bound_ctrl:1
	v_fma_f32 v18, -v37, v20, v73
	v_mul_f32_e32 v18, v35, v18
	v_add_f32_dpp v19, v19, v19 quad_perm:[2,3,0,1] row_mask:0xf bank_mask:0xf bound_ctrl:1
	v_mul_f32_e32 v20, v37, v19
	v_pk_fma_f32 v[20:21], v[36:37], v[18:19], v[20:21] op_sel_hi:[1,1,0]
	s_ashr_i32 s19, s18, 31
	v_bfe_u32 v19, v20, 16, 1
	s_lshl_b64 s[20:21], s[18:19], 9
	v_add3_u32 v19, v20, v19, s28
	v_lshl_add_u64 v[20:21], v[92:93], 0, s[20:21]
	global_store_short_d16_hi v[20:21], v19, off
	v_pk_mul_f32 v[20:21], v[74:75], v[36:37] op_sel:[0,1]
	s_nop 0
	v_pk_fma_f32 v[74:75], v[2:3], v[18:19], v[20:21] op_sel_hi:[1,0,1]
	v_pk_mul_f32 v[2:3], v[78:79], v[36:37] op_sel:[0,1]
	s_waitcnt lgkmcnt(9)
	v_pk_fma_f32 v[66:67], v[74:75], v[66:67], 0 op_sel_hi:[1,1,0]
	v_pk_fma_f32 v[78:79], v[4:5], v[18:19], v[2:3] op_sel_hi:[1,0,1]
	v_pk_mul_f32 v[2:3], v[80:81], v[36:37] op_sel:[0,1]
	v_pk_fma_f32 v[66:67], v[78:79], v[68:69], v[66:67]
	v_pk_fma_f32 v[80:81], v[6:7], v[18:19], v[2:3] op_sel_hi:[1,0,1]
	v_pk_mul_f32 v[2:3], v[82:83], v[36:37] op_sel:[0,1]
	s_waitcnt lgkmcnt(8)
	v_pk_fma_f32 v[62:63], v[80:81], v[62:63], v[66:67]
	v_pk_fma_f32 v[82:83], v[8:9], v[18:19], v[2:3] op_sel_hi:[1,0,1]
	v_pk_mul_f32 v[2:3], v[84:85], v[36:37] op_sel:[0,1]
	v_pk_fma_f32 v[62:63], v[82:83], v[64:65], v[62:63]
	v_pk_fma_f32 v[84:85], v[14:15], v[18:19], v[2:3] op_sel_hi:[1,0,1]
	v_pk_mul_f32 v[2:3], v[86:87], v[36:37] op_sel:[0,1]
	s_waitcnt lgkmcnt(7)
	v_pk_fma_f32 v[58:59], v[84:85], v[58:59], v[62:63]
	v_pk_fma_f32 v[86:87], v[16:17], v[18:19], v[2:3] op_sel_hi:[1,0,1]
	v_pk_mul_f32 v[2:3], v[88:89], v[36:37] op_sel:[0,1]
	v_pk_fma_f32 v[58:59], v[86:87], v[60:61], v[58:59]
	v_pk_fma_f32 v[88:89], v[10:11], v[18:19], v[2:3] op_sel_hi:[1,0,1]
	v_pk_mul_f32 v[2:3], v[90:91], v[36:37] op_sel:[0,1]
	s_waitcnt lgkmcnt(6)
	v_pk_fma_f32 v[54:55], v[88:89], v[54:55], v[58:59]
	v_pk_fma_f32 v[90:91], v[12:13], v[18:19], v[2:3] op_sel_hi:[1,0,1]
	ds_read_b128 v[30:33], v34 offset:1600
	ds_read_b128 v[26:29], v34 offset:1616
	ds_read_b128 v[22:25], v34 offset:1632
	ds_read_b128 v[18:21], v34 offset:1648
	ds_read_b128 v[2:5], v34 offset:1856
	ds_read_b128 v[6:9], v34 offset:1872
	ds_read_b128 v[14:17], v34 offset:1888
	ds_read_b128 v[10:13], v34 offset:1904
	v_mov_b32_e32 v34, s7
	ds_read_b32 v73, v98 offset:800
	ds_read_b96 v[34:36], v34 offset:2368
	s_waitcnt lgkmcnt(14)
	v_pk_fma_f32 v[98:99], v[74:75], v[50:51], 0 op_sel_hi:[1,1,0]
	v_pk_fma_f32 v[54:55], v[90:91], v[56:57], v[54:55]
	v_pk_fma_f32 v[98:99], v[78:79], v[52:53], v[98:99]
	s_nop 0
	v_pk_fma_f32 v[68:69], v[80:81], v[46:47], v[98:99]
	s_nop 0
	v_pk_fma_f32 v[66:67], v[82:83], v[48:49], v[68:69]
	s_waitcnt lgkmcnt(13)
	v_pk_fma_f32 v[64:65], v[84:85], v[42:43], v[66:67]
	s_nop 0
	v_pk_fma_f32 v[62:63], v[86:87], v[44:45], v[64:65]
	s_waitcnt lgkmcnt(12)
	v_pk_fma_f32 v[60:61], v[88:89], v[38:39], v[62:63]
	s_nop 0
	v_pk_fma_f32 v[58:59], v[90:91], v[40:41], v[60:61]
	s_nop 0
	v_add_f32_e32 v37, v58, v59
	s_nop 1
	v_add_f32_dpp v37, v37, v37 quad_perm:[1,0,3,2] row_mask:0xf bank_mask:0xf bound_ctrl:1
	s_nop 1
	v_add_f32_dpp v56, v37, v37 quad_perm:[2,3,0,1] row_mask:0xf bank_mask:0xf bound_ctrl:1
	v_add_f32_e32 v37, v54, v55
	s_waitcnt lgkmcnt(10)
	v_fma_f32 v0, -v70, v56, v0
	v_mul_f32_e32 v0, v71, v0
	v_add_f32_dpp v37, v37, v37 quad_perm:[1,0,3,2] row_mask:0xf bank_mask:0xf bound_ctrl:1
	s_nop 1
	v_add_f32_dpp v54, v37, v37 quad_perm:[2,3,0,1] row_mask:0xf bank_mask:0xf bound_ctrl:1
	v_mov_b32_e32 v71, v72
	v_mov_b32_e32 v55, v0
	v_mul_f32_e32 v56, v72, v0
	s_add_i32 s20, s24, s18
	v_pk_fma_f32 v[54:55], v[70:71], v[54:55], v[56:57] op_sel_hi:[1,1,0]
	s_ashr_i32 s21, s20, 31
	v_bfe_u32 v37, v54, 16, 1
	s_lshl_b64 s[20:21], s[20:21], 9
	v_add3_u32 v37, v54, v37, s28
	v_lshl_add_u64 v[54:55], v[92:93], 0, s[20:21]
	global_store_short_d16_hi v[54:55], v37, off
	v_pk_mul_f32 v[54:55], v[70:71], v[74:75] op_sel_hi:[0,1]
	v_pk_fma_f32 v[74:75], v[50:51], v[0:1], v[54:55] op_sel_hi:[1,0,1]
	v_pk_mul_f32 v[50:51], v[70:71], v[78:79] op_sel_hi:[0,1]
	v_pk_fma_f32 v[78:79], v[52:53], v[0:1], v[50:51] op_sel_hi:[1,0,1]
	v_pk_mul_f32 v[50:51], v[70:71], v[80:81] op_sel_hi:[0,1]
	v_pk_fma_f32 v[80:81], v[46:47], v[0:1], v[50:51] op_sel_hi:[1,0,1]
	v_pk_mul_f32 v[46:47], v[70:71], v[82:83] op_sel_hi:[0,1]
	v_pk_fma_f32 v[82:83], v[48:49], v[0:1], v[46:47] op_sel_hi:[1,0,1]
	v_pk_mul_f32 v[46:47], v[70:71], v[84:85] op_sel_hi:[0,1]
	v_pk_fma_f32 v[84:85], v[42:43], v[0:1], v[46:47] op_sel_hi:[1,0,1]
	v_pk_mul_f32 v[42:43], v[70:71], v[86:87] op_sel_hi:[0,1]
	v_pk_fma_f32 v[86:87], v[44:45], v[0:1], v[42:43] op_sel_hi:[1,0,1]
	v_pk_mul_f32 v[42:43], v[70:71], v[88:89] op_sel_hi:[0,1]
	v_pk_fma_f32 v[88:89], v[38:39], v[0:1], v[42:43] op_sel_hi:[1,0,1]
	v_pk_mul_f32 v[38:39], v[70:71], v[90:91] op_sel_hi:[0,1]
	s_add_i32 s18, s18, s25
	s_add_i32 s10, s10, 2
	s_addk_i32 s7, 0x640
	v_pk_fma_f32 v[90:91], v[40:41], v[0:1], v[38:39] op_sel_hi:[1,0,1]
	s_waitcnt lgkmcnt(5)
	v_pk_fma_f32 v[100:101], v[74:75], v[2:3], 0 op_sel_hi:[1,1,0]
	s_waitcnt lgkmcnt(0)
	v_mov_b32_e32 v37, v34
	v_add_u32_e32 v34, s7, v94
	v_pk_fma_f32 v[30:31], v[74:75], v[30:31], 0 op_sel_hi:[1,1,0]
	v_pk_fma_f32 v[100:101], v[78:79], v[4:5], v[100:101]
	ds_read_b128 v[66:69], v34 offset:800
	ds_read_b128 v[62:65], v34 offset:816
	ds_read_b128 v[58:61], v34 offset:832
	ds_read_b128 v[54:57], v34 offset:848
	ds_read_b128 v[50:53], v34 offset:1056
	ds_read_b128 v[46:49], v34 offset:1072
	ds_read_b128 v[42:45], v34 offset:1088
	ds_read_b128 v[38:41], v34 offset:1104
	v_pk_fma_f32 v[30:31], v[78:79], v[32:33], v[30:31]
	v_pk_fma_f32 v[32:33], v[80:81], v[6:7], v[100:101]
	v_pk_fma_f32 v[26:27], v[80:81], v[26:27], v[30:31]
	v_pk_fma_f32 v[30:31], v[82:83], v[8:9], v[32:33]
	v_pk_fma_f32 v[26:27], v[82:83], v[28:29], v[26:27]
	s_waitcnt lgkmcnt(9)
	v_pk_fma_f32 v[28:29], v[84:85], v[14:15], v[30:31]
	v_pk_fma_f32 v[22:23], v[84:85], v[22:23], v[26:27]
	v_pk_fma_f32 v[26:27], v[86:87], v[16:17], v[28:29]
	v_pk_fma_f32 v[22:23], v[86:87], v[24:25], v[22:23]
	s_waitcnt lgkmcnt(8)
	v_pk_fma_f32 v[24:25], v[88:89], v[10:11], v[26:27]
	v_add_u32_e32 v98, s7, v97
	v_mov_b32_e32 v70, s7
	v_pk_fma_f32 v[18:19], v[88:89], v[18:19], v[22:23]
	v_pk_fma_f32 v[22:23], v[90:91], v[12:13], v[24:25]
	ds_read_b32 v0, v98
	ds_read_b96 v[70:72], v70 offset:1568
	v_pk_fma_f32 v[18:19], v[90:91], v[20:21], v[18:19]
	v_add_f32_e32 v20, v22, v23
	v_add_f32_e32 v18, v18, v19
	s_nop 0
	v_add_f32_dpp v20, v20, v20 quad_perm:[1,0,3,2] row_mask:0xf bank_mask:0xf bound_ctrl:1
	v_add_f32_dpp v19, v18, v18 quad_perm:[1,0,3,2] row_mask:0xf bank_mask:0xf bound_ctrl:1
	s_nop 0
	v_add_f32_dpp v20, v20, v20 quad_perm:[2,3,0,1] row_mask:0xf bank_mask:0xf bound_ctrl:1
	v_fma_f32 v18, -v37, v20, v73
	v_mul_f32_e32 v18, v35, v18
	v_add_f32_dpp v19, v19, v19 quad_perm:[2,3,0,1] row_mask:0xf bank_mask:0xf bound_ctrl:1
	v_mul_f32_e32 v20, v37, v19
	v_pk_fma_f32 v[20:21], v[36:37], v[18:19], v[20:21] op_sel_hi:[1,1,0]
	s_ashr_i32 s19, s18, 31
	v_bfe_u32 v19, v20, 16, 1
	s_lshl_b64 s[20:21], s[18:19], 9
	v_add3_u32 v19, v20, v19, s28
	v_lshl_add_u64 v[20:21], v[92:93], 0, s[20:21]
	global_store_short_d16_hi v[20:21], v19, off
	v_pk_mul_f32 v[20:21], v[74:75], v[36:37] op_sel:[0,1]
	s_nop 0
	v_pk_fma_f32 v[74:75], v[2:3], v[18:19], v[20:21] op_sel_hi:[1,0,1]
	v_pk_mul_f32 v[2:3], v[78:79], v[36:37] op_sel:[0,1]
	s_waitcnt lgkmcnt(9)
	v_pk_fma_f32 v[66:67], v[74:75], v[66:67], 0 op_sel_hi:[1,1,0]
	v_pk_fma_f32 v[78:79], v[4:5], v[18:19], v[2:3] op_sel_hi:[1,0,1]
	v_pk_mul_f32 v[2:3], v[80:81], v[36:37] op_sel:[0,1]
	v_pk_fma_f32 v[66:67], v[78:79], v[68:69], v[66:67]
	v_pk_fma_f32 v[80:81], v[6:7], v[18:19], v[2:3] op_sel_hi:[1,0,1]
	v_pk_mul_f32 v[2:3], v[82:83], v[36:37] op_sel:[0,1]
	s_waitcnt lgkmcnt(8)
	v_pk_fma_f32 v[62:63], v[80:81], v[62:63], v[66:67]
	v_pk_fma_f32 v[82:83], v[8:9], v[18:19], v[2:3] op_sel_hi:[1,0,1]
	v_pk_mul_f32 v[2:3], v[84:85], v[36:37] op_sel:[0,1]
	v_pk_fma_f32 v[62:63], v[82:83], v[64:65], v[62:63]
	v_pk_fma_f32 v[84:85], v[14:15], v[18:19], v[2:3] op_sel_hi:[1,0,1]
	v_pk_mul_f32 v[2:3], v[86:87], v[36:37] op_sel:[0,1]
	s_waitcnt lgkmcnt(7)
	v_pk_fma_f32 v[58:59], v[84:85], v[58:59], v[62:63]
	v_pk_fma_f32 v[86:87], v[16:17], v[18:19], v[2:3] op_sel_hi:[1,0,1]
	v_pk_mul_f32 v[2:3], v[88:89], v[36:37] op_sel:[0,1]
	v_pk_fma_f32 v[58:59], v[86:87], v[60:61], v[58:59]
	v_pk_fma_f32 v[88:89], v[10:11], v[18:19], v[2:3] op_sel_hi:[1,0,1]
	v_pk_mul_f32 v[2:3], v[90:91], v[36:37] op_sel:[0,1]
	s_waitcnt lgkmcnt(6)
	v_pk_fma_f32 v[54:55], v[88:89], v[54:55], v[58:59]
	v_pk_fma_f32 v[90:91], v[12:13], v[18:19], v[2:3] op_sel_hi:[1,0,1]
	ds_read_b128 v[30:33], v34 offset:1600
	ds_read_b128 v[26:29], v34 offset:1616
	ds_read_b128 v[22:25], v34 offset:1632
	ds_read_b128 v[18:21], v34 offset:1648
	ds_read_b128 v[2:5], v34 offset:1856
	ds_read_b128 v[6:9], v34 offset:1872
	ds_read_b128 v[14:17], v34 offset:1888
	ds_read_b128 v[10:13], v34 offset:1904
	v_mov_b32_e32 v34, s7
	ds_read_b32 v73, v98 offset:800
	ds_read_b96 v[34:36], v34 offset:2368
	s_waitcnt lgkmcnt(14)
	v_pk_fma_f32 v[98:99], v[74:75], v[50:51], 0 op_sel_hi:[1,1,0]
	v_pk_fma_f32 v[54:55], v[90:91], v[56:57], v[54:55]
	v_pk_fma_f32 v[98:99], v[78:79], v[52:53], v[98:99]
	s_nop 0
	v_pk_fma_f32 v[68:69], v[80:81], v[46:47], v[98:99]
	s_nop 0
	v_pk_fma_f32 v[66:67], v[82:83], v[48:49], v[68:69]
	s_waitcnt lgkmcnt(13)
	v_pk_fma_f32 v[64:65], v[84:85], v[42:43], v[66:67]
	s_nop 0
	v_pk_fma_f32 v[62:63], v[86:87], v[44:45], v[64:65]
	s_waitcnt lgkmcnt(12)
	v_pk_fma_f32 v[60:61], v[88:89], v[38:39], v[62:63]
	s_nop 0
	v_pk_fma_f32 v[58:59], v[90:91], v[40:41], v[60:61]
	s_nop 0
	v_add_f32_e32 v37, v58, v59
	s_nop 1
	v_add_f32_dpp v37, v37, v37 quad_perm:[1,0,3,2] row_mask:0xf bank_mask:0xf bound_ctrl:1
	s_nop 1
	v_add_f32_dpp v56, v37, v37 quad_perm:[2,3,0,1] row_mask:0xf bank_mask:0xf bound_ctrl:1
	v_add_f32_e32 v37, v54, v55
	s_waitcnt lgkmcnt(10)
	v_fma_f32 v0, -v70, v56, v0
	v_mul_f32_e32 v0, v71, v0
	v_add_f32_dpp v37, v37, v37 quad_perm:[1,0,3,2] row_mask:0xf bank_mask:0xf bound_ctrl:1
	s_nop 1
	v_add_f32_dpp v54, v37, v37 quad_perm:[2,3,0,1] row_mask:0xf bank_mask:0xf bound_ctrl:1
	v_mov_b32_e32 v71, v72
	v_mov_b32_e32 v55, v0
	v_mul_f32_e32 v56, v72, v0
	s_add_i32 s20, s24, s18
	v_pk_fma_f32 v[54:55], v[70:71], v[54:55], v[56:57] op_sel_hi:[1,1,0]
	s_ashr_i32 s21, s20, 31
	v_bfe_u32 v37, v54, 16, 1
	s_lshl_b64 s[20:21], s[20:21], 9
	v_add3_u32 v37, v54, v37, s28
	v_lshl_add_u64 v[54:55], v[92:93], 0, s[20:21]
	global_store_short_d16_hi v[54:55], v37, off
	v_pk_mul_f32 v[54:55], v[70:71], v[74:75] op_sel_hi:[0,1]
	v_pk_fma_f32 v[74:75], v[50:51], v[0:1], v[54:55] op_sel_hi:[1,0,1]
	v_pk_mul_f32 v[50:51], v[70:71], v[78:79] op_sel_hi:[0,1]
	v_pk_fma_f32 v[78:79], v[52:53], v[0:1], v[50:51] op_sel_hi:[1,0,1]
	v_pk_mul_f32 v[50:51], v[70:71], v[80:81] op_sel_hi:[0,1]
	v_pk_fma_f32 v[80:81], v[46:47], v[0:1], v[50:51] op_sel_hi:[1,0,1]
	v_pk_mul_f32 v[46:47], v[70:71], v[82:83] op_sel_hi:[0,1]
	v_pk_fma_f32 v[82:83], v[48:49], v[0:1], v[46:47] op_sel_hi:[1,0,1]
	v_pk_mul_f32 v[46:47], v[70:71], v[84:85] op_sel_hi:[0,1]
	v_pk_fma_f32 v[84:85], v[42:43], v[0:1], v[46:47] op_sel_hi:[1,0,1]
	v_pk_mul_f32 v[42:43], v[70:71], v[86:87] op_sel_hi:[0,1]
	v_pk_fma_f32 v[86:87], v[44:45], v[0:1], v[42:43] op_sel_hi:[1,0,1]
	v_pk_mul_f32 v[42:43], v[70:71], v[88:89] op_sel_hi:[0,1]
	v_pk_fma_f32 v[88:89], v[38:39], v[0:1], v[42:43] op_sel_hi:[1,0,1]
	v_pk_mul_f32 v[38:39], v[70:71], v[90:91] op_sel_hi:[0,1]
	s_add_i32 s18, s18, s25
	s_add_i32 s10, s10, 2
	s_addk_i32 s7, 0x640
	v_pk_fma_f32 v[90:91], v[40:41], v[0:1], v[38:39] op_sel_hi:[1,0,1]
	s_waitcnt lgkmcnt(5)
	v_pk_fma_f32 v[100:101], v[74:75], v[2:3], 0 op_sel_hi:[1,1,0]
	s_waitcnt lgkmcnt(0)
	v_mov_b32_e32 v37, v34
	v_add_u32_e32 v34, s7, v94
	v_pk_fma_f32 v[30:31], v[74:75], v[30:31], 0 op_sel_hi:[1,1,0]
	v_pk_fma_f32 v[100:101], v[78:79], v[4:5], v[100:101]
	ds_read_b128 v[66:69], v34 offset:800
	ds_read_b128 v[62:65], v34 offset:816
	ds_read_b128 v[58:61], v34 offset:832
	ds_read_b128 v[54:57], v34 offset:848
	ds_read_b128 v[50:53], v34 offset:1056
	ds_read_b128 v[46:49], v34 offset:1072
	ds_read_b128 v[42:45], v34 offset:1088
	ds_read_b128 v[38:41], v34 offset:1104
	v_pk_fma_f32 v[30:31], v[78:79], v[32:33], v[30:31]
	v_pk_fma_f32 v[32:33], v[80:81], v[6:7], v[100:101]
	v_pk_fma_f32 v[26:27], v[80:81], v[26:27], v[30:31]
	v_pk_fma_f32 v[30:31], v[82:83], v[8:9], v[32:33]
	v_pk_fma_f32 v[26:27], v[82:83], v[28:29], v[26:27]
	s_waitcnt lgkmcnt(9)
	v_pk_fma_f32 v[28:29], v[84:85], v[14:15], v[30:31]
	v_pk_fma_f32 v[22:23], v[84:85], v[22:23], v[26:27]
	v_pk_fma_f32 v[26:27], v[86:87], v[16:17], v[28:29]
	v_pk_fma_f32 v[22:23], v[86:87], v[24:25], v[22:23]
	s_waitcnt lgkmcnt(8)
	v_pk_fma_f32 v[24:25], v[88:89], v[10:11], v[26:27]
	v_add_u32_e32 v98, s7, v97
	v_mov_b32_e32 v70, s7
	v_pk_fma_f32 v[18:19], v[88:89], v[18:19], v[22:23]
	v_pk_fma_f32 v[22:23], v[90:91], v[12:13], v[24:25]
	ds_read_b32 v0, v98
	ds_read_b96 v[70:72], v70 offset:1568
	v_pk_fma_f32 v[18:19], v[90:91], v[20:21], v[18:19]
	v_add_f32_e32 v20, v22, v23
	v_add_f32_e32 v18, v18, v19
	s_nop 0
	v_add_f32_dpp v20, v20, v20 quad_perm:[1,0,3,2] row_mask:0xf bank_mask:0xf bound_ctrl:1
	v_add_f32_dpp v19, v18, v18 quad_perm:[1,0,3,2] row_mask:0xf bank_mask:0xf bound_ctrl:1
	s_nop 0
	v_add_f32_dpp v20, v20, v20 quad_perm:[2,3,0,1] row_mask:0xf bank_mask:0xf bound_ctrl:1
	v_fma_f32 v18, -v37, v20, v73
	v_mul_f32_e32 v18, v35, v18
	v_add_f32_dpp v19, v19, v19 quad_perm:[2,3,0,1] row_mask:0xf bank_mask:0xf bound_ctrl:1
	v_mul_f32_e32 v20, v37, v19
	v_pk_fma_f32 v[20:21], v[36:37], v[18:19], v[20:21] op_sel_hi:[1,1,0]
	s_ashr_i32 s19, s18, 31
	v_bfe_u32 v19, v20, 16, 1
	s_lshl_b64 s[20:21], s[18:19], 9
	v_add3_u32 v19, v20, v19, s28
	v_lshl_add_u64 v[20:21], v[92:93], 0, s[20:21]
	global_store_short_d16_hi v[20:21], v19, off
	v_pk_mul_f32 v[20:21], v[74:75], v[36:37] op_sel:[0,1]
	s_nop 0
	v_pk_fma_f32 v[74:75], v[2:3], v[18:19], v[20:21] op_sel_hi:[1,0,1]
	v_pk_mul_f32 v[2:3], v[78:79], v[36:37] op_sel:[0,1]
	s_waitcnt lgkmcnt(9)
	v_pk_fma_f32 v[66:67], v[74:75], v[66:67], 0 op_sel_hi:[1,1,0]
	v_pk_fma_f32 v[78:79], v[4:5], v[18:19], v[2:3] op_sel_hi:[1,0,1]
	v_pk_mul_f32 v[2:3], v[80:81], v[36:37] op_sel:[0,1]
	v_pk_fma_f32 v[66:67], v[78:79], v[68:69], v[66:67]
	v_pk_fma_f32 v[80:81], v[6:7], v[18:19], v[2:3] op_sel_hi:[1,0,1]
	v_pk_mul_f32 v[2:3], v[82:83], v[36:37] op_sel:[0,1]
	s_waitcnt lgkmcnt(8)
	v_pk_fma_f32 v[62:63], v[80:81], v[62:63], v[66:67]
	v_pk_fma_f32 v[82:83], v[8:9], v[18:19], v[2:3] op_sel_hi:[1,0,1]
	v_pk_mul_f32 v[2:3], v[84:85], v[36:37] op_sel:[0,1]
	v_pk_fma_f32 v[62:63], v[82:83], v[64:65], v[62:63]
	v_pk_fma_f32 v[84:85], v[14:15], v[18:19], v[2:3] op_sel_hi:[1,0,1]
	v_pk_mul_f32 v[2:3], v[86:87], v[36:37] op_sel:[0,1]
	s_waitcnt lgkmcnt(7)
	v_pk_fma_f32 v[58:59], v[84:85], v[58:59], v[62:63]
	v_pk_fma_f32 v[86:87], v[16:17], v[18:19], v[2:3] op_sel_hi:[1,0,1]
	v_pk_mul_f32 v[2:3], v[88:89], v[36:37] op_sel:[0,1]
	v_pk_fma_f32 v[58:59], v[86:87], v[60:61], v[58:59]
	v_pk_fma_f32 v[88:89], v[10:11], v[18:19], v[2:3] op_sel_hi:[1,0,1]
	v_pk_mul_f32 v[2:3], v[90:91], v[36:37] op_sel:[0,1]
	s_waitcnt lgkmcnt(6)
	v_pk_fma_f32 v[54:55], v[88:89], v[54:55], v[58:59]
	v_pk_fma_f32 v[90:91], v[12:13], v[18:19], v[2:3] op_sel_hi:[1,0,1]
	ds_read_b128 v[30:33], v34 offset:1600
	ds_read_b128 v[26:29], v34 offset:1616
	ds_read_b128 v[22:25], v34 offset:1632
	ds_read_b128 v[18:21], v34 offset:1648
	ds_read_b128 v[2:5], v34 offset:1856
	ds_read_b128 v[6:9], v34 offset:1872
	ds_read_b128 v[14:17], v34 offset:1888
	ds_read_b128 v[10:13], v34 offset:1904
	v_mov_b32_e32 v34, s7
	ds_read_b32 v73, v98 offset:800
	ds_read_b96 v[34:36], v34 offset:2368
	s_waitcnt lgkmcnt(14)
	v_pk_fma_f32 v[98:99], v[74:75], v[50:51], 0 op_sel_hi:[1,1,0]
	v_pk_fma_f32 v[54:55], v[90:91], v[56:57], v[54:55]
	v_pk_fma_f32 v[98:99], v[78:79], v[52:53], v[98:99]
	s_nop 0
	v_pk_fma_f32 v[68:69], v[80:81], v[46:47], v[98:99]
	s_nop 0
	v_pk_fma_f32 v[66:67], v[82:83], v[48:49], v[68:69]
	s_waitcnt lgkmcnt(13)
	v_pk_fma_f32 v[64:65], v[84:85], v[42:43], v[66:67]
	s_nop 0
	v_pk_fma_f32 v[62:63], v[86:87], v[44:45], v[64:65]
	s_waitcnt lgkmcnt(12)
	v_pk_fma_f32 v[60:61], v[88:89], v[38:39], v[62:63]
	s_nop 0
	v_pk_fma_f32 v[58:59], v[90:91], v[40:41], v[60:61]
	s_nop 0
	v_add_f32_e32 v37, v58, v59
	s_nop 1
	v_add_f32_dpp v37, v37, v37 quad_perm:[1,0,3,2] row_mask:0xf bank_mask:0xf bound_ctrl:1
	s_nop 1
	v_add_f32_dpp v56, v37, v37 quad_perm:[2,3,0,1] row_mask:0xf bank_mask:0xf bound_ctrl:1
	v_add_f32_e32 v37, v54, v55
	s_waitcnt lgkmcnt(10)
	v_fma_f32 v0, -v70, v56, v0
	v_mul_f32_e32 v0, v71, v0
	v_add_f32_dpp v37, v37, v37 quad_perm:[1,0,3,2] row_mask:0xf bank_mask:0xf bound_ctrl:1
	s_nop 1
	v_add_f32_dpp v54, v37, v37 quad_perm:[2,3,0,1] row_mask:0xf bank_mask:0xf bound_ctrl:1
	v_mov_b32_e32 v71, v72
	v_mov_b32_e32 v55, v0
	v_mul_f32_e32 v56, v72, v0
	s_add_i32 s20, s24, s18
	v_pk_fma_f32 v[54:55], v[70:71], v[54:55], v[56:57] op_sel_hi:[1,1,0]
	s_ashr_i32 s21, s20, 31
	v_bfe_u32 v37, v54, 16, 1
	s_lshl_b64 s[20:21], s[20:21], 9
	v_add3_u32 v37, v54, v37, s28
	v_lshl_add_u64 v[54:55], v[92:93], 0, s[20:21]
	global_store_short_d16_hi v[54:55], v37, off
	v_pk_mul_f32 v[54:55], v[70:71], v[74:75] op_sel_hi:[0,1]
	v_pk_fma_f32 v[74:75], v[50:51], v[0:1], v[54:55] op_sel_hi:[1,0,1]
	v_pk_mul_f32 v[50:51], v[70:71], v[78:79] op_sel_hi:[0,1]
	v_pk_fma_f32 v[78:79], v[52:53], v[0:1], v[50:51] op_sel_hi:[1,0,1]
	v_pk_mul_f32 v[50:51], v[70:71], v[80:81] op_sel_hi:[0,1]
	v_pk_fma_f32 v[80:81], v[46:47], v[0:1], v[50:51] op_sel_hi:[1,0,1]
	v_pk_mul_f32 v[46:47], v[70:71], v[82:83] op_sel_hi:[0,1]
	v_pk_fma_f32 v[82:83], v[48:49], v[0:1], v[46:47] op_sel_hi:[1,0,1]
	v_pk_mul_f32 v[46:47], v[70:71], v[84:85] op_sel_hi:[0,1]
	v_pk_fma_f32 v[84:85], v[42:43], v[0:1], v[46:47] op_sel_hi:[1,0,1]
	v_pk_mul_f32 v[42:43], v[70:71], v[86:87] op_sel_hi:[0,1]
	v_pk_fma_f32 v[86:87], v[44:45], v[0:1], v[42:43] op_sel_hi:[1,0,1]
	v_pk_mul_f32 v[42:43], v[70:71], v[88:89] op_sel_hi:[0,1]
	v_pk_fma_f32 v[88:89], v[38:39], v[0:1], v[42:43] op_sel_hi:[1,0,1]
	v_pk_mul_f32 v[38:39], v[70:71], v[90:91] op_sel_hi:[0,1]
	s_add_i32 s18, s18, s25
	s_add_i32 s10, s10, 2
	s_addk_i32 s7, 0x640
	v_pk_fma_f32 v[90:91], v[40:41], v[0:1], v[38:39] op_sel_hi:[1,0,1]
	s_waitcnt lgkmcnt(5)
	v_pk_fma_f32 v[100:101], v[74:75], v[2:3], 0 op_sel_hi:[1,1,0]
	s_waitcnt lgkmcnt(0)
	v_mov_b32_e32 v37, v34
	v_add_u32_e32 v34, s7, v94
	v_pk_fma_f32 v[30:31], v[74:75], v[30:31], 0 op_sel_hi:[1,1,0]
	v_pk_fma_f32 v[100:101], v[78:79], v[4:5], v[100:101]
	ds_read_b128 v[66:69], v34 offset:800
	ds_read_b128 v[62:65], v34 offset:816
	ds_read_b128 v[58:61], v34 offset:832
	ds_read_b128 v[54:57], v34 offset:848
	ds_read_b128 v[50:53], v34 offset:1056
	ds_read_b128 v[46:49], v34 offset:1072
	ds_read_b128 v[42:45], v34 offset:1088
	ds_read_b128 v[38:41], v34 offset:1104
	v_pk_fma_f32 v[30:31], v[78:79], v[32:33], v[30:31]
	v_pk_fma_f32 v[32:33], v[80:81], v[6:7], v[100:101]
	v_pk_fma_f32 v[26:27], v[80:81], v[26:27], v[30:31]
	v_pk_fma_f32 v[30:31], v[82:83], v[8:9], v[32:33]
	v_pk_fma_f32 v[26:27], v[82:83], v[28:29], v[26:27]
	s_waitcnt lgkmcnt(9)
	v_pk_fma_f32 v[28:29], v[84:85], v[14:15], v[30:31]
	v_pk_fma_f32 v[22:23], v[84:85], v[22:23], v[26:27]
	v_pk_fma_f32 v[26:27], v[86:87], v[16:17], v[28:29]
	v_pk_fma_f32 v[22:23], v[86:87], v[24:25], v[22:23]
	s_waitcnt lgkmcnt(8)
	v_pk_fma_f32 v[24:25], v[88:89], v[10:11], v[26:27]
	v_add_u32_e32 v98, s7, v97
	v_mov_b32_e32 v70, s7
	v_pk_fma_f32 v[18:19], v[88:89], v[18:19], v[22:23]
	v_pk_fma_f32 v[22:23], v[90:91], v[12:13], v[24:25]
	ds_read_b32 v0, v98
	ds_read_b96 v[70:72], v70 offset:1568
	v_pk_fma_f32 v[18:19], v[90:91], v[20:21], v[18:19]
	v_add_f32_e32 v20, v22, v23
	v_add_f32_e32 v18, v18, v19
	s_nop 0
	v_add_f32_dpp v20, v20, v20 quad_perm:[1,0,3,2] row_mask:0xf bank_mask:0xf bound_ctrl:1
	v_add_f32_dpp v19, v18, v18 quad_perm:[1,0,3,2] row_mask:0xf bank_mask:0xf bound_ctrl:1
	s_nop 0
	v_add_f32_dpp v20, v20, v20 quad_perm:[2,3,0,1] row_mask:0xf bank_mask:0xf bound_ctrl:1
	v_fma_f32 v18, -v37, v20, v73
	v_mul_f32_e32 v18, v35, v18
	v_add_f32_dpp v19, v19, v19 quad_perm:[2,3,0,1] row_mask:0xf bank_mask:0xf bound_ctrl:1
	v_mul_f32_e32 v20, v37, v19
	v_pk_fma_f32 v[20:21], v[36:37], v[18:19], v[20:21] op_sel_hi:[1,1,0]
	s_ashr_i32 s19, s18, 31
	v_bfe_u32 v19, v20, 16, 1
	s_lshl_b64 s[20:21], s[18:19], 9
	v_add3_u32 v19, v20, v19, s28
	v_lshl_add_u64 v[20:21], v[92:93], 0, s[20:21]
	global_store_short_d16_hi v[20:21], v19, off
	v_pk_mul_f32 v[20:21], v[74:75], v[36:37] op_sel:[0,1]
	s_nop 0
	v_pk_fma_f32 v[74:75], v[2:3], v[18:19], v[20:21] op_sel_hi:[1,0,1]
	v_pk_mul_f32 v[2:3], v[78:79], v[36:37] op_sel:[0,1]
	s_waitcnt lgkmcnt(9)
	v_pk_fma_f32 v[66:67], v[74:75], v[66:67], 0 op_sel_hi:[1,1,0]
	v_pk_fma_f32 v[78:79], v[4:5], v[18:19], v[2:3] op_sel_hi:[1,0,1]
	v_pk_mul_f32 v[2:3], v[80:81], v[36:37] op_sel:[0,1]
	v_pk_fma_f32 v[66:67], v[78:79], v[68:69], v[66:67]
	v_pk_fma_f32 v[80:81], v[6:7], v[18:19], v[2:3] op_sel_hi:[1,0,1]
	v_pk_mul_f32 v[2:3], v[82:83], v[36:37] op_sel:[0,1]
	s_waitcnt lgkmcnt(8)
	v_pk_fma_f32 v[62:63], v[80:81], v[62:63], v[66:67]
	v_pk_fma_f32 v[82:83], v[8:9], v[18:19], v[2:3] op_sel_hi:[1,0,1]
	v_pk_mul_f32 v[2:3], v[84:85], v[36:37] op_sel:[0,1]
	v_pk_fma_f32 v[62:63], v[82:83], v[64:65], v[62:63]
	v_pk_fma_f32 v[84:85], v[14:15], v[18:19], v[2:3] op_sel_hi:[1,0,1]
	v_pk_mul_f32 v[2:3], v[86:87], v[36:37] op_sel:[0,1]
	s_waitcnt lgkmcnt(7)
	v_pk_fma_f32 v[58:59], v[84:85], v[58:59], v[62:63]
	v_pk_fma_f32 v[86:87], v[16:17], v[18:19], v[2:3] op_sel_hi:[1,0,1]
	v_pk_mul_f32 v[2:3], v[88:89], v[36:37] op_sel:[0,1]
	v_pk_fma_f32 v[58:59], v[86:87], v[60:61], v[58:59]
	v_pk_fma_f32 v[88:89], v[10:11], v[18:19], v[2:3] op_sel_hi:[1,0,1]
	v_pk_mul_f32 v[2:3], v[90:91], v[36:37] op_sel:[0,1]
	s_waitcnt lgkmcnt(6)
	v_pk_fma_f32 v[54:55], v[88:89], v[54:55], v[58:59]
	v_pk_fma_f32 v[90:91], v[12:13], v[18:19], v[2:3] op_sel_hi:[1,0,1]
	ds_read_b128 v[30:33], v34 offset:1600
	ds_read_b128 v[26:29], v34 offset:1616
	ds_read_b128 v[22:25], v34 offset:1632
	ds_read_b128 v[18:21], v34 offset:1648
	ds_read_b128 v[2:5], v34 offset:1856
	ds_read_b128 v[6:9], v34 offset:1872
	ds_read_b128 v[14:17], v34 offset:1888
	ds_read_b128 v[10:13], v34 offset:1904
	v_mov_b32_e32 v34, s7
	ds_read_b32 v73, v98 offset:800
	ds_read_b96 v[34:36], v34 offset:2368
	s_waitcnt lgkmcnt(14)
	v_pk_fma_f32 v[98:99], v[74:75], v[50:51], 0 op_sel_hi:[1,1,0]
	v_pk_fma_f32 v[54:55], v[90:91], v[56:57], v[54:55]
	v_pk_fma_f32 v[98:99], v[78:79], v[52:53], v[98:99]
	s_nop 0
	v_pk_fma_f32 v[68:69], v[80:81], v[46:47], v[98:99]
	s_nop 0
	v_pk_fma_f32 v[66:67], v[82:83], v[48:49], v[68:69]
	s_waitcnt lgkmcnt(13)
	v_pk_fma_f32 v[64:65], v[84:85], v[42:43], v[66:67]
	s_nop 0
	v_pk_fma_f32 v[62:63], v[86:87], v[44:45], v[64:65]
	s_waitcnt lgkmcnt(12)
	v_pk_fma_f32 v[60:61], v[88:89], v[38:39], v[62:63]
	s_nop 0
	v_pk_fma_f32 v[58:59], v[90:91], v[40:41], v[60:61]
	s_nop 0
	v_add_f32_e32 v37, v58, v59
	s_nop 1
	v_add_f32_dpp v37, v37, v37 quad_perm:[1,0,3,2] row_mask:0xf bank_mask:0xf bound_ctrl:1
	s_nop 1
	v_add_f32_dpp v56, v37, v37 quad_perm:[2,3,0,1] row_mask:0xf bank_mask:0xf bound_ctrl:1
	v_add_f32_e32 v37, v54, v55
	s_waitcnt lgkmcnt(10)
	v_fma_f32 v0, -v70, v56, v0
	v_mul_f32_e32 v0, v71, v0
	v_add_f32_dpp v37, v37, v37 quad_perm:[1,0,3,2] row_mask:0xf bank_mask:0xf bound_ctrl:1
	s_nop 1
	v_add_f32_dpp v54, v37, v37 quad_perm:[2,3,0,1] row_mask:0xf bank_mask:0xf bound_ctrl:1
	v_mov_b32_e32 v71, v72
	v_mov_b32_e32 v55, v0
	v_mul_f32_e32 v56, v72, v0
	s_add_i32 s20, s24, s18
	v_pk_fma_f32 v[54:55], v[70:71], v[54:55], v[56:57] op_sel_hi:[1,1,0]
	s_ashr_i32 s21, s20, 31
	v_bfe_u32 v37, v54, 16, 1
	s_lshl_b64 s[20:21], s[20:21], 9
	v_add3_u32 v37, v54, v37, s28
	v_lshl_add_u64 v[54:55], v[92:93], 0, s[20:21]
	global_store_short_d16_hi v[54:55], v37, off
	v_pk_mul_f32 v[54:55], v[70:71], v[74:75] op_sel_hi:[0,1]
	v_pk_fma_f32 v[74:75], v[50:51], v[0:1], v[54:55] op_sel_hi:[1,0,1]
	v_pk_mul_f32 v[50:51], v[70:71], v[78:79] op_sel_hi:[0,1]
	v_pk_fma_f32 v[78:79], v[52:53], v[0:1], v[50:51] op_sel_hi:[1,0,1]
	v_pk_mul_f32 v[50:51], v[70:71], v[80:81] op_sel_hi:[0,1]
	v_pk_fma_f32 v[80:81], v[46:47], v[0:1], v[50:51] op_sel_hi:[1,0,1]
	v_pk_mul_f32 v[46:47], v[70:71], v[82:83] op_sel_hi:[0,1]
	v_pk_fma_f32 v[82:83], v[48:49], v[0:1], v[46:47] op_sel_hi:[1,0,1]
	v_pk_mul_f32 v[46:47], v[70:71], v[84:85] op_sel_hi:[0,1]
	v_pk_fma_f32 v[84:85], v[42:43], v[0:1], v[46:47] op_sel_hi:[1,0,1]
	v_pk_mul_f32 v[42:43], v[70:71], v[86:87] op_sel_hi:[0,1]
	v_pk_fma_f32 v[86:87], v[44:45], v[0:1], v[42:43] op_sel_hi:[1,0,1]
	v_pk_mul_f32 v[42:43], v[70:71], v[88:89] op_sel_hi:[0,1]
	v_pk_fma_f32 v[88:89], v[38:39], v[0:1], v[42:43] op_sel_hi:[1,0,1]
	v_pk_mul_f32 v[38:39], v[70:71], v[90:91] op_sel_hi:[0,1]
	s_add_i32 s18, s18, s25
	s_add_i32 s10, s10, 2
	s_addk_i32 s7, 0x640
	v_pk_fma_f32 v[90:91], v[40:41], v[0:1], v[38:39] op_sel_hi:[1,0,1]
	s_waitcnt lgkmcnt(5)
	v_pk_fma_f32 v[100:101], v[74:75], v[2:3], 0 op_sel_hi:[1,1,0]
	s_waitcnt lgkmcnt(0)
	v_mov_b32_e32 v37, v34
	v_add_u32_e32 v34, s7, v94
	v_pk_fma_f32 v[30:31], v[74:75], v[30:31], 0 op_sel_hi:[1,1,0]
	v_pk_fma_f32 v[100:101], v[78:79], v[4:5], v[100:101]
	ds_read_b128 v[66:69], v34 offset:800
	ds_read_b128 v[62:65], v34 offset:816
	ds_read_b128 v[58:61], v34 offset:832
	ds_read_b128 v[54:57], v34 offset:848
	ds_read_b128 v[50:53], v34 offset:1056
	ds_read_b128 v[46:49], v34 offset:1072
	ds_read_b128 v[42:45], v34 offset:1088
	ds_read_b128 v[38:41], v34 offset:1104
	v_pk_fma_f32 v[30:31], v[78:79], v[32:33], v[30:31]
	v_pk_fma_f32 v[32:33], v[80:81], v[6:7], v[100:101]
	v_pk_fma_f32 v[26:27], v[80:81], v[26:27], v[30:31]
	v_pk_fma_f32 v[30:31], v[82:83], v[8:9], v[32:33]
	v_pk_fma_f32 v[26:27], v[82:83], v[28:29], v[26:27]
	s_waitcnt lgkmcnt(9)
	v_pk_fma_f32 v[28:29], v[84:85], v[14:15], v[30:31]
	v_pk_fma_f32 v[22:23], v[84:85], v[22:23], v[26:27]
	v_pk_fma_f32 v[26:27], v[86:87], v[16:17], v[28:29]
	v_pk_fma_f32 v[22:23], v[86:87], v[24:25], v[22:23]
	s_waitcnt lgkmcnt(8)
	v_pk_fma_f32 v[24:25], v[88:89], v[10:11], v[26:27]
	v_add_u32_e32 v98, s7, v97
	v_mov_b32_e32 v70, s7
	v_pk_fma_f32 v[18:19], v[88:89], v[18:19], v[22:23]
	v_pk_fma_f32 v[22:23], v[90:91], v[12:13], v[24:25]
	ds_read_b32 v0, v98
	ds_read_b96 v[70:72], v70 offset:1568
	v_pk_fma_f32 v[18:19], v[90:91], v[20:21], v[18:19]
	v_add_f32_e32 v20, v22, v23
	v_add_f32_e32 v18, v18, v19
	s_nop 0
	v_add_f32_dpp v20, v20, v20 quad_perm:[1,0,3,2] row_mask:0xf bank_mask:0xf bound_ctrl:1
	v_add_f32_dpp v19, v18, v18 quad_perm:[1,0,3,2] row_mask:0xf bank_mask:0xf bound_ctrl:1
	s_nop 0
	v_add_f32_dpp v20, v20, v20 quad_perm:[2,3,0,1] row_mask:0xf bank_mask:0xf bound_ctrl:1
	v_fma_f32 v18, -v37, v20, v73
	v_mul_f32_e32 v18, v35, v18
	v_add_f32_dpp v19, v19, v19 quad_perm:[2,3,0,1] row_mask:0xf bank_mask:0xf bound_ctrl:1
	v_mul_f32_e32 v20, v37, v19
	v_pk_fma_f32 v[20:21], v[36:37], v[18:19], v[20:21] op_sel_hi:[1,1,0]
	s_ashr_i32 s19, s18, 31
	v_bfe_u32 v19, v20, 16, 1
	s_lshl_b64 s[20:21], s[18:19], 9
	v_add3_u32 v19, v20, v19, s28
	v_lshl_add_u64 v[20:21], v[92:93], 0, s[20:21]
	global_store_short_d16_hi v[20:21], v19, off
	v_pk_mul_f32 v[20:21], v[74:75], v[36:37] op_sel:[0,1]
	s_nop 0
	v_pk_fma_f32 v[74:75], v[2:3], v[18:19], v[20:21] op_sel_hi:[1,0,1]
	v_pk_mul_f32 v[2:3], v[78:79], v[36:37] op_sel:[0,1]
	s_waitcnt lgkmcnt(9)
	v_pk_fma_f32 v[66:67], v[74:75], v[66:67], 0 op_sel_hi:[1,1,0]
	v_pk_fma_f32 v[78:79], v[4:5], v[18:19], v[2:3] op_sel_hi:[1,0,1]
	v_pk_mul_f32 v[2:3], v[80:81], v[36:37] op_sel:[0,1]
	v_pk_fma_f32 v[66:67], v[78:79], v[68:69], v[66:67]
	v_pk_fma_f32 v[80:81], v[6:7], v[18:19], v[2:3] op_sel_hi:[1,0,1]
	v_pk_mul_f32 v[2:3], v[82:83], v[36:37] op_sel:[0,1]
	s_waitcnt lgkmcnt(8)
	v_pk_fma_f32 v[62:63], v[80:81], v[62:63], v[66:67]
	v_pk_fma_f32 v[82:83], v[8:9], v[18:19], v[2:3] op_sel_hi:[1,0,1]
	v_pk_mul_f32 v[2:3], v[84:85], v[36:37] op_sel:[0,1]
	v_pk_fma_f32 v[62:63], v[82:83], v[64:65], v[62:63]
	v_pk_fma_f32 v[84:85], v[14:15], v[18:19], v[2:3] op_sel_hi:[1,0,1]
	v_pk_mul_f32 v[2:3], v[86:87], v[36:37] op_sel:[0,1]
	s_waitcnt lgkmcnt(7)
	v_pk_fma_f32 v[58:59], v[84:85], v[58:59], v[62:63]
	v_pk_fma_f32 v[86:87], v[16:17], v[18:19], v[2:3] op_sel_hi:[1,0,1]
	v_pk_mul_f32 v[2:3], v[88:89], v[36:37] op_sel:[0,1]
	v_pk_fma_f32 v[58:59], v[86:87], v[60:61], v[58:59]
	v_pk_fma_f32 v[88:89], v[10:11], v[18:19], v[2:3] op_sel_hi:[1,0,1]
	v_pk_mul_f32 v[2:3], v[90:91], v[36:37] op_sel:[0,1]
	s_waitcnt lgkmcnt(6)
	v_pk_fma_f32 v[54:55], v[88:89], v[54:55], v[58:59]
	v_pk_fma_f32 v[90:91], v[12:13], v[18:19], v[2:3] op_sel_hi:[1,0,1]
	ds_read_b128 v[30:33], v34 offset:1600
	ds_read_b128 v[26:29], v34 offset:1616
	ds_read_b128 v[22:25], v34 offset:1632
	ds_read_b128 v[18:21], v34 offset:1648
	ds_read_b128 v[2:5], v34 offset:1856
	ds_read_b128 v[6:9], v34 offset:1872
	ds_read_b128 v[14:17], v34 offset:1888
	ds_read_b128 v[10:13], v34 offset:1904
	v_mov_b32_e32 v34, s7
	ds_read_b32 v73, v98 offset:800
	ds_read_b96 v[34:36], v34 offset:2368
	s_waitcnt lgkmcnt(14)
	v_pk_fma_f32 v[98:99], v[74:75], v[50:51], 0 op_sel_hi:[1,1,0]
	v_pk_fma_f32 v[54:55], v[90:91], v[56:57], v[54:55]
	v_pk_fma_f32 v[98:99], v[78:79], v[52:53], v[98:99]
	s_nop 0
	v_pk_fma_f32 v[68:69], v[80:81], v[46:47], v[98:99]
	s_nop 0
	v_pk_fma_f32 v[66:67], v[82:83], v[48:49], v[68:69]
	s_waitcnt lgkmcnt(13)
	v_pk_fma_f32 v[64:65], v[84:85], v[42:43], v[66:67]
	s_nop 0
	v_pk_fma_f32 v[62:63], v[86:87], v[44:45], v[64:65]
	s_waitcnt lgkmcnt(12)
	v_pk_fma_f32 v[60:61], v[88:89], v[38:39], v[62:63]
	s_nop 0
	v_pk_fma_f32 v[58:59], v[90:91], v[40:41], v[60:61]
	s_nop 0
	v_add_f32_e32 v37, v58, v59
	s_nop 1
	v_add_f32_dpp v37, v37, v37 quad_perm:[1,0,3,2] row_mask:0xf bank_mask:0xf bound_ctrl:1
	s_nop 1
	v_add_f32_dpp v56, v37, v37 quad_perm:[2,3,0,1] row_mask:0xf bank_mask:0xf bound_ctrl:1
	v_add_f32_e32 v37, v54, v55
	s_waitcnt lgkmcnt(10)
	v_fma_f32 v0, -v70, v56, v0
	v_mul_f32_e32 v0, v71, v0
	v_add_f32_dpp v37, v37, v37 quad_perm:[1,0,3,2] row_mask:0xf bank_mask:0xf bound_ctrl:1
	s_nop 1
	v_add_f32_dpp v54, v37, v37 quad_perm:[2,3,0,1] row_mask:0xf bank_mask:0xf bound_ctrl:1
	v_mov_b32_e32 v71, v72
	v_mov_b32_e32 v55, v0
	v_mul_f32_e32 v56, v72, v0
	s_add_i32 s20, s24, s18
	v_pk_fma_f32 v[54:55], v[70:71], v[54:55], v[56:57] op_sel_hi:[1,1,0]
	s_ashr_i32 s21, s20, 31
	v_bfe_u32 v37, v54, 16, 1
	s_lshl_b64 s[20:21], s[20:21], 9
	v_add3_u32 v37, v54, v37, s28
	v_lshl_add_u64 v[54:55], v[92:93], 0, s[20:21]
	global_store_short_d16_hi v[54:55], v37, off
	v_pk_mul_f32 v[54:55], v[70:71], v[74:75] op_sel_hi:[0,1]
	v_pk_fma_f32 v[74:75], v[50:51], v[0:1], v[54:55] op_sel_hi:[1,0,1]
	v_pk_mul_f32 v[50:51], v[70:71], v[78:79] op_sel_hi:[0,1]
	v_pk_fma_f32 v[78:79], v[52:53], v[0:1], v[50:51] op_sel_hi:[1,0,1]
	v_pk_mul_f32 v[50:51], v[70:71], v[80:81] op_sel_hi:[0,1]
	v_pk_fma_f32 v[80:81], v[46:47], v[0:1], v[50:51] op_sel_hi:[1,0,1]
	v_pk_mul_f32 v[46:47], v[70:71], v[82:83] op_sel_hi:[0,1]
	v_pk_fma_f32 v[82:83], v[48:49], v[0:1], v[46:47] op_sel_hi:[1,0,1]
	v_pk_mul_f32 v[46:47], v[70:71], v[84:85] op_sel_hi:[0,1]
	v_pk_fma_f32 v[84:85], v[42:43], v[0:1], v[46:47] op_sel_hi:[1,0,1]
	v_pk_mul_f32 v[42:43], v[70:71], v[86:87] op_sel_hi:[0,1]
	v_pk_fma_f32 v[86:87], v[44:45], v[0:1], v[42:43] op_sel_hi:[1,0,1]
	v_pk_mul_f32 v[42:43], v[70:71], v[88:89] op_sel_hi:[0,1]
	v_pk_fma_f32 v[88:89], v[38:39], v[0:1], v[42:43] op_sel_hi:[1,0,1]
	v_pk_mul_f32 v[38:39], v[70:71], v[90:91] op_sel_hi:[0,1]
	s_add_i32 s18, s18, s25
	s_add_i32 s10, s10, 2
	s_addk_i32 s7, 0x640
	v_pk_fma_f32 v[90:91], v[40:41], v[0:1], v[38:39] op_sel_hi:[1,0,1]
	s_waitcnt lgkmcnt(5)
	v_pk_fma_f32 v[100:101], v[74:75], v[2:3], 0 op_sel_hi:[1,1,0]
	s_waitcnt lgkmcnt(0)
	v_mov_b32_e32 v37, v34
	v_add_u32_e32 v34, s7, v94
	v_pk_fma_f32 v[30:31], v[74:75], v[30:31], 0 op_sel_hi:[1,1,0]
	v_pk_fma_f32 v[100:101], v[78:79], v[4:5], v[100:101]
	ds_read_b128 v[66:69], v34 offset:800
	ds_read_b128 v[62:65], v34 offset:816
	ds_read_b128 v[58:61], v34 offset:832
	ds_read_b128 v[54:57], v34 offset:848
	ds_read_b128 v[50:53], v34 offset:1056
	ds_read_b128 v[46:49], v34 offset:1072
	ds_read_b128 v[42:45], v34 offset:1088
	ds_read_b128 v[38:41], v34 offset:1104
	v_pk_fma_f32 v[30:31], v[78:79], v[32:33], v[30:31]
	v_pk_fma_f32 v[32:33], v[80:81], v[6:7], v[100:101]
	v_pk_fma_f32 v[26:27], v[80:81], v[26:27], v[30:31]
	v_pk_fma_f32 v[30:31], v[82:83], v[8:9], v[32:33]
	v_pk_fma_f32 v[26:27], v[82:83], v[28:29], v[26:27]
	s_waitcnt lgkmcnt(9)
	v_pk_fma_f32 v[28:29], v[84:85], v[14:15], v[30:31]
	v_pk_fma_f32 v[22:23], v[84:85], v[22:23], v[26:27]
	v_pk_fma_f32 v[26:27], v[86:87], v[16:17], v[28:29]
	v_pk_fma_f32 v[22:23], v[86:87], v[24:25], v[22:23]
	s_waitcnt lgkmcnt(8)
	v_pk_fma_f32 v[24:25], v[88:89], v[10:11], v[26:27]
	v_add_u32_e32 v98, s7, v97
	v_mov_b32_e32 v70, s7
	v_pk_fma_f32 v[18:19], v[88:89], v[18:19], v[22:23]
	v_pk_fma_f32 v[22:23], v[90:91], v[12:13], v[24:25]
	ds_read_b32 v0, v98
	ds_read_b96 v[70:72], v70 offset:1568
	v_pk_fma_f32 v[18:19], v[90:91], v[20:21], v[18:19]
	v_add_f32_e32 v20, v22, v23
	v_add_f32_e32 v18, v18, v19
	s_nop 0
	v_add_f32_dpp v20, v20, v20 quad_perm:[1,0,3,2] row_mask:0xf bank_mask:0xf bound_ctrl:1
	v_add_f32_dpp v19, v18, v18 quad_perm:[1,0,3,2] row_mask:0xf bank_mask:0xf bound_ctrl:1
	s_nop 0
	v_add_f32_dpp v20, v20, v20 quad_perm:[2,3,0,1] row_mask:0xf bank_mask:0xf bound_ctrl:1
	v_fma_f32 v18, -v37, v20, v73
	v_mul_f32_e32 v18, v35, v18
	v_add_f32_dpp v19, v19, v19 quad_perm:[2,3,0,1] row_mask:0xf bank_mask:0xf bound_ctrl:1
	v_mul_f32_e32 v20, v37, v19
	v_pk_fma_f32 v[20:21], v[36:37], v[18:19], v[20:21] op_sel_hi:[1,1,0]
	s_ashr_i32 s19, s18, 31
	v_bfe_u32 v19, v20, 16, 1
	s_lshl_b64 s[20:21], s[18:19], 9
	v_add3_u32 v19, v20, v19, s28
	v_lshl_add_u64 v[20:21], v[92:93], 0, s[20:21]
	global_store_short_d16_hi v[20:21], v19, off
	v_pk_mul_f32 v[20:21], v[74:75], v[36:37] op_sel:[0,1]
	s_nop 0
	v_pk_fma_f32 v[74:75], v[2:3], v[18:19], v[20:21] op_sel_hi:[1,0,1]
	v_pk_mul_f32 v[2:3], v[78:79], v[36:37] op_sel:[0,1]
	s_waitcnt lgkmcnt(9)
	v_pk_fma_f32 v[66:67], v[74:75], v[66:67], 0 op_sel_hi:[1,1,0]
	v_pk_fma_f32 v[78:79], v[4:5], v[18:19], v[2:3] op_sel_hi:[1,0,1]
	v_pk_mul_f32 v[2:3], v[80:81], v[36:37] op_sel:[0,1]
	v_pk_fma_f32 v[66:67], v[78:79], v[68:69], v[66:67]
	v_pk_fma_f32 v[80:81], v[6:7], v[18:19], v[2:3] op_sel_hi:[1,0,1]
	v_pk_mul_f32 v[2:3], v[82:83], v[36:37] op_sel:[0,1]
	s_waitcnt lgkmcnt(8)
	v_pk_fma_f32 v[62:63], v[80:81], v[62:63], v[66:67]
	v_pk_fma_f32 v[82:83], v[8:9], v[18:19], v[2:3] op_sel_hi:[1,0,1]
	v_pk_mul_f32 v[2:3], v[84:85], v[36:37] op_sel:[0,1]
	v_pk_fma_f32 v[62:63], v[82:83], v[64:65], v[62:63]
	v_pk_fma_f32 v[84:85], v[14:15], v[18:19], v[2:3] op_sel_hi:[1,0,1]
	v_pk_mul_f32 v[2:3], v[86:87], v[36:37] op_sel:[0,1]
	s_waitcnt lgkmcnt(7)
	v_pk_fma_f32 v[58:59], v[84:85], v[58:59], v[62:63]
	v_pk_fma_f32 v[86:87], v[16:17], v[18:19], v[2:3] op_sel_hi:[1,0,1]
	v_pk_mul_f32 v[2:3], v[88:89], v[36:37] op_sel:[0,1]
	v_pk_fma_f32 v[58:59], v[86:87], v[60:61], v[58:59]
	v_pk_fma_f32 v[88:89], v[10:11], v[18:19], v[2:3] op_sel_hi:[1,0,1]
	v_pk_mul_f32 v[2:3], v[90:91], v[36:37] op_sel:[0,1]
	s_waitcnt lgkmcnt(6)
	v_pk_fma_f32 v[54:55], v[88:89], v[54:55], v[58:59]
	v_pk_fma_f32 v[90:91], v[12:13], v[18:19], v[2:3] op_sel_hi:[1,0,1]
	ds_read_b128 v[30:33], v34 offset:1600
	ds_read_b128 v[26:29], v34 offset:1616
	ds_read_b128 v[22:25], v34 offset:1632
	ds_read_b128 v[18:21], v34 offset:1648
	ds_read_b128 v[2:5], v34 offset:1856
	ds_read_b128 v[6:9], v34 offset:1872
	ds_read_b128 v[14:17], v34 offset:1888
	ds_read_b128 v[10:13], v34 offset:1904
	v_mov_b32_e32 v34, s7
	ds_read_b32 v73, v98 offset:800
	ds_read_b96 v[34:36], v34 offset:2368
	s_waitcnt lgkmcnt(14)
	v_pk_fma_f32 v[98:99], v[74:75], v[50:51], 0 op_sel_hi:[1,1,0]
	v_pk_fma_f32 v[54:55], v[90:91], v[56:57], v[54:55]
	v_pk_fma_f32 v[98:99], v[78:79], v[52:53], v[98:99]
	s_nop 0
	v_pk_fma_f32 v[68:69], v[80:81], v[46:47], v[98:99]
	s_nop 0
	v_pk_fma_f32 v[66:67], v[82:83], v[48:49], v[68:69]
	s_waitcnt lgkmcnt(13)
	v_pk_fma_f32 v[64:65], v[84:85], v[42:43], v[66:67]
	s_nop 0
	v_pk_fma_f32 v[62:63], v[86:87], v[44:45], v[64:65]
	s_waitcnt lgkmcnt(12)
	v_pk_fma_f32 v[60:61], v[88:89], v[38:39], v[62:63]
	s_nop 0
	v_pk_fma_f32 v[58:59], v[90:91], v[40:41], v[60:61]
	s_nop 0
	v_add_f32_e32 v37, v58, v59
	s_nop 1
	v_add_f32_dpp v37, v37, v37 quad_perm:[1,0,3,2] row_mask:0xf bank_mask:0xf bound_ctrl:1
	s_nop 1
	v_add_f32_dpp v56, v37, v37 quad_perm:[2,3,0,1] row_mask:0xf bank_mask:0xf bound_ctrl:1
	v_add_f32_e32 v37, v54, v55
	s_waitcnt lgkmcnt(10)
	v_fma_f32 v0, -v70, v56, v0
	v_mul_f32_e32 v0, v71, v0
	v_add_f32_dpp v37, v37, v37 quad_perm:[1,0,3,2] row_mask:0xf bank_mask:0xf bound_ctrl:1
	s_nop 1
	v_add_f32_dpp v54, v37, v37 quad_perm:[2,3,0,1] row_mask:0xf bank_mask:0xf bound_ctrl:1
	v_mov_b32_e32 v71, v72
	v_mov_b32_e32 v55, v0
	v_mul_f32_e32 v56, v72, v0
	s_add_i32 s20, s24, s18
	v_pk_fma_f32 v[54:55], v[70:71], v[54:55], v[56:57] op_sel_hi:[1,1,0]
	s_ashr_i32 s21, s20, 31
	v_bfe_u32 v37, v54, 16, 1
	s_lshl_b64 s[20:21], s[20:21], 9
	v_add3_u32 v37, v54, v37, s28
	v_lshl_add_u64 v[54:55], v[92:93], 0, s[20:21]
	global_store_short_d16_hi v[54:55], v37, off
	v_pk_mul_f32 v[54:55], v[70:71], v[74:75] op_sel_hi:[0,1]
	v_pk_fma_f32 v[74:75], v[50:51], v[0:1], v[54:55] op_sel_hi:[1,0,1]
	v_pk_mul_f32 v[50:51], v[70:71], v[78:79] op_sel_hi:[0,1]
	v_pk_fma_f32 v[78:79], v[52:53], v[0:1], v[50:51] op_sel_hi:[1,0,1]
	v_pk_mul_f32 v[50:51], v[70:71], v[80:81] op_sel_hi:[0,1]
	v_pk_fma_f32 v[80:81], v[46:47], v[0:1], v[50:51] op_sel_hi:[1,0,1]
	v_pk_mul_f32 v[46:47], v[70:71], v[82:83] op_sel_hi:[0,1]
	v_pk_fma_f32 v[82:83], v[48:49], v[0:1], v[46:47] op_sel_hi:[1,0,1]
	v_pk_mul_f32 v[46:47], v[70:71], v[84:85] op_sel_hi:[0,1]
	v_pk_fma_f32 v[84:85], v[42:43], v[0:1], v[46:47] op_sel_hi:[1,0,1]
	v_pk_mul_f32 v[42:43], v[70:71], v[86:87] op_sel_hi:[0,1]
	v_pk_fma_f32 v[86:87], v[44:45], v[0:1], v[42:43] op_sel_hi:[1,0,1]
	v_pk_mul_f32 v[42:43], v[70:71], v[88:89] op_sel_hi:[0,1]
	v_pk_fma_f32 v[88:89], v[38:39], v[0:1], v[42:43] op_sel_hi:[1,0,1]
	v_pk_mul_f32 v[38:39], v[70:71], v[90:91] op_sel_hi:[0,1]
	s_add_i32 s18, s18, s25
	s_add_i32 s10, s10, 2
	s_addk_i32 s7, 0x640
	v_pk_fma_f32 v[90:91], v[40:41], v[0:1], v[38:39] op_sel_hi:[1,0,1]
	s_waitcnt lgkmcnt(5)
	v_pk_fma_f32 v[100:101], v[74:75], v[2:3], 0 op_sel_hi:[1,1,0]
	s_waitcnt lgkmcnt(0)
	v_mov_b32_e32 v37, v34
	v_add_u32_e32 v34, s7, v94
	v_pk_fma_f32 v[30:31], v[74:75], v[30:31], 0 op_sel_hi:[1,1,0]
	v_pk_fma_f32 v[100:101], v[78:79], v[4:5], v[100:101]
	ds_read_b128 v[66:69], v34 offset:800
	ds_read_b128 v[62:65], v34 offset:816
	ds_read_b128 v[58:61], v34 offset:832
	ds_read_b128 v[54:57], v34 offset:848
	ds_read_b128 v[50:53], v34 offset:1056
	ds_read_b128 v[46:49], v34 offset:1072
	ds_read_b128 v[42:45], v34 offset:1088
	ds_read_b128 v[38:41], v34 offset:1104
	v_pk_fma_f32 v[30:31], v[78:79], v[32:33], v[30:31]
	v_pk_fma_f32 v[32:33], v[80:81], v[6:7], v[100:101]
	v_pk_fma_f32 v[26:27], v[80:81], v[26:27], v[30:31]
	v_pk_fma_f32 v[30:31], v[82:83], v[8:9], v[32:33]
	v_pk_fma_f32 v[26:27], v[82:83], v[28:29], v[26:27]
	s_waitcnt lgkmcnt(9)
	v_pk_fma_f32 v[28:29], v[84:85], v[14:15], v[30:31]
	v_pk_fma_f32 v[22:23], v[84:85], v[22:23], v[26:27]
	v_pk_fma_f32 v[26:27], v[86:87], v[16:17], v[28:29]
	v_pk_fma_f32 v[22:23], v[86:87], v[24:25], v[22:23]
	s_waitcnt lgkmcnt(8)
	v_pk_fma_f32 v[24:25], v[88:89], v[10:11], v[26:27]
	v_add_u32_e32 v98, s7, v97
	v_mov_b32_e32 v70, s7
	v_pk_fma_f32 v[18:19], v[88:89], v[18:19], v[22:23]
	v_pk_fma_f32 v[22:23], v[90:91], v[12:13], v[24:25]
	ds_read_b32 v0, v98
	ds_read_b96 v[70:72], v70 offset:1568
	v_pk_fma_f32 v[18:19], v[90:91], v[20:21], v[18:19]
	v_add_f32_e32 v20, v22, v23
	v_add_f32_e32 v18, v18, v19
	s_nop 0
	v_add_f32_dpp v20, v20, v20 quad_perm:[1,0,3,2] row_mask:0xf bank_mask:0xf bound_ctrl:1
	v_add_f32_dpp v19, v18, v18 quad_perm:[1,0,3,2] row_mask:0xf bank_mask:0xf bound_ctrl:1
	s_nop 0
	v_add_f32_dpp v20, v20, v20 quad_perm:[2,3,0,1] row_mask:0xf bank_mask:0xf bound_ctrl:1
	v_fma_f32 v18, -v37, v20, v73
	v_mul_f32_e32 v18, v35, v18
	v_add_f32_dpp v19, v19, v19 quad_perm:[2,3,0,1] row_mask:0xf bank_mask:0xf bound_ctrl:1
	v_mul_f32_e32 v20, v37, v19
	v_pk_fma_f32 v[20:21], v[36:37], v[18:19], v[20:21] op_sel_hi:[1,1,0]
	s_ashr_i32 s19, s18, 31
	v_bfe_u32 v19, v20, 16, 1
	s_lshl_b64 s[20:21], s[18:19], 9
	v_add3_u32 v19, v20, v19, s28
	v_lshl_add_u64 v[20:21], v[92:93], 0, s[20:21]
	global_store_short_d16_hi v[20:21], v19, off
	v_pk_mul_f32 v[20:21], v[74:75], v[36:37] op_sel:[0,1]
	s_nop 0
	v_pk_fma_f32 v[74:75], v[2:3], v[18:19], v[20:21] op_sel_hi:[1,0,1]
	v_pk_mul_f32 v[2:3], v[78:79], v[36:37] op_sel:[0,1]
	s_waitcnt lgkmcnt(9)
	v_pk_fma_f32 v[66:67], v[74:75], v[66:67], 0 op_sel_hi:[1,1,0]
	v_pk_fma_f32 v[78:79], v[4:5], v[18:19], v[2:3] op_sel_hi:[1,0,1]
	v_pk_mul_f32 v[2:3], v[80:81], v[36:37] op_sel:[0,1]
	v_pk_fma_f32 v[66:67], v[78:79], v[68:69], v[66:67]
	v_pk_fma_f32 v[80:81], v[6:7], v[18:19], v[2:3] op_sel_hi:[1,0,1]
	v_pk_mul_f32 v[2:3], v[82:83], v[36:37] op_sel:[0,1]
	s_waitcnt lgkmcnt(8)
	v_pk_fma_f32 v[62:63], v[80:81], v[62:63], v[66:67]
	v_pk_fma_f32 v[82:83], v[8:9], v[18:19], v[2:3] op_sel_hi:[1,0,1]
	v_pk_mul_f32 v[2:3], v[84:85], v[36:37] op_sel:[0,1]
	v_pk_fma_f32 v[62:63], v[82:83], v[64:65], v[62:63]
	v_pk_fma_f32 v[84:85], v[14:15], v[18:19], v[2:3] op_sel_hi:[1,0,1]
	v_pk_mul_f32 v[2:3], v[86:87], v[36:37] op_sel:[0,1]
	s_waitcnt lgkmcnt(7)
	v_pk_fma_f32 v[58:59], v[84:85], v[58:59], v[62:63]
	v_pk_fma_f32 v[86:87], v[16:17], v[18:19], v[2:3] op_sel_hi:[1,0,1]
	v_pk_mul_f32 v[2:3], v[88:89], v[36:37] op_sel:[0,1]
	v_pk_fma_f32 v[58:59], v[86:87], v[60:61], v[58:59]
	v_pk_fma_f32 v[88:89], v[10:11], v[18:19], v[2:3] op_sel_hi:[1,0,1]
	v_pk_mul_f32 v[2:3], v[90:91], v[36:37] op_sel:[0,1]
	s_waitcnt lgkmcnt(6)
	v_pk_fma_f32 v[54:55], v[88:89], v[54:55], v[58:59]
	v_pk_fma_f32 v[90:91], v[12:13], v[18:19], v[2:3] op_sel_hi:[1,0,1]
	ds_read_b128 v[30:33], v34 offset:1600
	ds_read_b128 v[26:29], v34 offset:1616
	ds_read_b128 v[22:25], v34 offset:1632
	ds_read_b128 v[18:21], v34 offset:1648
	ds_read_b128 v[2:5], v34 offset:1856
	ds_read_b128 v[6:9], v34 offset:1872
	ds_read_b128 v[14:17], v34 offset:1888
	ds_read_b128 v[10:13], v34 offset:1904
	v_mov_b32_e32 v34, s7
	ds_read_b32 v73, v98 offset:800
	ds_read_b96 v[34:36], v34 offset:2368
	s_waitcnt lgkmcnt(14)
	v_pk_fma_f32 v[98:99], v[74:75], v[50:51], 0 op_sel_hi:[1,1,0]
	v_pk_fma_f32 v[54:55], v[90:91], v[56:57], v[54:55]
	v_pk_fma_f32 v[98:99], v[78:79], v[52:53], v[98:99]
	s_nop 0
	v_pk_fma_f32 v[68:69], v[80:81], v[46:47], v[98:99]
	s_nop 0
	v_pk_fma_f32 v[66:67], v[82:83], v[48:49], v[68:69]
	s_waitcnt lgkmcnt(13)
	v_pk_fma_f32 v[64:65], v[84:85], v[42:43], v[66:67]
	s_nop 0
	v_pk_fma_f32 v[62:63], v[86:87], v[44:45], v[64:65]
	s_waitcnt lgkmcnt(12)
	v_pk_fma_f32 v[60:61], v[88:89], v[38:39], v[62:63]
	s_nop 0
	v_pk_fma_f32 v[58:59], v[90:91], v[40:41], v[60:61]
	s_nop 0
	v_add_f32_e32 v37, v58, v59
	s_nop 1
	v_add_f32_dpp v37, v37, v37 quad_perm:[1,0,3,2] row_mask:0xf bank_mask:0xf bound_ctrl:1
	s_nop 1
	v_add_f32_dpp v56, v37, v37 quad_perm:[2,3,0,1] row_mask:0xf bank_mask:0xf bound_ctrl:1
	v_add_f32_e32 v37, v54, v55
	s_waitcnt lgkmcnt(10)
	v_fma_f32 v0, -v70, v56, v0
	v_mul_f32_e32 v0, v71, v0
	v_add_f32_dpp v37, v37, v37 quad_perm:[1,0,3,2] row_mask:0xf bank_mask:0xf bound_ctrl:1
	s_nop 1
	v_add_f32_dpp v54, v37, v37 quad_perm:[2,3,0,1] row_mask:0xf bank_mask:0xf bound_ctrl:1
	v_mov_b32_e32 v71, v72
	v_mov_b32_e32 v55, v0
	v_mul_f32_e32 v56, v72, v0
	s_add_i32 s20, s24, s18
	v_pk_fma_f32 v[54:55], v[70:71], v[54:55], v[56:57] op_sel_hi:[1,1,0]
	s_ashr_i32 s21, s20, 31
	v_bfe_u32 v37, v54, 16, 1
	s_lshl_b64 s[20:21], s[20:21], 9
	v_add3_u32 v37, v54, v37, s28
	v_lshl_add_u64 v[54:55], v[92:93], 0, s[20:21]
	global_store_short_d16_hi v[54:55], v37, off
	v_pk_mul_f32 v[54:55], v[70:71], v[74:75] op_sel_hi:[0,1]
	v_pk_fma_f32 v[74:75], v[50:51], v[0:1], v[54:55] op_sel_hi:[1,0,1]
	v_pk_mul_f32 v[50:51], v[70:71], v[78:79] op_sel_hi:[0,1]
	v_pk_fma_f32 v[78:79], v[52:53], v[0:1], v[50:51] op_sel_hi:[1,0,1]
	v_pk_mul_f32 v[50:51], v[70:71], v[80:81] op_sel_hi:[0,1]
	v_pk_fma_f32 v[80:81], v[46:47], v[0:1], v[50:51] op_sel_hi:[1,0,1]
	v_pk_mul_f32 v[46:47], v[70:71], v[82:83] op_sel_hi:[0,1]
	v_pk_fma_f32 v[82:83], v[48:49], v[0:1], v[46:47] op_sel_hi:[1,0,1]
	v_pk_mul_f32 v[46:47], v[70:71], v[84:85] op_sel_hi:[0,1]
	v_pk_fma_f32 v[84:85], v[42:43], v[0:1], v[46:47] op_sel_hi:[1,0,1]
	v_pk_mul_f32 v[42:43], v[70:71], v[86:87] op_sel_hi:[0,1]
	v_pk_fma_f32 v[86:87], v[44:45], v[0:1], v[42:43] op_sel_hi:[1,0,1]
	v_pk_mul_f32 v[42:43], v[70:71], v[88:89] op_sel_hi:[0,1]
	v_pk_fma_f32 v[88:89], v[38:39], v[0:1], v[42:43] op_sel_hi:[1,0,1]
	v_pk_mul_f32 v[38:39], v[70:71], v[90:91] op_sel_hi:[0,1]
	s_add_i32 s18, s18, s25
	s_add_i32 s10, s10, 2
	s_addk_i32 s7, 0x640
	v_pk_fma_f32 v[90:91], v[40:41], v[0:1], v[38:39] op_sel_hi:[1,0,1]
	s_waitcnt lgkmcnt(5)
	v_pk_fma_f32 v[100:101], v[74:75], v[2:3], 0 op_sel_hi:[1,1,0]
	s_waitcnt lgkmcnt(0)
	v_mov_b32_e32 v37, v34
	v_add_u32_e32 v34, s7, v94
	v_pk_fma_f32 v[30:31], v[74:75], v[30:31], 0 op_sel_hi:[1,1,0]
	v_pk_fma_f32 v[100:101], v[78:79], v[4:5], v[100:101]
	ds_read_b128 v[66:69], v34 offset:800
	ds_read_b128 v[62:65], v34 offset:816
	ds_read_b128 v[58:61], v34 offset:832
	ds_read_b128 v[54:57], v34 offset:848
	ds_read_b128 v[50:53], v34 offset:1056
	ds_read_b128 v[46:49], v34 offset:1072
	ds_read_b128 v[42:45], v34 offset:1088
	ds_read_b128 v[38:41], v34 offset:1104
	v_pk_fma_f32 v[30:31], v[78:79], v[32:33], v[30:31]
	v_pk_fma_f32 v[32:33], v[80:81], v[6:7], v[100:101]
	v_pk_fma_f32 v[26:27], v[80:81], v[26:27], v[30:31]
	v_pk_fma_f32 v[30:31], v[82:83], v[8:9], v[32:33]
	v_pk_fma_f32 v[26:27], v[82:83], v[28:29], v[26:27]
	s_waitcnt lgkmcnt(9)
	v_pk_fma_f32 v[28:29], v[84:85], v[14:15], v[30:31]
	v_pk_fma_f32 v[22:23], v[84:85], v[22:23], v[26:27]
	v_pk_fma_f32 v[26:27], v[86:87], v[16:17], v[28:29]
	v_pk_fma_f32 v[22:23], v[86:87], v[24:25], v[22:23]
	s_waitcnt lgkmcnt(8)
	v_pk_fma_f32 v[24:25], v[88:89], v[10:11], v[26:27]
	v_add_u32_e32 v98, s7, v97
	v_mov_b32_e32 v70, s7
	v_pk_fma_f32 v[18:19], v[88:89], v[18:19], v[22:23]
	v_pk_fma_f32 v[22:23], v[90:91], v[12:13], v[24:25]
	ds_read_b32 v0, v98
	ds_read_b96 v[70:72], v70 offset:1568
	v_pk_fma_f32 v[18:19], v[90:91], v[20:21], v[18:19]
	v_add_f32_e32 v20, v22, v23
	v_add_f32_e32 v18, v18, v19
	s_nop 0
	v_add_f32_dpp v20, v20, v20 quad_perm:[1,0,3,2] row_mask:0xf bank_mask:0xf bound_ctrl:1
	v_add_f32_dpp v19, v18, v18 quad_perm:[1,0,3,2] row_mask:0xf bank_mask:0xf bound_ctrl:1
	s_nop 0
	v_add_f32_dpp v20, v20, v20 quad_perm:[2,3,0,1] row_mask:0xf bank_mask:0xf bound_ctrl:1
	v_fma_f32 v18, -v37, v20, v73
	v_mul_f32_e32 v18, v35, v18
	v_add_f32_dpp v19, v19, v19 quad_perm:[2,3,0,1] row_mask:0xf bank_mask:0xf bound_ctrl:1
	v_mul_f32_e32 v20, v37, v19
	v_pk_fma_f32 v[20:21], v[36:37], v[18:19], v[20:21] op_sel_hi:[1,1,0]
	s_ashr_i32 s19, s18, 31
	v_bfe_u32 v19, v20, 16, 1
	s_lshl_b64 s[20:21], s[18:19], 9
	v_add3_u32 v19, v20, v19, s28
	v_lshl_add_u64 v[20:21], v[92:93], 0, s[20:21]
	global_store_short_d16_hi v[20:21], v19, off
	v_pk_mul_f32 v[20:21], v[74:75], v[36:37] op_sel:[0,1]
	s_nop 0
	v_pk_fma_f32 v[74:75], v[2:3], v[18:19], v[20:21] op_sel_hi:[1,0,1]
	v_pk_mul_f32 v[2:3], v[78:79], v[36:37] op_sel:[0,1]
	s_waitcnt lgkmcnt(9)
	v_pk_fma_f32 v[66:67], v[74:75], v[66:67], 0 op_sel_hi:[1,1,0]
	v_pk_fma_f32 v[78:79], v[4:5], v[18:19], v[2:3] op_sel_hi:[1,0,1]
	v_pk_mul_f32 v[2:3], v[80:81], v[36:37] op_sel:[0,1]
	v_pk_fma_f32 v[66:67], v[78:79], v[68:69], v[66:67]
	v_pk_fma_f32 v[80:81], v[6:7], v[18:19], v[2:3] op_sel_hi:[1,0,1]
	v_pk_mul_f32 v[2:3], v[82:83], v[36:37] op_sel:[0,1]
	s_waitcnt lgkmcnt(8)
	v_pk_fma_f32 v[62:63], v[80:81], v[62:63], v[66:67]
	v_pk_fma_f32 v[82:83], v[8:9], v[18:19], v[2:3] op_sel_hi:[1,0,1]
	v_pk_mul_f32 v[2:3], v[84:85], v[36:37] op_sel:[0,1]
	v_pk_fma_f32 v[62:63], v[82:83], v[64:65], v[62:63]
	v_pk_fma_f32 v[84:85], v[14:15], v[18:19], v[2:3] op_sel_hi:[1,0,1]
	v_pk_mul_f32 v[2:3], v[86:87], v[36:37] op_sel:[0,1]
	s_waitcnt lgkmcnt(7)
	v_pk_fma_f32 v[58:59], v[84:85], v[58:59], v[62:63]
	v_pk_fma_f32 v[86:87], v[16:17], v[18:19], v[2:3] op_sel_hi:[1,0,1]
	v_pk_mul_f32 v[2:3], v[88:89], v[36:37] op_sel:[0,1]
	v_pk_fma_f32 v[58:59], v[86:87], v[60:61], v[58:59]
	v_pk_fma_f32 v[88:89], v[10:11], v[18:19], v[2:3] op_sel_hi:[1,0,1]
	v_pk_mul_f32 v[2:3], v[90:91], v[36:37] op_sel:[0,1]
	s_waitcnt lgkmcnt(6)
	v_pk_fma_f32 v[54:55], v[88:89], v[54:55], v[58:59]
	v_pk_fma_f32 v[90:91], v[12:13], v[18:19], v[2:3] op_sel_hi:[1,0,1]
	ds_read_b128 v[30:33], v34 offset:1600
	ds_read_b128 v[26:29], v34 offset:1616
	ds_read_b128 v[22:25], v34 offset:1632
	ds_read_b128 v[18:21], v34 offset:1648
	ds_read_b128 v[2:5], v34 offset:1856
	ds_read_b128 v[6:9], v34 offset:1872
	ds_read_b128 v[14:17], v34 offset:1888
	ds_read_b128 v[10:13], v34 offset:1904
	v_mov_b32_e32 v34, s7
	ds_read_b32 v73, v98 offset:800
	ds_read_b96 v[34:36], v34 offset:2368
	s_waitcnt lgkmcnt(14)
	v_pk_fma_f32 v[98:99], v[74:75], v[50:51], 0 op_sel_hi:[1,1,0]
	v_pk_fma_f32 v[54:55], v[90:91], v[56:57], v[54:55]
	v_pk_fma_f32 v[98:99], v[78:79], v[52:53], v[98:99]
	s_nop 0
	v_pk_fma_f32 v[68:69], v[80:81], v[46:47], v[98:99]
	s_nop 0
	v_pk_fma_f32 v[66:67], v[82:83], v[48:49], v[68:69]
	s_waitcnt lgkmcnt(13)
	v_pk_fma_f32 v[64:65], v[84:85], v[42:43], v[66:67]
	s_nop 0
	v_pk_fma_f32 v[62:63], v[86:87], v[44:45], v[64:65]
	s_waitcnt lgkmcnt(12)
	v_pk_fma_f32 v[60:61], v[88:89], v[38:39], v[62:63]
	s_nop 0
	v_pk_fma_f32 v[58:59], v[90:91], v[40:41], v[60:61]
	s_nop 0
	v_add_f32_e32 v37, v58, v59
	s_nop 1
	v_add_f32_dpp v37, v37, v37 quad_perm:[1,0,3,2] row_mask:0xf bank_mask:0xf bound_ctrl:1
	s_nop 1
	v_add_f32_dpp v56, v37, v37 quad_perm:[2,3,0,1] row_mask:0xf bank_mask:0xf bound_ctrl:1
	v_add_f32_e32 v37, v54, v55
	s_waitcnt lgkmcnt(10)
	v_fma_f32 v0, -v70, v56, v0
	v_mul_f32_e32 v0, v71, v0
	v_add_f32_dpp v37, v37, v37 quad_perm:[1,0,3,2] row_mask:0xf bank_mask:0xf bound_ctrl:1
	s_nop 1
	v_add_f32_dpp v54, v37, v37 quad_perm:[2,3,0,1] row_mask:0xf bank_mask:0xf bound_ctrl:1
	v_mov_b32_e32 v71, v72
	v_mov_b32_e32 v55, v0
	v_mul_f32_e32 v56, v72, v0
	s_add_i32 s20, s24, s18
	v_pk_fma_f32 v[54:55], v[70:71], v[54:55], v[56:57] op_sel_hi:[1,1,0]
	s_ashr_i32 s21, s20, 31
	v_bfe_u32 v37, v54, 16, 1
	s_lshl_b64 s[20:21], s[20:21], 9
	v_add3_u32 v37, v54, v37, s28
	v_lshl_add_u64 v[54:55], v[92:93], 0, s[20:21]
	global_store_short_d16_hi v[54:55], v37, off
	v_pk_mul_f32 v[54:55], v[70:71], v[74:75] op_sel_hi:[0,1]
	v_pk_fma_f32 v[74:75], v[50:51], v[0:1], v[54:55] op_sel_hi:[1,0,1]
	v_pk_mul_f32 v[50:51], v[70:71], v[78:79] op_sel_hi:[0,1]
	v_pk_fma_f32 v[78:79], v[52:53], v[0:1], v[50:51] op_sel_hi:[1,0,1]
	v_pk_mul_f32 v[50:51], v[70:71], v[80:81] op_sel_hi:[0,1]
	v_pk_fma_f32 v[80:81], v[46:47], v[0:1], v[50:51] op_sel_hi:[1,0,1]
	v_pk_mul_f32 v[46:47], v[70:71], v[82:83] op_sel_hi:[0,1]
	v_pk_fma_f32 v[82:83], v[48:49], v[0:1], v[46:47] op_sel_hi:[1,0,1]
	v_pk_mul_f32 v[46:47], v[70:71], v[84:85] op_sel_hi:[0,1]
	v_pk_fma_f32 v[84:85], v[42:43], v[0:1], v[46:47] op_sel_hi:[1,0,1]
	v_pk_mul_f32 v[42:43], v[70:71], v[86:87] op_sel_hi:[0,1]
	v_pk_fma_f32 v[86:87], v[44:45], v[0:1], v[42:43] op_sel_hi:[1,0,1]
	v_pk_mul_f32 v[42:43], v[70:71], v[88:89] op_sel_hi:[0,1]
	v_pk_fma_f32 v[88:89], v[38:39], v[0:1], v[42:43] op_sel_hi:[1,0,1]
	v_pk_mul_f32 v[38:39], v[70:71], v[90:91] op_sel_hi:[0,1]
	s_add_i32 s18, s18, s25
	s_add_i32 s10, s10, 2
	s_addk_i32 s7, 0x640
	s_cmp_gt_u32 s10, 13
	v_pk_fma_f32 v[90:91], v[40:41], v[0:1], v[38:39] op_sel_hi:[1,0,1]
	s_cbranch_scc0 .LBB0_906

.LBB0_916:
	s_waitcnt lgkmcnt(5)
	v_pk_fma_f32 v[100:101], v[74:75], v[2:3], 0 op_sel_hi:[1,1,0]
	s_waitcnt lgkmcnt(0)
	v_mov_b32_e32 v37, v34
	v_add_u32_e32 v34, s7, v94
	v_pk_fma_f32 v[30:31], v[74:75], v[30:31], 0 op_sel_hi:[1,1,0]
	v_pk_fma_f32 v[100:101], v[78:79], v[4:5], v[100:101]
	ds_read_b128 v[66:69], v34
	ds_read_b128 v[62:65], v34 offset:16
	ds_read_b128 v[58:61], v34 offset:32
	ds_read_b128 v[54:57], v34 offset:48
	ds_read_b128 v[50:53], v34 offset:256
	ds_read_b128 v[46:49], v34 offset:272
	ds_read_b128 v[42:45], v34 offset:288
	ds_read_b128 v[38:41], v34 offset:304
	v_pk_fma_f32 v[30:31], v[78:79], v[32:33], v[30:31]
	v_pk_fma_f32 v[32:33], v[80:81], v[6:7], v[100:101]
	v_pk_fma_f32 v[26:27], v[80:81], v[26:27], v[30:31]
	v_pk_fma_f32 v[30:31], v[82:83], v[8:9], v[32:33]
	v_pk_fma_f32 v[26:27], v[82:83], v[28:29], v[26:27]
	s_waitcnt lgkmcnt(9)
	v_pk_fma_f32 v[28:29], v[84:85], v[14:15], v[30:31]
	v_pk_fma_f32 v[22:23], v[84:85], v[22:23], v[26:27]
	v_pk_fma_f32 v[26:27], v[86:87], v[16:17], v[28:29]
	v_pk_fma_f32 v[22:23], v[86:87], v[24:25], v[22:23]
	s_waitcnt lgkmcnt(8)
	v_pk_fma_f32 v[24:25], v[88:89], v[10:11], v[26:27]
	v_add_u32_e32 v98, s7, v96
	v_mov_b32_e32 v70, s7
	v_pk_fma_f32 v[18:19], v[88:89], v[18:19], v[22:23]
	v_pk_fma_f32 v[22:23], v[90:91], v[12:13], v[24:25]
	ds_read_b32 v0, v98 offset:512
	ds_read_b96 v[70:72], v70 offset:768
	v_pk_fma_f32 v[18:19], v[90:91], v[20:21], v[18:19]
	v_add_f32_e32 v20, v22, v23
	v_add_f32_e32 v18, v18, v19
	s_nop 0
	v_add_f32_dpp v20, v20, v20 quad_perm:[1,0,3,2] row_mask:0xf bank_mask:0xf bound_ctrl:1
	v_add_f32_dpp v19, v18, v18 quad_perm:[1,0,3,2] row_mask:0xf bank_mask:0xf bound_ctrl:1
	s_nop 0
	v_add_f32_dpp v20, v20, v20 quad_perm:[2,3,0,1] row_mask:0xf bank_mask:0xf bound_ctrl:1
	v_fma_f32 v18, -v37, v20, v73
	v_mul_f32_e32 v18, v35, v18
	v_add_f32_dpp v19, v19, v19 quad_perm:[2,3,0,1] row_mask:0xf bank_mask:0xf bound_ctrl:1
	v_mul_f32_e32 v20, v37, v19
	v_pk_fma_f32 v[20:21], v[36:37], v[18:19], v[20:21] op_sel_hi:[1,1,0]
	s_ashr_i32 s17, s16, 31
	v_bfe_u32 v19, v20, 16, 1
	s_lshl_b64 s[10:11], s[16:17], 9
	v_add3_u32 v19, v20, v19, s28
	v_lshl_add_u64 v[20:21], v[92:93], 0, s[10:11]
	global_store_short_d16_hi v[20:21], v19, off
	v_pk_mul_f32 v[20:21], v[74:75], v[36:37] op_sel:[0,1]
	s_nop 0
	v_pk_fma_f32 v[74:75], v[2:3], v[18:19], v[20:21] op_sel_hi:[1,0,1]
	v_pk_mul_f32 v[2:3], v[78:79], v[36:37] op_sel:[0,1]
	s_waitcnt lgkmcnt(9)
	v_pk_fma_f32 v[66:67], v[74:75], v[66:67], 0 op_sel_hi:[1,1,0]
	v_pk_fma_f32 v[78:79], v[4:5], v[18:19], v[2:3] op_sel_hi:[1,0,1]
	v_pk_mul_f32 v[2:3], v[80:81], v[36:37] op_sel:[0,1]
	v_pk_fma_f32 v[66:67], v[78:79], v[68:69], v[66:67]
	v_pk_fma_f32 v[80:81], v[6:7], v[18:19], v[2:3] op_sel_hi:[1,0,1]
	v_pk_mul_f32 v[2:3], v[82:83], v[36:37] op_sel:[0,1]
	s_waitcnt lgkmcnt(8)
	v_pk_fma_f32 v[62:63], v[80:81], v[62:63], v[66:67]
	v_pk_fma_f32 v[82:83], v[8:9], v[18:19], v[2:3] op_sel_hi:[1,0,1]
	v_pk_mul_f32 v[2:3], v[84:85], v[36:37] op_sel:[0,1]
	v_pk_fma_f32 v[62:63], v[82:83], v[64:65], v[62:63]
	v_pk_fma_f32 v[84:85], v[14:15], v[18:19], v[2:3] op_sel_hi:[1,0,1]
	v_pk_mul_f32 v[2:3], v[86:87], v[36:37] op_sel:[0,1]
	s_waitcnt lgkmcnt(7)
	v_pk_fma_f32 v[58:59], v[84:85], v[58:59], v[62:63]
	v_pk_fma_f32 v[86:87], v[16:17], v[18:19], v[2:3] op_sel_hi:[1,0,1]
	v_pk_mul_f32 v[2:3], v[88:89], v[36:37] op_sel:[0,1]
	v_pk_fma_f32 v[58:59], v[86:87], v[60:61], v[58:59]
	v_pk_fma_f32 v[88:89], v[10:11], v[18:19], v[2:3] op_sel_hi:[1,0,1]
	v_pk_mul_f32 v[2:3], v[90:91], v[36:37] op_sel:[0,1]
	s_waitcnt lgkmcnt(6)
	v_pk_fma_f32 v[54:55], v[88:89], v[54:55], v[58:59]
	v_pk_fma_f32 v[90:91], v[12:13], v[18:19], v[2:3] op_sel_hi:[1,0,1]
	ds_read_b128 v[30:33], v34 offset:800
	ds_read_b128 v[26:29], v34 offset:816
	ds_read_b128 v[22:25], v34 offset:832
	ds_read_b128 v[18:21], v34 offset:848
	ds_read_b128 v[2:5], v34 offset:1056
	ds_read_b128 v[6:9], v34 offset:1072
	ds_read_b128 v[14:17], v34 offset:1088
	ds_read_b128 v[10:13], v34 offset:1104
	v_mov_b32_e32 v34, s7
	ds_read_b32 v73, v98 offset:1312
	ds_read_b96 v[34:36], v34 offset:1568
	s_waitcnt lgkmcnt(14)
	v_pk_fma_f32 v[98:99], v[74:75], v[50:51], 0 op_sel_hi:[1,1,0]
	v_pk_fma_f32 v[54:55], v[90:91], v[56:57], v[54:55]
	v_pk_fma_f32 v[98:99], v[78:79], v[52:53], v[98:99]
	s_nop 0
	v_pk_fma_f32 v[68:69], v[80:81], v[46:47], v[98:99]
	s_nop 0
	v_pk_fma_f32 v[66:67], v[82:83], v[48:49], v[68:69]
	s_waitcnt lgkmcnt(13)
	v_pk_fma_f32 v[64:65], v[84:85], v[42:43], v[66:67]
	s_nop 0
	v_pk_fma_f32 v[62:63], v[86:87], v[44:45], v[64:65]
	s_waitcnt lgkmcnt(12)
	v_pk_fma_f32 v[60:61], v[88:89], v[38:39], v[62:63]
	s_nop 0
	v_pk_fma_f32 v[58:59], v[90:91], v[40:41], v[60:61]
	s_nop 0
	v_add_f32_e32 v37, v58, v59
	s_nop 1
	v_add_f32_dpp v37, v37, v37 quad_perm:[1,0,3,2] row_mask:0xf bank_mask:0xf bound_ctrl:1
	s_nop 1
	v_add_f32_dpp v56, v37, v37 quad_perm:[2,3,0,1] row_mask:0xf bank_mask:0xf bound_ctrl:1
	v_add_f32_e32 v37, v54, v55
	s_waitcnt lgkmcnt(10)
	v_fma_f32 v0, -v70, v56, v0
	v_mul_f32_e32 v0, v71, v0
	v_add_f32_dpp v37, v37, v37 quad_perm:[1,0,3,2] row_mask:0xf bank_mask:0xf bound_ctrl:1
	s_nop 1
	v_add_f32_dpp v54, v37, v37 quad_perm:[2,3,0,1] row_mask:0xf bank_mask:0xf bound_ctrl:1
	v_mov_b32_e32 v71, v72
	v_mov_b32_e32 v55, v0
	v_mul_f32_e32 v56, v72, v0
	s_add_i32 s10, s24, s16
	v_pk_fma_f32 v[54:55], v[70:71], v[54:55], v[56:57] op_sel_hi:[1,1,0]
	s_ashr_i32 s11, s10, 31
	v_bfe_u32 v37, v54, 16, 1
	s_lshl_b64 s[10:11], s[10:11], 9
	v_add3_u32 v37, v54, v37, s28
	v_lshl_add_u64 v[54:55], v[92:93], 0, s[10:11]
	global_store_short_d16_hi v[54:55], v37, off
	v_pk_mul_f32 v[54:55], v[70:71], v[74:75] op_sel_hi:[0,1]
	v_pk_fma_f32 v[74:75], v[50:51], v[0:1], v[54:55] op_sel_hi:[1,0,1]
	v_pk_mul_f32 v[50:51], v[70:71], v[78:79] op_sel_hi:[0,1]
	v_pk_fma_f32 v[78:79], v[52:53], v[0:1], v[50:51] op_sel_hi:[1,0,1]
	v_pk_mul_f32 v[50:51], v[70:71], v[80:81] op_sel_hi:[0,1]
	v_pk_fma_f32 v[80:81], v[46:47], v[0:1], v[50:51] op_sel_hi:[1,0,1]
	v_pk_mul_f32 v[46:47], v[70:71], v[82:83] op_sel_hi:[0,1]
	v_pk_fma_f32 v[82:83], v[48:49], v[0:1], v[46:47] op_sel_hi:[1,0,1]
	v_pk_mul_f32 v[46:47], v[70:71], v[84:85] op_sel_hi:[0,1]
	v_pk_fma_f32 v[84:85], v[42:43], v[0:1], v[46:47] op_sel_hi:[1,0,1]
	v_pk_mul_f32 v[42:43], v[70:71], v[86:87] op_sel_hi:[0,1]
	v_pk_fma_f32 v[86:87], v[44:45], v[0:1], v[42:43] op_sel_hi:[1,0,1]
	v_pk_mul_f32 v[42:43], v[70:71], v[88:89] op_sel_hi:[0,1]
	v_pk_fma_f32 v[88:89], v[38:39], v[0:1], v[42:43] op_sel_hi:[1,0,1]
	v_pk_mul_f32 v[38:39], v[70:71], v[90:91] op_sel_hi:[0,1]
	s_add_i32 s16, s16, s25
	s_add_i32 s6, s6, 2
	s_addk_i32 s7, 0x640
	v_pk_fma_f32 v[90:91], v[40:41], v[0:1], v[38:39] op_sel_hi:[1,0,1]
	s_waitcnt lgkmcnt(5)
	v_pk_fma_f32 v[100:101], v[74:75], v[2:3], 0 op_sel_hi:[1,1,0]
	s_waitcnt lgkmcnt(0)
	v_mov_b32_e32 v37, v34
	v_add_u32_e32 v34, s7, v94
	v_pk_fma_f32 v[30:31], v[74:75], v[30:31], 0 op_sel_hi:[1,1,0]
	v_pk_fma_f32 v[100:101], v[78:79], v[4:5], v[100:101]
	ds_read_b128 v[66:69], v34
	ds_read_b128 v[62:65], v34 offset:16
	ds_read_b128 v[58:61], v34 offset:32
	ds_read_b128 v[54:57], v34 offset:48
	ds_read_b128 v[50:53], v34 offset:256
	ds_read_b128 v[46:49], v34 offset:272
	ds_read_b128 v[42:45], v34 offset:288
	ds_read_b128 v[38:41], v34 offset:304
	v_pk_fma_f32 v[30:31], v[78:79], v[32:33], v[30:31]
	v_pk_fma_f32 v[32:33], v[80:81], v[6:7], v[100:101]
	v_pk_fma_f32 v[26:27], v[80:81], v[26:27], v[30:31]
	v_pk_fma_f32 v[30:31], v[82:83], v[8:9], v[32:33]
	v_pk_fma_f32 v[26:27], v[82:83], v[28:29], v[26:27]
	s_waitcnt lgkmcnt(9)
	v_pk_fma_f32 v[28:29], v[84:85], v[14:15], v[30:31]
	v_pk_fma_f32 v[22:23], v[84:85], v[22:23], v[26:27]
	v_pk_fma_f32 v[26:27], v[86:87], v[16:17], v[28:29]
	v_pk_fma_f32 v[22:23], v[86:87], v[24:25], v[22:23]
	s_waitcnt lgkmcnt(8)
	v_pk_fma_f32 v[24:25], v[88:89], v[10:11], v[26:27]
	v_add_u32_e32 v98, s7, v96
	v_mov_b32_e32 v70, s7
	v_pk_fma_f32 v[18:19], v[88:89], v[18:19], v[22:23]
	v_pk_fma_f32 v[22:23], v[90:91], v[12:13], v[24:25]
	ds_read_b32 v0, v98 offset:512
	ds_read_b96 v[70:72], v70 offset:768
	v_pk_fma_f32 v[18:19], v[90:91], v[20:21], v[18:19]
	v_add_f32_e32 v20, v22, v23
	v_add_f32_e32 v18, v18, v19
	s_nop 0
	v_add_f32_dpp v20, v20, v20 quad_perm:[1,0,3,2] row_mask:0xf bank_mask:0xf bound_ctrl:1
	v_add_f32_dpp v19, v18, v18 quad_perm:[1,0,3,2] row_mask:0xf bank_mask:0xf bound_ctrl:1
	s_nop 0
	v_add_f32_dpp v20, v20, v20 quad_perm:[2,3,0,1] row_mask:0xf bank_mask:0xf bound_ctrl:1
	v_fma_f32 v18, -v37, v20, v73
	v_mul_f32_e32 v18, v35, v18
	v_add_f32_dpp v19, v19, v19 quad_perm:[2,3,0,1] row_mask:0xf bank_mask:0xf bound_ctrl:1
	v_mul_f32_e32 v20, v37, v19
	v_pk_fma_f32 v[20:21], v[36:37], v[18:19], v[20:21] op_sel_hi:[1,1,0]
	s_ashr_i32 s17, s16, 31
	v_bfe_u32 v19, v20, 16, 1
	s_lshl_b64 s[10:11], s[16:17], 9
	v_add3_u32 v19, v20, v19, s28
	v_lshl_add_u64 v[20:21], v[92:93], 0, s[10:11]
	global_store_short_d16_hi v[20:21], v19, off
	v_pk_mul_f32 v[20:21], v[74:75], v[36:37] op_sel:[0,1]
	s_nop 0
	v_pk_fma_f32 v[74:75], v[2:3], v[18:19], v[20:21] op_sel_hi:[1,0,1]
	v_pk_mul_f32 v[2:3], v[78:79], v[36:37] op_sel:[0,1]
	s_waitcnt lgkmcnt(9)
	v_pk_fma_f32 v[66:67], v[74:75], v[66:67], 0 op_sel_hi:[1,1,0]
	v_pk_fma_f32 v[78:79], v[4:5], v[18:19], v[2:3] op_sel_hi:[1,0,1]
	v_pk_mul_f32 v[2:3], v[80:81], v[36:37] op_sel:[0,1]
	v_pk_fma_f32 v[66:67], v[78:79], v[68:69], v[66:67]
	v_pk_fma_f32 v[80:81], v[6:7], v[18:19], v[2:3] op_sel_hi:[1,0,1]
	v_pk_mul_f32 v[2:3], v[82:83], v[36:37] op_sel:[0,1]
	s_waitcnt lgkmcnt(8)
	v_pk_fma_f32 v[62:63], v[80:81], v[62:63], v[66:67]
	v_pk_fma_f32 v[82:83], v[8:9], v[18:19], v[2:3] op_sel_hi:[1,0,1]
	v_pk_mul_f32 v[2:3], v[84:85], v[36:37] op_sel:[0,1]
	v_pk_fma_f32 v[62:63], v[82:83], v[64:65], v[62:63]
	v_pk_fma_f32 v[84:85], v[14:15], v[18:19], v[2:3] op_sel_hi:[1,0,1]
	v_pk_mul_f32 v[2:3], v[86:87], v[36:37] op_sel:[0,1]
	s_waitcnt lgkmcnt(7)
	v_pk_fma_f32 v[58:59], v[84:85], v[58:59], v[62:63]
	v_pk_fma_f32 v[86:87], v[16:17], v[18:19], v[2:3] op_sel_hi:[1,0,1]
	v_pk_mul_f32 v[2:3], v[88:89], v[36:37] op_sel:[0,1]
	v_pk_fma_f32 v[58:59], v[86:87], v[60:61], v[58:59]
	v_pk_fma_f32 v[88:89], v[10:11], v[18:19], v[2:3] op_sel_hi:[1,0,1]
	v_pk_mul_f32 v[2:3], v[90:91], v[36:37] op_sel:[0,1]
	s_waitcnt lgkmcnt(6)
	v_pk_fma_f32 v[54:55], v[88:89], v[54:55], v[58:59]
	v_pk_fma_f32 v[90:91], v[12:13], v[18:19], v[2:3] op_sel_hi:[1,0,1]
	ds_read_b128 v[30:33], v34 offset:800
	ds_read_b128 v[26:29], v34 offset:816
	ds_read_b128 v[22:25], v34 offset:832
	ds_read_b128 v[18:21], v34 offset:848
	ds_read_b128 v[2:5], v34 offset:1056
	ds_read_b128 v[6:9], v34 offset:1072
	ds_read_b128 v[14:17], v34 offset:1088
	ds_read_b128 v[10:13], v34 offset:1104
	v_mov_b32_e32 v34, s7
	ds_read_b32 v73, v98 offset:1312
	ds_read_b96 v[34:36], v34 offset:1568
	s_waitcnt lgkmcnt(14)
	v_pk_fma_f32 v[98:99], v[74:75], v[50:51], 0 op_sel_hi:[1,1,0]
	v_pk_fma_f32 v[54:55], v[90:91], v[56:57], v[54:55]
	v_pk_fma_f32 v[98:99], v[78:79], v[52:53], v[98:99]
	s_nop 0
	v_pk_fma_f32 v[68:69], v[80:81], v[46:47], v[98:99]
	s_nop 0
	v_pk_fma_f32 v[66:67], v[82:83], v[48:49], v[68:69]
	s_waitcnt lgkmcnt(13)
	v_pk_fma_f32 v[64:65], v[84:85], v[42:43], v[66:67]
	s_nop 0
	v_pk_fma_f32 v[62:63], v[86:87], v[44:45], v[64:65]
	s_waitcnt lgkmcnt(12)
	v_pk_fma_f32 v[60:61], v[88:89], v[38:39], v[62:63]
	s_nop 0
	v_pk_fma_f32 v[58:59], v[90:91], v[40:41], v[60:61]
	s_nop 0
	v_add_f32_e32 v37, v58, v59
	s_nop 1
	v_add_f32_dpp v37, v37, v37 quad_perm:[1,0,3,2] row_mask:0xf bank_mask:0xf bound_ctrl:1
	s_nop 1
	v_add_f32_dpp v56, v37, v37 quad_perm:[2,3,0,1] row_mask:0xf bank_mask:0xf bound_ctrl:1
	v_add_f32_e32 v37, v54, v55
	s_waitcnt lgkmcnt(10)
	v_fma_f32 v0, -v70, v56, v0
	v_mul_f32_e32 v0, v71, v0
	v_add_f32_dpp v37, v37, v37 quad_perm:[1,0,3,2] row_mask:0xf bank_mask:0xf bound_ctrl:1
	s_nop 1
	v_add_f32_dpp v54, v37, v37 quad_perm:[2,3,0,1] row_mask:0xf bank_mask:0xf bound_ctrl:1
	v_mov_b32_e32 v71, v72
	v_mov_b32_e32 v55, v0
	v_mul_f32_e32 v56, v72, v0
	s_add_i32 s10, s24, s16
	v_pk_fma_f32 v[54:55], v[70:71], v[54:55], v[56:57] op_sel_hi:[1,1,0]
	s_ashr_i32 s11, s10, 31
	v_bfe_u32 v37, v54, 16, 1
	s_lshl_b64 s[10:11], s[10:11], 9
	v_add3_u32 v37, v54, v37, s28
	v_lshl_add_u64 v[54:55], v[92:93], 0, s[10:11]
	global_store_short_d16_hi v[54:55], v37, off
	v_pk_mul_f32 v[54:55], v[70:71], v[74:75] op_sel_hi:[0,1]
	v_pk_fma_f32 v[74:75], v[50:51], v[0:1], v[54:55] op_sel_hi:[1,0,1]
	v_pk_mul_f32 v[50:51], v[70:71], v[78:79] op_sel_hi:[0,1]
	v_pk_fma_f32 v[78:79], v[52:53], v[0:1], v[50:51] op_sel_hi:[1,0,1]
	v_pk_mul_f32 v[50:51], v[70:71], v[80:81] op_sel_hi:[0,1]
	v_pk_fma_f32 v[80:81], v[46:47], v[0:1], v[50:51] op_sel_hi:[1,0,1]
	v_pk_mul_f32 v[46:47], v[70:71], v[82:83] op_sel_hi:[0,1]
	v_pk_fma_f32 v[82:83], v[48:49], v[0:1], v[46:47] op_sel_hi:[1,0,1]
	v_pk_mul_f32 v[46:47], v[70:71], v[84:85] op_sel_hi:[0,1]
	v_pk_fma_f32 v[84:85], v[42:43], v[0:1], v[46:47] op_sel_hi:[1,0,1]
	v_pk_mul_f32 v[42:43], v[70:71], v[86:87] op_sel_hi:[0,1]
	v_pk_fma_f32 v[86:87], v[44:45], v[0:1], v[42:43] op_sel_hi:[1,0,1]
	v_pk_mul_f32 v[42:43], v[70:71], v[88:89] op_sel_hi:[0,1]
	v_pk_fma_f32 v[88:89], v[38:39], v[0:1], v[42:43] op_sel_hi:[1,0,1]
	v_pk_mul_f32 v[38:39], v[70:71], v[90:91] op_sel_hi:[0,1]
	s_add_i32 s16, s16, s25
	s_add_i32 s6, s6, 2
	s_addk_i32 s7, 0x640
	v_pk_fma_f32 v[90:91], v[40:41], v[0:1], v[38:39] op_sel_hi:[1,0,1]
	s_waitcnt lgkmcnt(5)
	v_pk_fma_f32 v[100:101], v[74:75], v[2:3], 0 op_sel_hi:[1,1,0]
	s_waitcnt lgkmcnt(0)
	v_mov_b32_e32 v37, v34
	v_add_u32_e32 v34, s7, v94
	v_pk_fma_f32 v[30:31], v[74:75], v[30:31], 0 op_sel_hi:[1,1,0]
	v_pk_fma_f32 v[100:101], v[78:79], v[4:5], v[100:101]
	ds_read_b128 v[66:69], v34
	ds_read_b128 v[62:65], v34 offset:16
	ds_read_b128 v[58:61], v34 offset:32
	ds_read_b128 v[54:57], v34 offset:48
	ds_read_b128 v[50:53], v34 offset:256
	ds_read_b128 v[46:49], v34 offset:272
	ds_read_b128 v[42:45], v34 offset:288
	ds_read_b128 v[38:41], v34 offset:304
	v_pk_fma_f32 v[30:31], v[78:79], v[32:33], v[30:31]
	v_pk_fma_f32 v[32:33], v[80:81], v[6:7], v[100:101]
	v_pk_fma_f32 v[26:27], v[80:81], v[26:27], v[30:31]
	v_pk_fma_f32 v[30:31], v[82:83], v[8:9], v[32:33]
	v_pk_fma_f32 v[26:27], v[82:83], v[28:29], v[26:27]
	s_waitcnt lgkmcnt(9)
	v_pk_fma_f32 v[28:29], v[84:85], v[14:15], v[30:31]
	v_pk_fma_f32 v[22:23], v[84:85], v[22:23], v[26:27]
	v_pk_fma_f32 v[26:27], v[86:87], v[16:17], v[28:29]
	v_pk_fma_f32 v[22:23], v[86:87], v[24:25], v[22:23]
	s_waitcnt lgkmcnt(8)
	v_pk_fma_f32 v[24:25], v[88:89], v[10:11], v[26:27]
	v_add_u32_e32 v98, s7, v96
	v_mov_b32_e32 v70, s7
	v_pk_fma_f32 v[18:19], v[88:89], v[18:19], v[22:23]
	v_pk_fma_f32 v[22:23], v[90:91], v[12:13], v[24:25]
	ds_read_b32 v0, v98 offset:512
	ds_read_b96 v[70:72], v70 offset:768
	v_pk_fma_f32 v[18:19], v[90:91], v[20:21], v[18:19]
	v_add_f32_e32 v20, v22, v23
	v_add_f32_e32 v18, v18, v19
	s_nop 0
	v_add_f32_dpp v20, v20, v20 quad_perm:[1,0,3,2] row_mask:0xf bank_mask:0xf bound_ctrl:1
	v_add_f32_dpp v19, v18, v18 quad_perm:[1,0,3,2] row_mask:0xf bank_mask:0xf bound_ctrl:1
	s_nop 0
	v_add_f32_dpp v20, v20, v20 quad_perm:[2,3,0,1] row_mask:0xf bank_mask:0xf bound_ctrl:1
	v_fma_f32 v18, -v37, v20, v73
	v_mul_f32_e32 v18, v35, v18
	v_add_f32_dpp v19, v19, v19 quad_perm:[2,3,0,1] row_mask:0xf bank_mask:0xf bound_ctrl:1
	v_mul_f32_e32 v20, v37, v19
	v_pk_fma_f32 v[20:21], v[36:37], v[18:19], v[20:21] op_sel_hi:[1,1,0]
	s_ashr_i32 s17, s16, 31
	v_bfe_u32 v19, v20, 16, 1
	s_lshl_b64 s[10:11], s[16:17], 9
	v_add3_u32 v19, v20, v19, s28
	v_lshl_add_u64 v[20:21], v[92:93], 0, s[10:11]
	global_store_short_d16_hi v[20:21], v19, off
	v_pk_mul_f32 v[20:21], v[74:75], v[36:37] op_sel:[0,1]
	s_nop 0
	v_pk_fma_f32 v[74:75], v[2:3], v[18:19], v[20:21] op_sel_hi:[1,0,1]
	v_pk_mul_f32 v[2:3], v[78:79], v[36:37] op_sel:[0,1]
	s_waitcnt lgkmcnt(9)
	v_pk_fma_f32 v[66:67], v[74:75], v[66:67], 0 op_sel_hi:[1,1,0]
	v_pk_fma_f32 v[78:79], v[4:5], v[18:19], v[2:3] op_sel_hi:[1,0,1]
	v_pk_mul_f32 v[2:3], v[80:81], v[36:37] op_sel:[0,1]
	v_pk_fma_f32 v[66:67], v[78:79], v[68:69], v[66:67]
	v_pk_fma_f32 v[80:81], v[6:7], v[18:19], v[2:3] op_sel_hi:[1,0,1]
	v_pk_mul_f32 v[2:3], v[82:83], v[36:37] op_sel:[0,1]
	s_waitcnt lgkmcnt(8)
	v_pk_fma_f32 v[62:63], v[80:81], v[62:63], v[66:67]
	v_pk_fma_f32 v[82:83], v[8:9], v[18:19], v[2:3] op_sel_hi:[1,0,1]
	v_pk_mul_f32 v[2:3], v[84:85], v[36:37] op_sel:[0,1]
	v_pk_fma_f32 v[62:63], v[82:83], v[64:65], v[62:63]
	v_pk_fma_f32 v[84:85], v[14:15], v[18:19], v[2:3] op_sel_hi:[1,0,1]
	v_pk_mul_f32 v[2:3], v[86:87], v[36:37] op_sel:[0,1]
	s_waitcnt lgkmcnt(7)
	v_pk_fma_f32 v[58:59], v[84:85], v[58:59], v[62:63]
	v_pk_fma_f32 v[86:87], v[16:17], v[18:19], v[2:3] op_sel_hi:[1,0,1]
	v_pk_mul_f32 v[2:3], v[88:89], v[36:37] op_sel:[0,1]
	v_pk_fma_f32 v[58:59], v[86:87], v[60:61], v[58:59]
	v_pk_fma_f32 v[88:89], v[10:11], v[18:19], v[2:3] op_sel_hi:[1,0,1]
	v_pk_mul_f32 v[2:3], v[90:91], v[36:37] op_sel:[0,1]
	s_waitcnt lgkmcnt(6)
	v_pk_fma_f32 v[54:55], v[88:89], v[54:55], v[58:59]
	v_pk_fma_f32 v[90:91], v[12:13], v[18:19], v[2:3] op_sel_hi:[1,0,1]
	ds_read_b128 v[30:33], v34 offset:800
	ds_read_b128 v[26:29], v34 offset:816
	ds_read_b128 v[22:25], v34 offset:832
	ds_read_b128 v[18:21], v34 offset:848
	ds_read_b128 v[2:5], v34 offset:1056
	ds_read_b128 v[6:9], v34 offset:1072
	ds_read_b128 v[14:17], v34 offset:1088
	ds_read_b128 v[10:13], v34 offset:1104
	v_mov_b32_e32 v34, s7
	ds_read_b32 v73, v98 offset:1312
	ds_read_b96 v[34:36], v34 offset:1568
	s_waitcnt lgkmcnt(14)
	v_pk_fma_f32 v[98:99], v[74:75], v[50:51], 0 op_sel_hi:[1,1,0]
	v_pk_fma_f32 v[54:55], v[90:91], v[56:57], v[54:55]
	v_pk_fma_f32 v[98:99], v[78:79], v[52:53], v[98:99]
	s_nop 0
	v_pk_fma_f32 v[68:69], v[80:81], v[46:47], v[98:99]
	s_nop 0
	v_pk_fma_f32 v[66:67], v[82:83], v[48:49], v[68:69]
	s_waitcnt lgkmcnt(13)
	v_pk_fma_f32 v[64:65], v[84:85], v[42:43], v[66:67]
	s_nop 0
	v_pk_fma_f32 v[62:63], v[86:87], v[44:45], v[64:65]
	s_waitcnt lgkmcnt(12)
	v_pk_fma_f32 v[60:61], v[88:89], v[38:39], v[62:63]
	s_nop 0
	v_pk_fma_f32 v[58:59], v[90:91], v[40:41], v[60:61]
	s_nop 0
	v_add_f32_e32 v37, v58, v59
	s_nop 1
	v_add_f32_dpp v37, v37, v37 quad_perm:[1,0,3,2] row_mask:0xf bank_mask:0xf bound_ctrl:1
	s_nop 1
	v_add_f32_dpp v56, v37, v37 quad_perm:[2,3,0,1] row_mask:0xf bank_mask:0xf bound_ctrl:1
	v_add_f32_e32 v37, v54, v55
	s_waitcnt lgkmcnt(10)
	v_fma_f32 v0, -v70, v56, v0
	v_mul_f32_e32 v0, v71, v0
	v_add_f32_dpp v37, v37, v37 quad_perm:[1,0,3,2] row_mask:0xf bank_mask:0xf bound_ctrl:1
	s_nop 1
	v_add_f32_dpp v54, v37, v37 quad_perm:[2,3,0,1] row_mask:0xf bank_mask:0xf bound_ctrl:1
	v_mov_b32_e32 v71, v72
	v_mov_b32_e32 v55, v0
	v_mul_f32_e32 v56, v72, v0
	s_add_i32 s10, s24, s16
	v_pk_fma_f32 v[54:55], v[70:71], v[54:55], v[56:57] op_sel_hi:[1,1,0]
	s_ashr_i32 s11, s10, 31
	v_bfe_u32 v37, v54, 16, 1
	s_lshl_b64 s[10:11], s[10:11], 9
	v_add3_u32 v37, v54, v37, s28
	v_lshl_add_u64 v[54:55], v[92:93], 0, s[10:11]
	global_store_short_d16_hi v[54:55], v37, off
	v_pk_mul_f32 v[54:55], v[70:71], v[74:75] op_sel_hi:[0,1]
	v_pk_fma_f32 v[74:75], v[50:51], v[0:1], v[54:55] op_sel_hi:[1,0,1]
	v_pk_mul_f32 v[50:51], v[70:71], v[78:79] op_sel_hi:[0,1]
	v_pk_fma_f32 v[78:79], v[52:53], v[0:1], v[50:51] op_sel_hi:[1,0,1]
	v_pk_mul_f32 v[50:51], v[70:71], v[80:81] op_sel_hi:[0,1]
	v_pk_fma_f32 v[80:81], v[46:47], v[0:1], v[50:51] op_sel_hi:[1,0,1]
	v_pk_mul_f32 v[46:47], v[70:71], v[82:83] op_sel_hi:[0,1]
	v_pk_fma_f32 v[82:83], v[48:49], v[0:1], v[46:47] op_sel_hi:[1,0,1]
	v_pk_mul_f32 v[46:47], v[70:71], v[84:85] op_sel_hi:[0,1]
	v_pk_fma_f32 v[84:85], v[42:43], v[0:1], v[46:47] op_sel_hi:[1,0,1]
	v_pk_mul_f32 v[42:43], v[70:71], v[86:87] op_sel_hi:[0,1]
	v_pk_fma_f32 v[86:87], v[44:45], v[0:1], v[42:43] op_sel_hi:[1,0,1]
	v_pk_mul_f32 v[42:43], v[70:71], v[88:89] op_sel_hi:[0,1]
	v_pk_fma_f32 v[88:89], v[38:39], v[0:1], v[42:43] op_sel_hi:[1,0,1]
	v_pk_mul_f32 v[38:39], v[70:71], v[90:91] op_sel_hi:[0,1]
	s_add_i32 s16, s16, s25
	s_add_i32 s6, s6, 2
	s_addk_i32 s7, 0x640
	v_pk_fma_f32 v[90:91], v[40:41], v[0:1], v[38:39] op_sel_hi:[1,0,1]
	s_waitcnt lgkmcnt(5)
	v_pk_fma_f32 v[100:101], v[74:75], v[2:3], 0 op_sel_hi:[1,1,0]
	s_waitcnt lgkmcnt(0)
	v_mov_b32_e32 v37, v34
	v_add_u32_e32 v34, s7, v94
	v_pk_fma_f32 v[30:31], v[74:75], v[30:31], 0 op_sel_hi:[1,1,0]
	v_pk_fma_f32 v[100:101], v[78:79], v[4:5], v[100:101]
	ds_read_b128 v[66:69], v34
	ds_read_b128 v[62:65], v34 offset:16
	ds_read_b128 v[58:61], v34 offset:32
	ds_read_b128 v[54:57], v34 offset:48
	ds_read_b128 v[50:53], v34 offset:256
	ds_read_b128 v[46:49], v34 offset:272
	ds_read_b128 v[42:45], v34 offset:288
	ds_read_b128 v[38:41], v34 offset:304
	v_pk_fma_f32 v[30:31], v[78:79], v[32:33], v[30:31]
	v_pk_fma_f32 v[32:33], v[80:81], v[6:7], v[100:101]
	v_pk_fma_f32 v[26:27], v[80:81], v[26:27], v[30:31]
	v_pk_fma_f32 v[30:31], v[82:83], v[8:9], v[32:33]
	v_pk_fma_f32 v[26:27], v[82:83], v[28:29], v[26:27]
	s_waitcnt lgkmcnt(9)
	v_pk_fma_f32 v[28:29], v[84:85], v[14:15], v[30:31]
	v_pk_fma_f32 v[22:23], v[84:85], v[22:23], v[26:27]
	v_pk_fma_f32 v[26:27], v[86:87], v[16:17], v[28:29]
	v_pk_fma_f32 v[22:23], v[86:87], v[24:25], v[22:23]
	s_waitcnt lgkmcnt(8)
	v_pk_fma_f32 v[24:25], v[88:89], v[10:11], v[26:27]
	v_add_u32_e32 v98, s7, v96
	v_mov_b32_e32 v70, s7
	v_pk_fma_f32 v[18:19], v[88:89], v[18:19], v[22:23]
	v_pk_fma_f32 v[22:23], v[90:91], v[12:13], v[24:25]
	ds_read_b32 v0, v98 offset:512
	ds_read_b96 v[70:72], v70 offset:768
	v_pk_fma_f32 v[18:19], v[90:91], v[20:21], v[18:19]
	v_add_f32_e32 v20, v22, v23
	v_add_f32_e32 v18, v18, v19
	s_nop 0
	v_add_f32_dpp v20, v20, v20 quad_perm:[1,0,3,2] row_mask:0xf bank_mask:0xf bound_ctrl:1
	v_add_f32_dpp v19, v18, v18 quad_perm:[1,0,3,2] row_mask:0xf bank_mask:0xf bound_ctrl:1
	s_nop 0
	v_add_f32_dpp v20, v20, v20 quad_perm:[2,3,0,1] row_mask:0xf bank_mask:0xf bound_ctrl:1
	v_fma_f32 v18, -v37, v20, v73
	v_mul_f32_e32 v18, v35, v18
	v_add_f32_dpp v19, v19, v19 quad_perm:[2,3,0,1] row_mask:0xf bank_mask:0xf bound_ctrl:1
	v_mul_f32_e32 v20, v37, v19
	v_pk_fma_f32 v[20:21], v[36:37], v[18:19], v[20:21] op_sel_hi:[1,1,0]
	s_ashr_i32 s17, s16, 31
	v_bfe_u32 v19, v20, 16, 1
	s_lshl_b64 s[10:11], s[16:17], 9
	v_add3_u32 v19, v20, v19, s28
	v_lshl_add_u64 v[20:21], v[92:93], 0, s[10:11]
	global_store_short_d16_hi v[20:21], v19, off
	v_pk_mul_f32 v[20:21], v[74:75], v[36:37] op_sel:[0,1]
	s_nop 0
	v_pk_fma_f32 v[74:75], v[2:3], v[18:19], v[20:21] op_sel_hi:[1,0,1]
	v_pk_mul_f32 v[2:3], v[78:79], v[36:37] op_sel:[0,1]
	s_waitcnt lgkmcnt(9)
	v_pk_fma_f32 v[66:67], v[74:75], v[66:67], 0 op_sel_hi:[1,1,0]
	v_pk_fma_f32 v[78:79], v[4:5], v[18:19], v[2:3] op_sel_hi:[1,0,1]
	v_pk_mul_f32 v[2:3], v[80:81], v[36:37] op_sel:[0,1]
	v_pk_fma_f32 v[66:67], v[78:79], v[68:69], v[66:67]
	v_pk_fma_f32 v[80:81], v[6:7], v[18:19], v[2:3] op_sel_hi:[1,0,1]
	v_pk_mul_f32 v[2:3], v[82:83], v[36:37] op_sel:[0,1]
	s_waitcnt lgkmcnt(8)
	v_pk_fma_f32 v[62:63], v[80:81], v[62:63], v[66:67]
	v_pk_fma_f32 v[82:83], v[8:9], v[18:19], v[2:3] op_sel_hi:[1,0,1]
	v_pk_mul_f32 v[2:3], v[84:85], v[36:37] op_sel:[0,1]
	v_pk_fma_f32 v[62:63], v[82:83], v[64:65], v[62:63]
	v_pk_fma_f32 v[84:85], v[14:15], v[18:19], v[2:3] op_sel_hi:[1,0,1]
	v_pk_mul_f32 v[2:3], v[86:87], v[36:37] op_sel:[0,1]
	s_waitcnt lgkmcnt(7)
	v_pk_fma_f32 v[58:59], v[84:85], v[58:59], v[62:63]
	v_pk_fma_f32 v[86:87], v[16:17], v[18:19], v[2:3] op_sel_hi:[1,0,1]
	v_pk_mul_f32 v[2:3], v[88:89], v[36:37] op_sel:[0,1]
	v_pk_fma_f32 v[58:59], v[86:87], v[60:61], v[58:59]
	v_pk_fma_f32 v[88:89], v[10:11], v[18:19], v[2:3] op_sel_hi:[1,0,1]
	v_pk_mul_f32 v[2:3], v[90:91], v[36:37] op_sel:[0,1]
	s_waitcnt lgkmcnt(6)
	v_pk_fma_f32 v[54:55], v[88:89], v[54:55], v[58:59]
	v_pk_fma_f32 v[90:91], v[12:13], v[18:19], v[2:3] op_sel_hi:[1,0,1]
	ds_read_b128 v[30:33], v34 offset:800
	ds_read_b128 v[26:29], v34 offset:816
	ds_read_b128 v[22:25], v34 offset:832
	ds_read_b128 v[18:21], v34 offset:848
	ds_read_b128 v[2:5], v34 offset:1056
	ds_read_b128 v[6:9], v34 offset:1072
	ds_read_b128 v[14:17], v34 offset:1088
	ds_read_b128 v[10:13], v34 offset:1104
	v_mov_b32_e32 v34, s7
	ds_read_b32 v73, v98 offset:1312
	ds_read_b96 v[34:36], v34 offset:1568
	s_waitcnt lgkmcnt(14)
	v_pk_fma_f32 v[98:99], v[74:75], v[50:51], 0 op_sel_hi:[1,1,0]
	v_pk_fma_f32 v[54:55], v[90:91], v[56:57], v[54:55]
	v_pk_fma_f32 v[98:99], v[78:79], v[52:53], v[98:99]
	s_nop 0
	v_pk_fma_f32 v[68:69], v[80:81], v[46:47], v[98:99]
	s_nop 0
	v_pk_fma_f32 v[66:67], v[82:83], v[48:49], v[68:69]
	s_waitcnt lgkmcnt(13)
	v_pk_fma_f32 v[64:65], v[84:85], v[42:43], v[66:67]
	s_nop 0
	v_pk_fma_f32 v[62:63], v[86:87], v[44:45], v[64:65]
	s_waitcnt lgkmcnt(12)
	v_pk_fma_f32 v[60:61], v[88:89], v[38:39], v[62:63]
	s_nop 0
	v_pk_fma_f32 v[58:59], v[90:91], v[40:41], v[60:61]
	s_nop 0
	v_add_f32_e32 v37, v58, v59
	s_nop 1
	v_add_f32_dpp v37, v37, v37 quad_perm:[1,0,3,2] row_mask:0xf bank_mask:0xf bound_ctrl:1
	s_nop 1
	v_add_f32_dpp v56, v37, v37 quad_perm:[2,3,0,1] row_mask:0xf bank_mask:0xf bound_ctrl:1
	v_add_f32_e32 v37, v54, v55
	s_waitcnt lgkmcnt(10)
	v_fma_f32 v0, -v70, v56, v0
	v_mul_f32_e32 v0, v71, v0
	v_add_f32_dpp v37, v37, v37 quad_perm:[1,0,3,2] row_mask:0xf bank_mask:0xf bound_ctrl:1
	s_nop 1
	v_add_f32_dpp v54, v37, v37 quad_perm:[2,3,0,1] row_mask:0xf bank_mask:0xf bound_ctrl:1
	v_mov_b32_e32 v71, v72
	v_mov_b32_e32 v55, v0
	v_mul_f32_e32 v56, v72, v0
	s_add_i32 s10, s24, s16
	v_pk_fma_f32 v[54:55], v[70:71], v[54:55], v[56:57] op_sel_hi:[1,1,0]
	s_ashr_i32 s11, s10, 31
	v_bfe_u32 v37, v54, 16, 1
	s_lshl_b64 s[10:11], s[10:11], 9
	v_add3_u32 v37, v54, v37, s28
	v_lshl_add_u64 v[54:55], v[92:93], 0, s[10:11]
	global_store_short_d16_hi v[54:55], v37, off
	v_pk_mul_f32 v[54:55], v[70:71], v[74:75] op_sel_hi:[0,1]
	v_pk_fma_f32 v[74:75], v[50:51], v[0:1], v[54:55] op_sel_hi:[1,0,1]
	v_pk_mul_f32 v[50:51], v[70:71], v[78:79] op_sel_hi:[0,1]
	v_pk_fma_f32 v[78:79], v[52:53], v[0:1], v[50:51] op_sel_hi:[1,0,1]
	v_pk_mul_f32 v[50:51], v[70:71], v[80:81] op_sel_hi:[0,1]
	v_pk_fma_f32 v[80:81], v[46:47], v[0:1], v[50:51] op_sel_hi:[1,0,1]
	v_pk_mul_f32 v[46:47], v[70:71], v[82:83] op_sel_hi:[0,1]
	v_pk_fma_f32 v[82:83], v[48:49], v[0:1], v[46:47] op_sel_hi:[1,0,1]
	v_pk_mul_f32 v[46:47], v[70:71], v[84:85] op_sel_hi:[0,1]
	v_pk_fma_f32 v[84:85], v[42:43], v[0:1], v[46:47] op_sel_hi:[1,0,1]
	v_pk_mul_f32 v[42:43], v[70:71], v[86:87] op_sel_hi:[0,1]
	v_pk_fma_f32 v[86:87], v[44:45], v[0:1], v[42:43] op_sel_hi:[1,0,1]
	v_pk_mul_f32 v[42:43], v[70:71], v[88:89] op_sel_hi:[0,1]
	v_pk_fma_f32 v[88:89], v[38:39], v[0:1], v[42:43] op_sel_hi:[1,0,1]
	v_pk_mul_f32 v[38:39], v[70:71], v[90:91] op_sel_hi:[0,1]
	s_add_i32 s16, s16, s25
	s_add_i32 s6, s6, 2
	s_addk_i32 s7, 0x640
	v_pk_fma_f32 v[90:91], v[40:41], v[0:1], v[38:39] op_sel_hi:[1,0,1]
	s_waitcnt lgkmcnt(5)
	v_pk_fma_f32 v[100:101], v[74:75], v[2:3], 0 op_sel_hi:[1,1,0]
	s_waitcnt lgkmcnt(0)
	v_mov_b32_e32 v37, v34
	v_add_u32_e32 v34, s7, v94
	v_pk_fma_f32 v[30:31], v[74:75], v[30:31], 0 op_sel_hi:[1,1,0]
	v_pk_fma_f32 v[100:101], v[78:79], v[4:5], v[100:101]
	ds_read_b128 v[66:69], v34
	ds_read_b128 v[62:65], v34 offset:16
	ds_read_b128 v[58:61], v34 offset:32
	ds_read_b128 v[54:57], v34 offset:48
	ds_read_b128 v[50:53], v34 offset:256
	ds_read_b128 v[46:49], v34 offset:272
	ds_read_b128 v[42:45], v34 offset:288
	ds_read_b128 v[38:41], v34 offset:304
	v_pk_fma_f32 v[30:31], v[78:79], v[32:33], v[30:31]
	v_pk_fma_f32 v[32:33], v[80:81], v[6:7], v[100:101]
	v_pk_fma_f32 v[26:27], v[80:81], v[26:27], v[30:31]
	v_pk_fma_f32 v[30:31], v[82:83], v[8:9], v[32:33]
	v_pk_fma_f32 v[26:27], v[82:83], v[28:29], v[26:27]
	s_waitcnt lgkmcnt(9)
	v_pk_fma_f32 v[28:29], v[84:85], v[14:15], v[30:31]
	v_pk_fma_f32 v[22:23], v[84:85], v[22:23], v[26:27]
	v_pk_fma_f32 v[26:27], v[86:87], v[16:17], v[28:29]
	v_pk_fma_f32 v[22:23], v[86:87], v[24:25], v[22:23]
	s_waitcnt lgkmcnt(8)
	v_pk_fma_f32 v[24:25], v[88:89], v[10:11], v[26:27]
	v_add_u32_e32 v98, s7, v96
	v_mov_b32_e32 v70, s7
	v_pk_fma_f32 v[18:19], v[88:89], v[18:19], v[22:23]
	v_pk_fma_f32 v[22:23], v[90:91], v[12:13], v[24:25]
	ds_read_b32 v0, v98 offset:512
	ds_read_b96 v[70:72], v70 offset:768
	v_pk_fma_f32 v[18:19], v[90:91], v[20:21], v[18:19]
	v_add_f32_e32 v20, v22, v23
	v_add_f32_e32 v18, v18, v19
	s_nop 0
	v_add_f32_dpp v20, v20, v20 quad_perm:[1,0,3,2] row_mask:0xf bank_mask:0xf bound_ctrl:1
	v_add_f32_dpp v19, v18, v18 quad_perm:[1,0,3,2] row_mask:0xf bank_mask:0xf bound_ctrl:1
	s_nop 0
	v_add_f32_dpp v20, v20, v20 quad_perm:[2,3,0,1] row_mask:0xf bank_mask:0xf bound_ctrl:1
	v_fma_f32 v18, -v37, v20, v73
	v_mul_f32_e32 v18, v35, v18
	v_add_f32_dpp v19, v19, v19 quad_perm:[2,3,0,1] row_mask:0xf bank_mask:0xf bound_ctrl:1
	v_mul_f32_e32 v20, v37, v19
	v_pk_fma_f32 v[20:21], v[36:37], v[18:19], v[20:21] op_sel_hi:[1,1,0]
	s_ashr_i32 s17, s16, 31
	v_bfe_u32 v19, v20, 16, 1
	s_lshl_b64 s[10:11], s[16:17], 9
	v_add3_u32 v19, v20, v19, s28
	v_lshl_add_u64 v[20:21], v[92:93], 0, s[10:11]
	global_store_short_d16_hi v[20:21], v19, off
	v_pk_mul_f32 v[20:21], v[74:75], v[36:37] op_sel:[0,1]
	s_nop 0
	v_pk_fma_f32 v[74:75], v[2:3], v[18:19], v[20:21] op_sel_hi:[1,0,1]
	v_pk_mul_f32 v[2:3], v[78:79], v[36:37] op_sel:[0,1]
	s_waitcnt lgkmcnt(9)
	v_pk_fma_f32 v[66:67], v[74:75], v[66:67], 0 op_sel_hi:[1,1,0]
	v_pk_fma_f32 v[78:79], v[4:5], v[18:19], v[2:3] op_sel_hi:[1,0,1]
	v_pk_mul_f32 v[2:3], v[80:81], v[36:37] op_sel:[0,1]
	v_pk_fma_f32 v[66:67], v[78:79], v[68:69], v[66:67]
	v_pk_fma_f32 v[80:81], v[6:7], v[18:19], v[2:3] op_sel_hi:[1,0,1]
	v_pk_mul_f32 v[2:3], v[82:83], v[36:37] op_sel:[0,1]
	s_waitcnt lgkmcnt(8)
	v_pk_fma_f32 v[62:63], v[80:81], v[62:63], v[66:67]
	v_pk_fma_f32 v[82:83], v[8:9], v[18:19], v[2:3] op_sel_hi:[1,0,1]
	v_pk_mul_f32 v[2:3], v[84:85], v[36:37] op_sel:[0,1]
	v_pk_fma_f32 v[62:63], v[82:83], v[64:65], v[62:63]
	v_pk_fma_f32 v[84:85], v[14:15], v[18:19], v[2:3] op_sel_hi:[1,0,1]
	v_pk_mul_f32 v[2:3], v[86:87], v[36:37] op_sel:[0,1]
	s_waitcnt lgkmcnt(7)
	v_pk_fma_f32 v[58:59], v[84:85], v[58:59], v[62:63]
	v_pk_fma_f32 v[86:87], v[16:17], v[18:19], v[2:3] op_sel_hi:[1,0,1]
	v_pk_mul_f32 v[2:3], v[88:89], v[36:37] op_sel:[0,1]
	v_pk_fma_f32 v[58:59], v[86:87], v[60:61], v[58:59]
	v_pk_fma_f32 v[88:89], v[10:11], v[18:19], v[2:3] op_sel_hi:[1,0,1]
	v_pk_mul_f32 v[2:3], v[90:91], v[36:37] op_sel:[0,1]
	s_waitcnt lgkmcnt(6)
	v_pk_fma_f32 v[54:55], v[88:89], v[54:55], v[58:59]
	v_pk_fma_f32 v[90:91], v[12:13], v[18:19], v[2:3] op_sel_hi:[1,0,1]
	ds_read_b128 v[30:33], v34 offset:800
	ds_read_b128 v[26:29], v34 offset:816
	ds_read_b128 v[22:25], v34 offset:832
	ds_read_b128 v[18:21], v34 offset:848
	ds_read_b128 v[2:5], v34 offset:1056
	ds_read_b128 v[6:9], v34 offset:1072
	ds_read_b128 v[14:17], v34 offset:1088
	ds_read_b128 v[10:13], v34 offset:1104
	v_mov_b32_e32 v34, s7
	ds_read_b32 v73, v98 offset:1312
	ds_read_b96 v[34:36], v34 offset:1568
	s_waitcnt lgkmcnt(14)
	v_pk_fma_f32 v[98:99], v[74:75], v[50:51], 0 op_sel_hi:[1,1,0]
	v_pk_fma_f32 v[54:55], v[90:91], v[56:57], v[54:55]
	v_pk_fma_f32 v[98:99], v[78:79], v[52:53], v[98:99]
	s_nop 0
	v_pk_fma_f32 v[68:69], v[80:81], v[46:47], v[98:99]
	s_nop 0
	v_pk_fma_f32 v[66:67], v[82:83], v[48:49], v[68:69]
	s_waitcnt lgkmcnt(13)
	v_pk_fma_f32 v[64:65], v[84:85], v[42:43], v[66:67]
	s_nop 0
	v_pk_fma_f32 v[62:63], v[86:87], v[44:45], v[64:65]
	s_waitcnt lgkmcnt(12)
	v_pk_fma_f32 v[60:61], v[88:89], v[38:39], v[62:63]
	s_nop 0
	v_pk_fma_f32 v[58:59], v[90:91], v[40:41], v[60:61]
	s_nop 0
	v_add_f32_e32 v37, v58, v59
	s_nop 1
	v_add_f32_dpp v37, v37, v37 quad_perm:[1,0,3,2] row_mask:0xf bank_mask:0xf bound_ctrl:1
	s_nop 1
	v_add_f32_dpp v56, v37, v37 quad_perm:[2,3,0,1] row_mask:0xf bank_mask:0xf bound_ctrl:1
	v_add_f32_e32 v37, v54, v55
	s_waitcnt lgkmcnt(10)
	v_fma_f32 v0, -v70, v56, v0
	v_mul_f32_e32 v0, v71, v0
	v_add_f32_dpp v37, v37, v37 quad_perm:[1,0,3,2] row_mask:0xf bank_mask:0xf bound_ctrl:1
	s_nop 1
	v_add_f32_dpp v54, v37, v37 quad_perm:[2,3,0,1] row_mask:0xf bank_mask:0xf bound_ctrl:1
	v_mov_b32_e32 v71, v72
	v_mov_b32_e32 v55, v0
	v_mul_f32_e32 v56, v72, v0
	s_add_i32 s10, s24, s16
	v_pk_fma_f32 v[54:55], v[70:71], v[54:55], v[56:57] op_sel_hi:[1,1,0]
	s_ashr_i32 s11, s10, 31
	v_bfe_u32 v37, v54, 16, 1
	s_lshl_b64 s[10:11], s[10:11], 9
	v_add3_u32 v37, v54, v37, s28
	v_lshl_add_u64 v[54:55], v[92:93], 0, s[10:11]
	global_store_short_d16_hi v[54:55], v37, off
	v_pk_mul_f32 v[54:55], v[70:71], v[74:75] op_sel_hi:[0,1]
	v_pk_fma_f32 v[74:75], v[50:51], v[0:1], v[54:55] op_sel_hi:[1,0,1]
	v_pk_mul_f32 v[50:51], v[70:71], v[78:79] op_sel_hi:[0,1]
	v_pk_fma_f32 v[78:79], v[52:53], v[0:1], v[50:51] op_sel_hi:[1,0,1]
	v_pk_mul_f32 v[50:51], v[70:71], v[80:81] op_sel_hi:[0,1]
	v_pk_fma_f32 v[80:81], v[46:47], v[0:1], v[50:51] op_sel_hi:[1,0,1]
	v_pk_mul_f32 v[46:47], v[70:71], v[82:83] op_sel_hi:[0,1]
	v_pk_fma_f32 v[82:83], v[48:49], v[0:1], v[46:47] op_sel_hi:[1,0,1]
	v_pk_mul_f32 v[46:47], v[70:71], v[84:85] op_sel_hi:[0,1]
	v_pk_fma_f32 v[84:85], v[42:43], v[0:1], v[46:47] op_sel_hi:[1,0,1]
	v_pk_mul_f32 v[42:43], v[70:71], v[86:87] op_sel_hi:[0,1]
	v_pk_fma_f32 v[86:87], v[44:45], v[0:1], v[42:43] op_sel_hi:[1,0,1]
	v_pk_mul_f32 v[42:43], v[70:71], v[88:89] op_sel_hi:[0,1]
	v_pk_fma_f32 v[88:89], v[38:39], v[0:1], v[42:43] op_sel_hi:[1,0,1]
	v_pk_mul_f32 v[38:39], v[70:71], v[90:91] op_sel_hi:[0,1]
	s_add_i32 s16, s16, s25
	s_add_i32 s6, s6, 2
	s_addk_i32 s7, 0x640
	v_pk_fma_f32 v[90:91], v[40:41], v[0:1], v[38:39] op_sel_hi:[1,0,1]
	s_waitcnt lgkmcnt(5)
	v_pk_fma_f32 v[100:101], v[74:75], v[2:3], 0 op_sel_hi:[1,1,0]
	s_waitcnt lgkmcnt(0)
	v_mov_b32_e32 v37, v34
	v_add_u32_e32 v34, s7, v94
	v_pk_fma_f32 v[30:31], v[74:75], v[30:31], 0 op_sel_hi:[1,1,0]
	v_pk_fma_f32 v[100:101], v[78:79], v[4:5], v[100:101]
	ds_read_b128 v[66:69], v34
	ds_read_b128 v[62:65], v34 offset:16
	ds_read_b128 v[58:61], v34 offset:32
	ds_read_b128 v[54:57], v34 offset:48
	ds_read_b128 v[50:53], v34 offset:256
	ds_read_b128 v[46:49], v34 offset:272
	ds_read_b128 v[42:45], v34 offset:288
	ds_read_b128 v[38:41], v34 offset:304
	v_pk_fma_f32 v[30:31], v[78:79], v[32:33], v[30:31]
	v_pk_fma_f32 v[32:33], v[80:81], v[6:7], v[100:101]
	v_pk_fma_f32 v[26:27], v[80:81], v[26:27], v[30:31]
	v_pk_fma_f32 v[30:31], v[82:83], v[8:9], v[32:33]
	v_pk_fma_f32 v[26:27], v[82:83], v[28:29], v[26:27]
	s_waitcnt lgkmcnt(9)
	v_pk_fma_f32 v[28:29], v[84:85], v[14:15], v[30:31]
	v_pk_fma_f32 v[22:23], v[84:85], v[22:23], v[26:27]
	v_pk_fma_f32 v[26:27], v[86:87], v[16:17], v[28:29]
	v_pk_fma_f32 v[22:23], v[86:87], v[24:25], v[22:23]
	s_waitcnt lgkmcnt(8)
	v_pk_fma_f32 v[24:25], v[88:89], v[10:11], v[26:27]
	v_add_u32_e32 v98, s7, v96
	v_mov_b32_e32 v70, s7
	v_pk_fma_f32 v[18:19], v[88:89], v[18:19], v[22:23]
	v_pk_fma_f32 v[22:23], v[90:91], v[12:13], v[24:25]
	ds_read_b32 v0, v98 offset:512
	ds_read_b96 v[70:72], v70 offset:768
	v_pk_fma_f32 v[18:19], v[90:91], v[20:21], v[18:19]
	v_add_f32_e32 v20, v22, v23
	v_add_f32_e32 v18, v18, v19
	s_nop 0
	v_add_f32_dpp v20, v20, v20 quad_perm:[1,0,3,2] row_mask:0xf bank_mask:0xf bound_ctrl:1
	v_add_f32_dpp v19, v18, v18 quad_perm:[1,0,3,2] row_mask:0xf bank_mask:0xf bound_ctrl:1
	s_nop 0
	v_add_f32_dpp v20, v20, v20 quad_perm:[2,3,0,1] row_mask:0xf bank_mask:0xf bound_ctrl:1
	v_fma_f32 v18, -v37, v20, v73
	v_mul_f32_e32 v18, v35, v18
	v_add_f32_dpp v19, v19, v19 quad_perm:[2,3,0,1] row_mask:0xf bank_mask:0xf bound_ctrl:1
	v_mul_f32_e32 v20, v37, v19
	v_pk_fma_f32 v[20:21], v[36:37], v[18:19], v[20:21] op_sel_hi:[1,1,0]
	s_ashr_i32 s17, s16, 31
	v_bfe_u32 v19, v20, 16, 1
	s_lshl_b64 s[10:11], s[16:17], 9
	v_add3_u32 v19, v20, v19, s28
	v_lshl_add_u64 v[20:21], v[92:93], 0, s[10:11]
	global_store_short_d16_hi v[20:21], v19, off
	v_pk_mul_f32 v[20:21], v[74:75], v[36:37] op_sel:[0,1]
	s_nop 0
	v_pk_fma_f32 v[74:75], v[2:3], v[18:19], v[20:21] op_sel_hi:[1,0,1]
	v_pk_mul_f32 v[2:3], v[78:79], v[36:37] op_sel:[0,1]
	s_waitcnt lgkmcnt(9)
	v_pk_fma_f32 v[66:67], v[74:75], v[66:67], 0 op_sel_hi:[1,1,0]
	v_pk_fma_f32 v[78:79], v[4:5], v[18:19], v[2:3] op_sel_hi:[1,0,1]
	v_pk_mul_f32 v[2:3], v[80:81], v[36:37] op_sel:[0,1]
	v_pk_fma_f32 v[66:67], v[78:79], v[68:69], v[66:67]
	v_pk_fma_f32 v[80:81], v[6:7], v[18:19], v[2:3] op_sel_hi:[1,0,1]
	v_pk_mul_f32 v[2:3], v[82:83], v[36:37] op_sel:[0,1]
	s_waitcnt lgkmcnt(8)
	v_pk_fma_f32 v[62:63], v[80:81], v[62:63], v[66:67]
	v_pk_fma_f32 v[82:83], v[8:9], v[18:19], v[2:3] op_sel_hi:[1,0,1]
	v_pk_mul_f32 v[2:3], v[84:85], v[36:37] op_sel:[0,1]
	v_pk_fma_f32 v[62:63], v[82:83], v[64:65], v[62:63]
	v_pk_fma_f32 v[84:85], v[14:15], v[18:19], v[2:3] op_sel_hi:[1,0,1]
	v_pk_mul_f32 v[2:3], v[86:87], v[36:37] op_sel:[0,1]
	s_waitcnt lgkmcnt(7)
	v_pk_fma_f32 v[58:59], v[84:85], v[58:59], v[62:63]
	v_pk_fma_f32 v[86:87], v[16:17], v[18:19], v[2:3] op_sel_hi:[1,0,1]
	v_pk_mul_f32 v[2:3], v[88:89], v[36:37] op_sel:[0,1]
	v_pk_fma_f32 v[58:59], v[86:87], v[60:61], v[58:59]
	v_pk_fma_f32 v[88:89], v[10:11], v[18:19], v[2:3] op_sel_hi:[1,0,1]
	v_pk_mul_f32 v[2:3], v[90:91], v[36:37] op_sel:[0,1]
	s_waitcnt lgkmcnt(6)
	v_pk_fma_f32 v[54:55], v[88:89], v[54:55], v[58:59]
	v_pk_fma_f32 v[90:91], v[12:13], v[18:19], v[2:3] op_sel_hi:[1,0,1]
	ds_read_b128 v[30:33], v34 offset:800
	ds_read_b128 v[26:29], v34 offset:816
	ds_read_b128 v[22:25], v34 offset:832
	ds_read_b128 v[18:21], v34 offset:848
	ds_read_b128 v[2:5], v34 offset:1056
	ds_read_b128 v[6:9], v34 offset:1072
	ds_read_b128 v[14:17], v34 offset:1088
	ds_read_b128 v[10:13], v34 offset:1104
	v_mov_b32_e32 v34, s7
	ds_read_b32 v73, v98 offset:1312
	ds_read_b96 v[34:36], v34 offset:1568
	s_waitcnt lgkmcnt(14)
	v_pk_fma_f32 v[98:99], v[74:75], v[50:51], 0 op_sel_hi:[1,1,0]
	v_pk_fma_f32 v[54:55], v[90:91], v[56:57], v[54:55]
	v_pk_fma_f32 v[98:99], v[78:79], v[52:53], v[98:99]
	s_nop 0
	v_pk_fma_f32 v[68:69], v[80:81], v[46:47], v[98:99]
	s_nop 0
	v_pk_fma_f32 v[66:67], v[82:83], v[48:49], v[68:69]
	s_waitcnt lgkmcnt(13)
	v_pk_fma_f32 v[64:65], v[84:85], v[42:43], v[66:67]
	s_nop 0
	v_pk_fma_f32 v[62:63], v[86:87], v[44:45], v[64:65]
	s_waitcnt lgkmcnt(12)
	v_pk_fma_f32 v[60:61], v[88:89], v[38:39], v[62:63]
	s_nop 0
	v_pk_fma_f32 v[58:59], v[90:91], v[40:41], v[60:61]
	s_nop 0
	v_add_f32_e32 v37, v58, v59
	s_nop 1
	v_add_f32_dpp v37, v37, v37 quad_perm:[1,0,3,2] row_mask:0xf bank_mask:0xf bound_ctrl:1
	s_nop 1
	v_add_f32_dpp v56, v37, v37 quad_perm:[2,3,0,1] row_mask:0xf bank_mask:0xf bound_ctrl:1
	v_add_f32_e32 v37, v54, v55
	s_waitcnt lgkmcnt(10)
	v_fma_f32 v0, -v70, v56, v0
	v_mul_f32_e32 v0, v71, v0
	v_add_f32_dpp v37, v37, v37 quad_perm:[1,0,3,2] row_mask:0xf bank_mask:0xf bound_ctrl:1
	s_nop 1
	v_add_f32_dpp v54, v37, v37 quad_perm:[2,3,0,1] row_mask:0xf bank_mask:0xf bound_ctrl:1
	v_mov_b32_e32 v71, v72
	v_mov_b32_e32 v55, v0
	v_mul_f32_e32 v56, v72, v0
	s_add_i32 s10, s24, s16
	v_pk_fma_f32 v[54:55], v[70:71], v[54:55], v[56:57] op_sel_hi:[1,1,0]
	s_ashr_i32 s11, s10, 31
	v_bfe_u32 v37, v54, 16, 1
	s_lshl_b64 s[10:11], s[10:11], 9
	v_add3_u32 v37, v54, v37, s28
	v_lshl_add_u64 v[54:55], v[92:93], 0, s[10:11]
	global_store_short_d16_hi v[54:55], v37, off
	v_pk_mul_f32 v[54:55], v[70:71], v[74:75] op_sel_hi:[0,1]
	v_pk_fma_f32 v[74:75], v[50:51], v[0:1], v[54:55] op_sel_hi:[1,0,1]
	v_pk_mul_f32 v[50:51], v[70:71], v[78:79] op_sel_hi:[0,1]
	v_pk_fma_f32 v[78:79], v[52:53], v[0:1], v[50:51] op_sel_hi:[1,0,1]
	v_pk_mul_f32 v[50:51], v[70:71], v[80:81] op_sel_hi:[0,1]
	v_pk_fma_f32 v[80:81], v[46:47], v[0:1], v[50:51] op_sel_hi:[1,0,1]
	v_pk_mul_f32 v[46:47], v[70:71], v[82:83] op_sel_hi:[0,1]
	v_pk_fma_f32 v[82:83], v[48:49], v[0:1], v[46:47] op_sel_hi:[1,0,1]
	v_pk_mul_f32 v[46:47], v[70:71], v[84:85] op_sel_hi:[0,1]
	v_pk_fma_f32 v[84:85], v[42:43], v[0:1], v[46:47] op_sel_hi:[1,0,1]
	v_pk_mul_f32 v[42:43], v[70:71], v[86:87] op_sel_hi:[0,1]
	v_pk_fma_f32 v[86:87], v[44:45], v[0:1], v[42:43] op_sel_hi:[1,0,1]
	v_pk_mul_f32 v[42:43], v[70:71], v[88:89] op_sel_hi:[0,1]
	v_pk_fma_f32 v[88:89], v[38:39], v[0:1], v[42:43] op_sel_hi:[1,0,1]
	v_pk_mul_f32 v[38:39], v[70:71], v[90:91] op_sel_hi:[0,1]
	s_add_i32 s16, s16, s25
	s_add_i32 s6, s6, 2
	s_addk_i32 s7, 0x640
	v_pk_fma_f32 v[90:91], v[40:41], v[0:1], v[38:39] op_sel_hi:[1,0,1]
	s_waitcnt lgkmcnt(5)
	v_pk_fma_f32 v[100:101], v[74:75], v[2:3], 0 op_sel_hi:[1,1,0]
	s_waitcnt lgkmcnt(0)
	v_mov_b32_e32 v37, v34
	v_add_u32_e32 v34, s7, v94
	v_pk_fma_f32 v[30:31], v[74:75], v[30:31], 0 op_sel_hi:[1,1,0]
	v_pk_fma_f32 v[100:101], v[78:79], v[4:5], v[100:101]
	ds_read_b128 v[66:69], v34
	ds_read_b128 v[62:65], v34 offset:16
	ds_read_b128 v[58:61], v34 offset:32
	ds_read_b128 v[54:57], v34 offset:48
	ds_read_b128 v[50:53], v34 offset:256
	ds_read_b128 v[46:49], v34 offset:272
	ds_read_b128 v[42:45], v34 offset:288
	ds_read_b128 v[38:41], v34 offset:304
	v_pk_fma_f32 v[30:31], v[78:79], v[32:33], v[30:31]
	v_pk_fma_f32 v[32:33], v[80:81], v[6:7], v[100:101]
	v_pk_fma_f32 v[26:27], v[80:81], v[26:27], v[30:31]
	v_pk_fma_f32 v[30:31], v[82:83], v[8:9], v[32:33]
	v_pk_fma_f32 v[26:27], v[82:83], v[28:29], v[26:27]
	s_waitcnt lgkmcnt(9)
	v_pk_fma_f32 v[28:29], v[84:85], v[14:15], v[30:31]
	v_pk_fma_f32 v[22:23], v[84:85], v[22:23], v[26:27]
	v_pk_fma_f32 v[26:27], v[86:87], v[16:17], v[28:29]
	v_pk_fma_f32 v[22:23], v[86:87], v[24:25], v[22:23]
	s_waitcnt lgkmcnt(8)
	v_pk_fma_f32 v[24:25], v[88:89], v[10:11], v[26:27]
	v_add_u32_e32 v98, s7, v96
	v_mov_b32_e32 v70, s7
	v_pk_fma_f32 v[18:19], v[88:89], v[18:19], v[22:23]
	v_pk_fma_f32 v[22:23], v[90:91], v[12:13], v[24:25]
	ds_read_b32 v0, v98 offset:512
	ds_read_b96 v[70:72], v70 offset:768
	v_pk_fma_f32 v[18:19], v[90:91], v[20:21], v[18:19]
	v_add_f32_e32 v20, v22, v23
	v_add_f32_e32 v18, v18, v19
	s_nop 0
	v_add_f32_dpp v20, v20, v20 quad_perm:[1,0,3,2] row_mask:0xf bank_mask:0xf bound_ctrl:1
	v_add_f32_dpp v19, v18, v18 quad_perm:[1,0,3,2] row_mask:0xf bank_mask:0xf bound_ctrl:1
	s_nop 0
	v_add_f32_dpp v20, v20, v20 quad_perm:[2,3,0,1] row_mask:0xf bank_mask:0xf bound_ctrl:1
	v_fma_f32 v18, -v37, v20, v73
	v_mul_f32_e32 v18, v35, v18
	v_add_f32_dpp v19, v19, v19 quad_perm:[2,3,0,1] row_mask:0xf bank_mask:0xf bound_ctrl:1
	v_mul_f32_e32 v20, v37, v19
	v_pk_fma_f32 v[20:21], v[36:37], v[18:19], v[20:21] op_sel_hi:[1,1,0]
	s_ashr_i32 s17, s16, 31
	v_bfe_u32 v19, v20, 16, 1
	s_lshl_b64 s[10:11], s[16:17], 9
	v_add3_u32 v19, v20, v19, s28
	v_lshl_add_u64 v[20:21], v[92:93], 0, s[10:11]
	global_store_short_d16_hi v[20:21], v19, off
	v_pk_mul_f32 v[20:21], v[74:75], v[36:37] op_sel:[0,1]
	s_nop 0
	v_pk_fma_f32 v[74:75], v[2:3], v[18:19], v[20:21] op_sel_hi:[1,0,1]
	v_pk_mul_f32 v[2:3], v[78:79], v[36:37] op_sel:[0,1]
	s_waitcnt lgkmcnt(9)
	v_pk_fma_f32 v[66:67], v[74:75], v[66:67], 0 op_sel_hi:[1,1,0]
	v_pk_fma_f32 v[78:79], v[4:5], v[18:19], v[2:3] op_sel_hi:[1,0,1]
	v_pk_mul_f32 v[2:3], v[80:81], v[36:37] op_sel:[0,1]
	v_pk_fma_f32 v[66:67], v[78:79], v[68:69], v[66:67]
	v_pk_fma_f32 v[80:81], v[6:7], v[18:19], v[2:3] op_sel_hi:[1,0,1]
	v_pk_mul_f32 v[2:3], v[82:83], v[36:37] op_sel:[0,1]
	s_waitcnt lgkmcnt(8)
	v_pk_fma_f32 v[62:63], v[80:81], v[62:63], v[66:67]
	v_pk_fma_f32 v[82:83], v[8:9], v[18:19], v[2:3] op_sel_hi:[1,0,1]
	v_pk_mul_f32 v[2:3], v[84:85], v[36:37] op_sel:[0,1]
	v_pk_fma_f32 v[62:63], v[82:83], v[64:65], v[62:63]
	v_pk_fma_f32 v[84:85], v[14:15], v[18:19], v[2:3] op_sel_hi:[1,0,1]
	v_pk_mul_f32 v[2:3], v[86:87], v[36:37] op_sel:[0,1]
	s_waitcnt lgkmcnt(7)
	v_pk_fma_f32 v[58:59], v[84:85], v[58:59], v[62:63]
	v_pk_fma_f32 v[86:87], v[16:17], v[18:19], v[2:3] op_sel_hi:[1,0,1]
	v_pk_mul_f32 v[2:3], v[88:89], v[36:37] op_sel:[0,1]
	v_pk_fma_f32 v[58:59], v[86:87], v[60:61], v[58:59]
	v_pk_fma_f32 v[88:89], v[10:11], v[18:19], v[2:3] op_sel_hi:[1,0,1]
	v_pk_mul_f32 v[2:3], v[90:91], v[36:37] op_sel:[0,1]
	s_waitcnt lgkmcnt(6)
	v_pk_fma_f32 v[54:55], v[88:89], v[54:55], v[58:59]
	v_pk_fma_f32 v[90:91], v[12:13], v[18:19], v[2:3] op_sel_hi:[1,0,1]
	ds_read_b128 v[30:33], v34 offset:800
	ds_read_b128 v[26:29], v34 offset:816
	ds_read_b128 v[22:25], v34 offset:832
	ds_read_b128 v[18:21], v34 offset:848
	ds_read_b128 v[2:5], v34 offset:1056
	ds_read_b128 v[6:9], v34 offset:1072
	ds_read_b128 v[14:17], v34 offset:1088
	ds_read_b128 v[10:13], v34 offset:1104
	v_mov_b32_e32 v34, s7
	ds_read_b32 v73, v98 offset:1312
	ds_read_b96 v[34:36], v34 offset:1568
	s_waitcnt lgkmcnt(14)
	v_pk_fma_f32 v[98:99], v[74:75], v[50:51], 0 op_sel_hi:[1,1,0]
	v_pk_fma_f32 v[54:55], v[90:91], v[56:57], v[54:55]
	v_pk_fma_f32 v[98:99], v[78:79], v[52:53], v[98:99]
	s_nop 0
	v_pk_fma_f32 v[68:69], v[80:81], v[46:47], v[98:99]
	s_nop 0
	v_pk_fma_f32 v[66:67], v[82:83], v[48:49], v[68:69]
	s_waitcnt lgkmcnt(13)
	v_pk_fma_f32 v[64:65], v[84:85], v[42:43], v[66:67]
	s_nop 0
	v_pk_fma_f32 v[62:63], v[86:87], v[44:45], v[64:65]
	s_waitcnt lgkmcnt(12)
	v_pk_fma_f32 v[60:61], v[88:89], v[38:39], v[62:63]
	s_nop 0
	v_pk_fma_f32 v[58:59], v[90:91], v[40:41], v[60:61]
	s_nop 0
	v_add_f32_e32 v37, v58, v59
	s_nop 1
	v_add_f32_dpp v37, v37, v37 quad_perm:[1,0,3,2] row_mask:0xf bank_mask:0xf bound_ctrl:1
	s_nop 1
	v_add_f32_dpp v56, v37, v37 quad_perm:[2,3,0,1] row_mask:0xf bank_mask:0xf bound_ctrl:1
	v_add_f32_e32 v37, v54, v55
	s_waitcnt lgkmcnt(10)
	v_fma_f32 v0, -v70, v56, v0
	v_mul_f32_e32 v0, v71, v0
	v_add_f32_dpp v37, v37, v37 quad_perm:[1,0,3,2] row_mask:0xf bank_mask:0xf bound_ctrl:1
	s_nop 1
	v_add_f32_dpp v54, v37, v37 quad_perm:[2,3,0,1] row_mask:0xf bank_mask:0xf bound_ctrl:1
	v_mov_b32_e32 v71, v72
	v_mov_b32_e32 v55, v0
	v_mul_f32_e32 v56, v72, v0
	s_add_i32 s10, s24, s16
	v_pk_fma_f32 v[54:55], v[70:71], v[54:55], v[56:57] op_sel_hi:[1,1,0]
	s_ashr_i32 s11, s10, 31
	v_bfe_u32 v37, v54, 16, 1
	s_lshl_b64 s[10:11], s[10:11], 9
	v_add3_u32 v37, v54, v37, s28
	v_lshl_add_u64 v[54:55], v[92:93], 0, s[10:11]
	global_store_short_d16_hi v[54:55], v37, off
	v_pk_mul_f32 v[54:55], v[70:71], v[74:75] op_sel_hi:[0,1]
	v_pk_fma_f32 v[74:75], v[50:51], v[0:1], v[54:55] op_sel_hi:[1,0,1]
	v_pk_mul_f32 v[50:51], v[70:71], v[78:79] op_sel_hi:[0,1]
	v_pk_fma_f32 v[78:79], v[52:53], v[0:1], v[50:51] op_sel_hi:[1,0,1]
	v_pk_mul_f32 v[50:51], v[70:71], v[80:81] op_sel_hi:[0,1]
	v_pk_fma_f32 v[80:81], v[46:47], v[0:1], v[50:51] op_sel_hi:[1,0,1]
	v_pk_mul_f32 v[46:47], v[70:71], v[82:83] op_sel_hi:[0,1]
	v_pk_fma_f32 v[82:83], v[48:49], v[0:1], v[46:47] op_sel_hi:[1,0,1]
	v_pk_mul_f32 v[46:47], v[70:71], v[84:85] op_sel_hi:[0,1]
	v_pk_fma_f32 v[84:85], v[42:43], v[0:1], v[46:47] op_sel_hi:[1,0,1]
	v_pk_mul_f32 v[42:43], v[70:71], v[86:87] op_sel_hi:[0,1]
	v_pk_fma_f32 v[86:87], v[44:45], v[0:1], v[42:43] op_sel_hi:[1,0,1]
	v_pk_mul_f32 v[42:43], v[70:71], v[88:89] op_sel_hi:[0,1]
	v_pk_fma_f32 v[88:89], v[38:39], v[0:1], v[42:43] op_sel_hi:[1,0,1]
	v_pk_mul_f32 v[38:39], v[70:71], v[90:91] op_sel_hi:[0,1]
	s_add_i32 s16, s16, s25
	s_add_i32 s6, s6, 2
	s_addk_i32 s7, 0x640
	v_pk_fma_f32 v[90:91], v[40:41], v[0:1], v[38:39] op_sel_hi:[1,0,1]
	s_waitcnt lgkmcnt(5)
	v_pk_fma_f32 v[100:101], v[74:75], v[2:3], 0 op_sel_hi:[1,1,0]
	s_waitcnt lgkmcnt(0)
	v_mov_b32_e32 v37, v34
	v_add_u32_e32 v34, s7, v94
	v_pk_fma_f32 v[30:31], v[74:75], v[30:31], 0 op_sel_hi:[1,1,0]
	v_pk_fma_f32 v[100:101], v[78:79], v[4:5], v[100:101]
	ds_read_b128 v[66:69], v34
	ds_read_b128 v[62:65], v34 offset:16
	ds_read_b128 v[58:61], v34 offset:32
	ds_read_b128 v[54:57], v34 offset:48
	ds_read_b128 v[50:53], v34 offset:256
	ds_read_b128 v[46:49], v34 offset:272
	ds_read_b128 v[42:45], v34 offset:288
	ds_read_b128 v[38:41], v34 offset:304
	v_pk_fma_f32 v[30:31], v[78:79], v[32:33], v[30:31]
	v_pk_fma_f32 v[32:33], v[80:81], v[6:7], v[100:101]
	v_pk_fma_f32 v[26:27], v[80:81], v[26:27], v[30:31]
	v_pk_fma_f32 v[30:31], v[82:83], v[8:9], v[32:33]
	v_pk_fma_f32 v[26:27], v[82:83], v[28:29], v[26:27]
	s_waitcnt lgkmcnt(9)
	v_pk_fma_f32 v[28:29], v[84:85], v[14:15], v[30:31]
	v_pk_fma_f32 v[22:23], v[84:85], v[22:23], v[26:27]
	v_pk_fma_f32 v[26:27], v[86:87], v[16:17], v[28:29]
	v_pk_fma_f32 v[22:23], v[86:87], v[24:25], v[22:23]
	s_waitcnt lgkmcnt(8)
	v_pk_fma_f32 v[24:25], v[88:89], v[10:11], v[26:27]
	v_add_u32_e32 v98, s7, v96
	v_mov_b32_e32 v70, s7
	v_pk_fma_f32 v[18:19], v[88:89], v[18:19], v[22:23]
	v_pk_fma_f32 v[22:23], v[90:91], v[12:13], v[24:25]
	ds_read_b32 v0, v98 offset:512
	ds_read_b96 v[70:72], v70 offset:768
	v_pk_fma_f32 v[18:19], v[90:91], v[20:21], v[18:19]
	v_add_f32_e32 v20, v22, v23
	v_add_f32_e32 v18, v18, v19
	s_nop 0
	v_add_f32_dpp v20, v20, v20 quad_perm:[1,0,3,2] row_mask:0xf bank_mask:0xf bound_ctrl:1
	v_add_f32_dpp v19, v18, v18 quad_perm:[1,0,3,2] row_mask:0xf bank_mask:0xf bound_ctrl:1
	s_nop 0
	v_add_f32_dpp v20, v20, v20 quad_perm:[2,3,0,1] row_mask:0xf bank_mask:0xf bound_ctrl:1
	v_fma_f32 v18, -v37, v20, v73
	v_mul_f32_e32 v18, v35, v18
	v_add_f32_dpp v19, v19, v19 quad_perm:[2,3,0,1] row_mask:0xf bank_mask:0xf bound_ctrl:1
	v_mul_f32_e32 v20, v37, v19
	v_pk_fma_f32 v[20:21], v[36:37], v[18:19], v[20:21] op_sel_hi:[1,1,0]
	s_ashr_i32 s17, s16, 31
	v_bfe_u32 v19, v20, 16, 1
	s_lshl_b64 s[10:11], s[16:17], 9
	v_add3_u32 v19, v20, v19, s28
	v_lshl_add_u64 v[20:21], v[92:93], 0, s[10:11]
	global_store_short_d16_hi v[20:21], v19, off
	v_pk_mul_f32 v[20:21], v[74:75], v[36:37] op_sel:[0,1]
	s_nop 0
	v_pk_fma_f32 v[74:75], v[2:3], v[18:19], v[20:21] op_sel_hi:[1,0,1]
	v_pk_mul_f32 v[2:3], v[78:79], v[36:37] op_sel:[0,1]
	s_waitcnt lgkmcnt(9)
	v_pk_fma_f32 v[66:67], v[74:75], v[66:67], 0 op_sel_hi:[1,1,0]
	v_pk_fma_f32 v[78:79], v[4:5], v[18:19], v[2:3] op_sel_hi:[1,0,1]
	v_pk_mul_f32 v[2:3], v[80:81], v[36:37] op_sel:[0,1]
	v_pk_fma_f32 v[66:67], v[78:79], v[68:69], v[66:67]
	v_pk_fma_f32 v[80:81], v[6:7], v[18:19], v[2:3] op_sel_hi:[1,0,1]
	v_pk_mul_f32 v[2:3], v[82:83], v[36:37] op_sel:[0,1]
	s_waitcnt lgkmcnt(8)
	v_pk_fma_f32 v[62:63], v[80:81], v[62:63], v[66:67]
	v_pk_fma_f32 v[82:83], v[8:9], v[18:19], v[2:3] op_sel_hi:[1,0,1]
	v_pk_mul_f32 v[2:3], v[84:85], v[36:37] op_sel:[0,1]
	v_pk_fma_f32 v[62:63], v[82:83], v[64:65], v[62:63]
	v_pk_fma_f32 v[84:85], v[14:15], v[18:19], v[2:3] op_sel_hi:[1,0,1]
	v_pk_mul_f32 v[2:3], v[86:87], v[36:37] op_sel:[0,1]
	s_waitcnt lgkmcnt(7)
	v_pk_fma_f32 v[58:59], v[84:85], v[58:59], v[62:63]
	v_pk_fma_f32 v[86:87], v[16:17], v[18:19], v[2:3] op_sel_hi:[1,0,1]
	v_pk_mul_f32 v[2:3], v[88:89], v[36:37] op_sel:[0,1]
	v_pk_fma_f32 v[58:59], v[86:87], v[60:61], v[58:59]
	v_pk_fma_f32 v[88:89], v[10:11], v[18:19], v[2:3] op_sel_hi:[1,0,1]
	v_pk_mul_f32 v[2:3], v[90:91], v[36:37] op_sel:[0,1]
	s_waitcnt lgkmcnt(6)
	v_pk_fma_f32 v[54:55], v[88:89], v[54:55], v[58:59]
	v_pk_fma_f32 v[90:91], v[12:13], v[18:19], v[2:3] op_sel_hi:[1,0,1]
	ds_read_b128 v[30:33], v34 offset:800
	ds_read_b128 v[26:29], v34 offset:816
	ds_read_b128 v[22:25], v34 offset:832
	ds_read_b128 v[18:21], v34 offset:848
	ds_read_b128 v[2:5], v34 offset:1056
	ds_read_b128 v[6:9], v34 offset:1072
	ds_read_b128 v[14:17], v34 offset:1088
	ds_read_b128 v[10:13], v34 offset:1104
	v_mov_b32_e32 v34, s7
	ds_read_b32 v73, v98 offset:1312
	ds_read_b96 v[34:36], v34 offset:1568
	s_waitcnt lgkmcnt(14)
	v_pk_fma_f32 v[98:99], v[74:75], v[50:51], 0 op_sel_hi:[1,1,0]
	v_pk_fma_f32 v[54:55], v[90:91], v[56:57], v[54:55]
	v_pk_fma_f32 v[98:99], v[78:79], v[52:53], v[98:99]
	s_nop 0
	v_pk_fma_f32 v[68:69], v[80:81], v[46:47], v[98:99]
	s_nop 0
	v_pk_fma_f32 v[66:67], v[82:83], v[48:49], v[68:69]
	s_waitcnt lgkmcnt(13)
	v_pk_fma_f32 v[64:65], v[84:85], v[42:43], v[66:67]
	s_nop 0
	v_pk_fma_f32 v[62:63], v[86:87], v[44:45], v[64:65]
	s_waitcnt lgkmcnt(12)
	v_pk_fma_f32 v[60:61], v[88:89], v[38:39], v[62:63]
	s_nop 0
	v_pk_fma_f32 v[58:59], v[90:91], v[40:41], v[60:61]
	s_nop 0
	v_add_f32_e32 v37, v58, v59
	s_nop 1
	v_add_f32_dpp v37, v37, v37 quad_perm:[1,0,3,2] row_mask:0xf bank_mask:0xf bound_ctrl:1
	s_nop 1
	v_add_f32_dpp v56, v37, v37 quad_perm:[2,3,0,1] row_mask:0xf bank_mask:0xf bound_ctrl:1
	v_add_f32_e32 v37, v54, v55
	s_waitcnt lgkmcnt(10)
	v_fma_f32 v0, -v70, v56, v0
	v_mul_f32_e32 v0, v71, v0
	v_add_f32_dpp v37, v37, v37 quad_perm:[1,0,3,2] row_mask:0xf bank_mask:0xf bound_ctrl:1
	s_nop 1
	v_add_f32_dpp v54, v37, v37 quad_perm:[2,3,0,1] row_mask:0xf bank_mask:0xf bound_ctrl:1
	v_mov_b32_e32 v71, v72
	v_mov_b32_e32 v55, v0
	v_mul_f32_e32 v56, v72, v0
	s_add_i32 s10, s24, s16
	v_pk_fma_f32 v[54:55], v[70:71], v[54:55], v[56:57] op_sel_hi:[1,1,0]
	s_ashr_i32 s11, s10, 31
	v_bfe_u32 v37, v54, 16, 1
	s_lshl_b64 s[10:11], s[10:11], 9
	v_add3_u32 v37, v54, v37, s28
	v_lshl_add_u64 v[54:55], v[92:93], 0, s[10:11]
	global_store_short_d16_hi v[54:55], v37, off
	v_pk_mul_f32 v[54:55], v[70:71], v[74:75] op_sel_hi:[0,1]
	v_pk_fma_f32 v[74:75], v[50:51], v[0:1], v[54:55] op_sel_hi:[1,0,1]
	v_pk_mul_f32 v[50:51], v[70:71], v[78:79] op_sel_hi:[0,1]
	v_pk_fma_f32 v[78:79], v[52:53], v[0:1], v[50:51] op_sel_hi:[1,0,1]
	v_pk_mul_f32 v[50:51], v[70:71], v[80:81] op_sel_hi:[0,1]
	v_pk_fma_f32 v[80:81], v[46:47], v[0:1], v[50:51] op_sel_hi:[1,0,1]
	v_pk_mul_f32 v[46:47], v[70:71], v[82:83] op_sel_hi:[0,1]
	v_pk_fma_f32 v[82:83], v[48:49], v[0:1], v[46:47] op_sel_hi:[1,0,1]
	v_pk_mul_f32 v[46:47], v[70:71], v[84:85] op_sel_hi:[0,1]
	v_pk_fma_f32 v[84:85], v[42:43], v[0:1], v[46:47] op_sel_hi:[1,0,1]
	v_pk_mul_f32 v[42:43], v[70:71], v[86:87] op_sel_hi:[0,1]
	v_pk_fma_f32 v[86:87], v[44:45], v[0:1], v[42:43] op_sel_hi:[1,0,1]
	v_pk_mul_f32 v[42:43], v[70:71], v[88:89] op_sel_hi:[0,1]
	v_pk_fma_f32 v[88:89], v[38:39], v[0:1], v[42:43] op_sel_hi:[1,0,1]
	v_pk_mul_f32 v[38:39], v[70:71], v[90:91] op_sel_hi:[0,1]
	s_add_i32 s16, s16, s25
	s_add_i32 s6, s6, 2
	s_addk_i32 s7, 0x640
	s_cmp_gt_u32 s6, 13
	v_pk_fma_f32 v[90:91], v[40:41], v[0:1], v[38:39] op_sel_hi:[1,0,1]
	s_cbranch_scc0 .LBB0_916
	s_branch .LBB0_899
